# GEMM tile boundaries: first two DMA waits of a tile relaxed to vmcnt(8+E) so they do not wait for the previous epilogue's stores
# speedup vs baseline: 1.0019x; 1.0018x over previous
; #define PG8_STAGE(bufoff, gbase, voff) do { _Pragma("unroll") for (int _i = 0; _i < 2; ++_i) \
;         __builtin_amdgcn_global_load_lds((const unsigned*)((const char*)(gbase) + (voff)[_i]), (PG8_LAS unsigned*)(lds + (bufoff) + ldsw + _i * 8192), 16, 0, 0); } while (0)
; #define PG8_WAIT_V(n) asm volatile("s_waitcnt vmcnt(" #n ")" ::: "memory")
; #define PG8_BAR __builtin_amdgcn_s_barrier()
; template <class Epi, class Sched, bool ALIGN_EPI = false, bool SP2 = false>
; __device__ __forceinline__ void gemm_phase(PG8_LAS unsigned char* lds, const Gemm g, const Sched& S, const Epi& E) {
;     ...
;     const int tid = tid_, wid = __builtin_amdgcn_readfirstlane(tid >> 6), lane = tid & 63, wr = wid >> 2, wc = wid & 3, fr = lane & 15, fq = lane >> 4;
;     const int K = g.K, nt = K / BK;
;     unsigned voffA[2], voffB[2];
; #pragma unroll
;     for (int i = 0; i < 2; ++i) { int R, C; stage_rc(tid * 16 + i * 8192, R, C); const int Rb = Epi::PERM ? ((R & ~31) + perm32(R & 31)) : R;
;         voffA[i] = (unsigned)(R * K + C) * 2u; voffB[i] = (unsigned)(Rb * K + C) * 2u; }
;     const size_t kstep = (size_t)(BK * 2);
;     const size_t hstep = (size_t)HALF * K * 2;
;     const size_t tstep = 2 * hstep;
;     const unsigned ldsw = (unsigned)wid * 1024u;
;     const int aoff = lds_byte(wr * 64 + fr, fq * 8), boff = lds_byte(wc * 32 + fr, fq * 8);
;     ...
;         PG8_STAGE(PG8_SB(1, 0), cB + kstep, voffB); PG8_STAGE(PG8_SA(1, 0), cA + kstep, voffA); PG8_STAGE(PG8_SB(1, 1), cB + hstep + kstep, voffB);
;         PG8_WAIT_V(6); PG8_BAR;
.LBB0_228:
	s_mov_b64 s[20:21], 0x80
	s_and_b32 s7, s4, 3
	s_add_i32 m0, s41, 0x18000
	v_lshl_add_u64 v[8:9], v[8:9], 0, s[20:21]
	s_lshl_b32 s26, s5, 6
	s_lshl_b32 s23, s5, 13
	s_lshl_b32 s27, s7, 12
	s_waitcnt vmcnt(2)
	s_barrier
	global_load_lds_dwordx4 v[8:9], off
	v_lshl_add_u64 v[6:7], v[6:7], 0, s[20:21]
	s_add_i32 m0, s41, 0x1a000
	s_add_i32 s57, s41, 0x8000
	s_add_i32 s58, s41, 0xa000
	global_load_lds_dwordx4 v[6:7], off
	v_lshl_add_u64 v[4:5], v[4:5], 0, s[20:21]
	s_mov_b32 m0, s57
	s_add_u32 s4, s44, 0x40080
	global_load_lds_dwordx4 v[4:5], off
	v_lshl_add_u64 v[2:3], v[2:3], 0, s[20:21]
	s_mov_b32 m0, s58
	s_addc_u32 s5, s45, 0
	global_load_lds_dwordx4 v[2:3], off
	s_add_i32 m0, s41, 0x1c000
	v_lshl_add_u64 v[2:3], s[4:5], 0, v[132:133]
	global_load_lds_dwordx4 v[2:3], off
	v_lshl_add_u64 v[2:3], s[4:5], 0, v[136:137]
	s_add_i32 m0, s41, 0x1e000
	v_bfe_u32 v4, v10, 4, 2
	global_load_lds_dwordx4 v[2:3], off
	v_and_b32_e32 v3, 15, v10
	v_lshlrev_b32_e32 v2, 3, v4
	v_lshlrev_b32_e32 v4, 4, v4
	v_lshlrev_b32_e32 v5, 2, v10
	v_lshl_or_b32 v4, v3, 6, v4
	v_and_b32_e32 v5, 32, v5
	s_cmpk_lt_u32 s22, 0x100
	v_bitop3_b32 v6, v4, s23, v5 bitop3:0xde
	s_cselect_b64 s[22:23], -1, 0
	s_ashr_i32 s4, s26, 31
	v_or_b32_e32 v140, s26, v3
	v_mov_b32_e32 v141, s4
	s_lshl_b32 s4, s7, 4
	v_lshrrev_b32_e32 v3, 2, v10
	v_and_or_b32 v3, v3, 8, s4
	v_bitop3_b32 v172, v4, s27, v5 bitop3:0xde
	v_and_b32_e32 v4, 16, v10
	v_or_b32_e32 v174, 0xfffffe00, v3
	v_lshlrev_b32_e32 v3, 14, v11
	v_cmp_eq_u32_e32 vcc, 0, v4
	v_lshl_or_b32 v4, s7, 5, v2
	v_and_b32_e32 v3, 0xffff8000, v3
	v_or_b32_e32 v173, 0xfffff800, v4
	v_lshl_add_u32 v3, v12, 11, v3
	v_and_b32_e32 v4, 1, v11
	v_lshl_or_b32 v3, v4, 6, v3
	v_lshl_add_u32 v144, v13, 1, v3
	v_lshlrev_b32_e32 v3, 14, v14
	s_ashr_i32 s61, s29, 31
	s_ashr_i32 s62, s14, 31
	v_and_b32_e32 v3, 0xffff8000, v3
	s_waitcnt vmcnt(6)
	v_bfrev_b32_e32 v5, 8
	v_mov_b32_e32 v7, 0xe000000
	s_add_u32 s26, s12, 0x14000000
	v_lshl_add_u32 v3, v15, 11, v3
	v_and_b32_e32 v4, 1, v14
	v_cndmask_b32_e32 v138, v5, v7, vcc
	s_addc_u32 s27, s13, 0
	v_lshl_or_b32 v3, v4, 6, v3
	s_add_i32 s64, 0, 0x10000
	s_add_i32 s65, 0, 0x14000
	s_mov_b32 s59, 0x18000
	s_mov_b32 s60, 0x8000
	v_lshl_add_u64 v[142:143], s[12:13], 0, v[138:139]
	v_lshl_or_b32 v175, s7, 6, v2
	v_mov_b32_e32 v145, v139
	v_lshl_add_u32 v146, v16, 1, v3
	v_mov_b32_e32 v147, v139
	v_mov_b64_e32 v[148:149], 0xc00
	v_mov_b64_e32 v[150:151], 0xbff
	s_movk_i32 s63, 0x181
	v_add_u32_e32 v176, s64, v172
	v_add_u32_e32 v177, s65, v172
	v_add_u32_e32 v178, 0, v6
	s_mov_b32 s66, 0xc000
	s_brev_b32 s67, 48
	s_movk_i32 s68, 0xfa00
	s_mov_b32 s69, 0x20000
	s_mov_b32 s70, 0x24000
	s_mov_b32 s71, 0x28000
	s_mov_b32 s72, 0x2c000
	s_mov_b32 s28, 0x437f0000
	s_mov_b32 s73, 0x40000
	s_mov_b32 s74, 0x48000
	s_mov_b32 s75, 0x50000
	v_lshlrev_b32_e32 v179, 2, v2
	s_mov_b32 s76, 0x6000000
	v_mov_b32_e32 v180, 0x358637bd
	v_mov_b32_e32 v181, 0x3e38aa3b
	s_barrier
	s_mov_b32 s89, 0
	s_branch .LBB0_231

; #define PG8_STAGE(bufoff, gbase, voff) do { _Pragma("unroll") for (int _i = 0; _i < 2; ++_i) \
;         __builtin_amdgcn_global_load_lds((const unsigned*)((const char*)(gbase) + (voff)[_i]), (PG8_LAS unsigned*)(lds + (bufoff) + ldsw + _i * 8192), 16, 0, 0); } while (0)
; #define PG8_LDA(dst, b, h) do { _Pragma("unroll") for (int m = 0; m < 4; ++m) _Pragma("unroll") for (int k = 0; k < 2; ++k) dst[m][k] = *(const PG8_LAS bf16x8*)(lds + PG8_SA(b, h) + aoff + m * 2048 + k * 1024); } while (0)
; #define PG8_LDB(dst, b, h) do { _Pragma("unroll") for (int n = 0; n < 2; ++n) _Pragma("unroll") for (int k = 0; k < 2; ++k) dst[n][k] = *(const PG8_LAS bf16x8*)(lds + PG8_SB(b, h) + boff + n * 2048 + k * 1024); } while (0)
; #define PG8_WAIT_V(n) asm volatile("s_waitcnt vmcnt(" #n ")" ::: "memory")
; #define PG8_WAIT_L(n) asm volatile("s_waitcnt lgkmcnt(" #n ")" ::: "memory")
; #define PG8_BAR __builtin_amdgcn_s_barrier()
; template <class Epi, class Sched, bool ALIGN_EPI = false, bool SP2 = false>
; __device__ __forceinline__ void gemm_phase(PG8_LAS unsigned char* lds, const Gemm g, const Sched& S, const Epi& E) {
;     ...
;         const bool has_next = S.next(ui + 1, nxt);
;         const char* nA = has_next ? (const char*)g.A + (size_t)nxt.pm * tstep : cA; const char* nB = has_next ? (const char*)g.Bt + (size_t)nxt.pn * tstep : cB;
;         for (int t = 0; t < nt; t += 2) {
;             if constexpr (Epi::MID) { if (t == nt / 2) E.mid(acc, cur, wr, wc, fr, fq); }
;             const bool last = (t == nt - 2);
;             const char* a1 = cA + (size_t)(t + 1) * kstep;
;             const char* a2 = last ? nA : cA + (size_t)(t + 2) * kstep; const char* b2 = last ? nB : cB + (size_t)(t + 2) * kstep;
;             const char* a3 = a2 + kstep; const char* b3 = b2 + kstep;
;             if (last && has_next) S.a_ready(nxt);
;             if constexpr (SP2) {
;             PG8_LDB(B0, 0, 0); PG8_LDB(B1, 0, 1); PG8_SCHED; PG8_LDA(At, 0, 0); PG8_STAGE(PG8_SA(1, 1), a1 + hstep, voffA);
;             PG8_WAIT_V(8); PG8_WAIT_L(0); PG8_BAR; PG8_MMA(0, 0, At, B0); PG8_MMA(0, 1, At, B1); PG8_BAR; PG8_SCHED;
;             PG8_LDA(At, 0, 1); PG8_STAGE(PG8_SB(0, 0), b2, voffB); PG8_STAGE(PG8_SB(0, 1), b2 + hstep, voffB); PG8_STAGE(PG8_SA(0, 0), a2, voffA);
;             PG8_WAIT_V(8); PG8_WAIT_L(0); PG8_BAR; PG8_MMA(1, 0, At, B0); PG8_MMA(1, 1, At, B1); PG8_BAR; PG8_SCHED;
.LBB0_233:
	s_ashr_i32 s35, s34, 31
	s_lshl_b64 s[36:37], s[34:35], 19
	s_add_u32 s36, s49, s36
	s_addc_u32 s37, s50, s37
	s_and_b64 s[38:39], s[4:5], exec
	s_cselect_b32 s7, s37, s43
	s_cselect_b32 s35, s36, s42
	s_ashr_i32 s31, s30, 31
	s_lshl_b64 s[38:39], s[30:31], 19
	s_add_u32 s38, s33, s38
	s_addc_u32 s39, s48, s39
	s_and_b64 s[46:47], s[4:5], exec
	s_cselect_b32 s31, s39, s45
	s_cselect_b32 s77, s38, s44
	s_add_u32 s42, s42, 0x40080
	s_addc_u32 s43, s43, 0
	s_add_u32 s78, s44, 0x100
	s_addc_u32 s79, s45, 0
	s_mov_b32 s80, -2
	ds_read_b128 v[152:155], v176
	ds_read_b128 v[156:159], v176 offset:1024
	ds_read_b128 v[160:163], v176 offset:2048
	ds_read_b128 v[182:185], v176 offset:3072
	ds_read_b128 v[186:189], v177
	ds_read_b128 v[190:193], v177 offset:1024
	ds_read_b128 v[194:197], v177 offset:2048
	ds_read_b128 v[198:201], v177 offset:3072
	s_add_u32 s44, s42, 0xfffc0080
	s_addc_u32 s45, s43, -1
	s_cmp_eq_u32 s80, 12
	s_cselect_b32 s47, s7, s45
	s_cselect_b32 s46, s35, s44
	s_cselect_b32 s45, s31, s79
	s_cselect_b32 s44, s77, s78
	v_lshl_add_u64 v[234:235], s[42:43], 0, v[144:145]
	s_add_i32 m0, s41, 0xc000
	ds_read_b128 v[202:205], v178
	ds_read_b128 v[206:209], v178 offset:1024
	ds_read_b128 v[210:213], v178 offset:2048
	ds_read_b128 v[214:217], v178 offset:3072
	ds_read_b128 v[218:221], v178 offset:4096
	ds_read_b128 v[222:225], v178 offset:5120
	ds_read_b128 v[226:229], v178 offset:6144
	ds_read_b128 v[230:233], v178 offset:7168
	global_load_lds_dwordx4 v[234:235], off
	v_lshl_add_u64 v[234:235], s[42:43], 0, v[146:147]
	s_add_i32 m0, s41, 0xe000
	s_nop 0
	global_load_lds_dwordx4 v[234:235], off
	s_cmp_eq_u32 s89, 0
	s_cbranch_scc1 .Lrw_p2_0_a
	s_cmp_eq_u32 s89, 1
	s_cbranch_scc1 .Lrw_p2_0_b
	s_waitcnt vmcnt(24)
	s_branch .Lrw_p2_0_z
.Lrw_p2_0_b:
	s_waitcnt vmcnt(16)
	s_branch .Lrw_p2_0_z
.Lrw_p2_0_a:
	s_waitcnt vmcnt(8)
.Lrw_p2_0_z:
	s_waitcnt lgkmcnt(0)
	s_barrier
	s_setprio 1
	s_waitcnt lgkmcnt(0)
	v_mfma_f32_16x16x32_bf16 v[126:129], v[152:155], v[202:205], 0
	v_mfma_f32_16x16x32_bf16 v[122:125], v[160:163], v[202:205], 0
	v_mfma_f32_16x16x32_bf16 v[114:117], v[152:155], v[210:213], 0
	v_mfma_f32_16x16x32_bf16 v[110:113], v[160:163], v[210:213], 0
	v_mfma_f32_16x16x32_bf16 v[98:101], v[152:155], v[218:221], 0
	v_mfma_f32_16x16x32_bf16 v[94:97], v[160:163], v[218:221], 0
	v_mfma_f32_16x16x32_bf16 v[82:85], v[152:155], v[226:229], 0
	v_mfma_f32_16x16x32_bf16 v[78:81], v[160:163], v[226:229], 0
	v_mfma_f32_16x16x32_bf16 v[126:129], v[156:159], v[206:209], v[126:129]
	v_mfma_f32_16x16x32_bf16 v[122:125], v[182:185], v[206:209], v[122:125]
	v_mfma_f32_16x16x32_bf16 v[114:117], v[156:159], v[214:217], v[114:117]
	v_mfma_f32_16x16x32_bf16 v[110:113], v[182:185], v[214:217], v[110:113]
	v_mfma_f32_16x16x32_bf16 v[98:101], v[156:159], v[222:225], v[98:101]
	v_mfma_f32_16x16x32_bf16 v[94:97], v[182:185], v[222:225], v[94:97]
	v_mfma_f32_16x16x32_bf16 v[82:85], v[156:159], v[230:233], v[82:85]
	v_mfma_f32_16x16x32_bf16 v[78:81], v[182:185], v[230:233], v[78:81]
	s_setprio 0
	s_setprio 1
	v_mfma_f32_16x16x32_bf16 v[118:121], v[186:189], v[202:205], 0
	v_mfma_f32_16x16x32_bf16 v[106:109], v[194:197], v[202:205], 0
	v_mfma_f32_16x16x32_bf16 v[102:105], v[186:189], v[210:213], 0
	v_mfma_f32_16x16x32_bf16 v[90:93], v[194:197], v[210:213], 0
	v_mfma_f32_16x16x32_bf16 v[86:89], v[186:189], v[218:221], 0
	v_mfma_f32_16x16x32_bf16 v[74:77], v[194:197], v[218:221], 0
	v_mfma_f32_16x16x32_bf16 v[70:73], v[186:189], v[226:229], 0
	v_mfma_f32_16x16x32_bf16 v[66:69], v[194:197], v[226:229], 0
	v_mfma_f32_16x16x32_bf16 v[118:121], v[190:193], v[206:209], v[118:121]
	v_mfma_f32_16x16x32_bf16 v[106:109], v[198:201], v[206:209], v[106:109]
	v_mfma_f32_16x16x32_bf16 v[102:105], v[190:193], v[214:217], v[102:105]
	v_mfma_f32_16x16x32_bf16 v[90:93], v[198:201], v[214:217], v[90:93]
	v_mfma_f32_16x16x32_bf16 v[86:89], v[190:193], v[222:225], v[86:89]
	v_mfma_f32_16x16x32_bf16 v[74:77], v[198:201], v[222:225], v[74:77]
	v_mfma_f32_16x16x32_bf16 v[70:73], v[190:193], v[230:233], v[70:73]
	v_mfma_f32_16x16x32_bf16 v[66:69], v[198:201], v[230:233], v[66:69]
	s_setprio 0
	s_barrier
	s_add_i32 s81, s64, s15
	v_lshl_add_u64 v[234:235], s[44:45], 0, v[132:133]
	s_mov_b32 m0, s81
	ds_read_b128 v[202:205], v178 offset:16384
	ds_read_b128 v[206:209], v178 offset:17408
	ds_read_b128 v[210:213], v178 offset:18432
	ds_read_b128 v[214:217], v178 offset:19456
	ds_read_b128 v[218:221], v178 offset:20480
	ds_read_b128 v[222:225], v178 offset:21504
	ds_read_b128 v[226:229], v178 offset:22528
	ds_read_b128 v[230:233], v178 offset:23552
	global_load_lds_dwordx4 v[234:235], off
	s_add_i32 m0, s81, 0x2000
	s_add_u32 s82, s44, 0x40000
	v_lshl_add_u64 v[236:237], s[44:45], 0, v[136:137]
	s_addc_u32 s83, s45, 0
	s_add_i32 s81, s65, s15
	global_load_lds_dwordx4 v[236:237], off
	v_lshl_add_u64 v[238:239], s[82:83], 0, v[132:133]
	s_mov_b32 m0, s81
	v_lshl_add_u64 v[240:241], s[46:47], 0, v[134:135]
	global_load_lds_dwordx4 v[238:239], off
	v_lshl_add_u64 v[238:239], s[82:83], 0, v[136:137]
	s_add_i32 m0, s81, 0x2000
	s_nop 0
	global_load_lds_dwordx4 v[238:239], off
	v_lshl_add_u64 v[238:239], s[46:47], 0, v[130:131]
	s_mov_b32 m0, s41
	s_nop 0
	global_load_lds_dwordx4 v[238:239], off
	s_mov_b32 m0, s51
	s_nop 0
	global_load_lds_dwordx4 v[240:241], off
	s_cmp_eq_u32 s89, 0
	s_cbranch_scc1 .Lrw_p2_1_a
	s_cmp_eq_u32 s89, 1
	s_cbranch_scc1 .Lrw_p2_1_b
	s_waitcnt vmcnt(24)
	s_branch .Lrw_p2_1_z

; #define PG8_STAGE(bufoff, gbase, voff) do { _Pragma("unroll") for (int _i = 0; _i < 2; ++_i) \
;         __builtin_amdgcn_global_load_lds((const unsigned*)((const char*)(gbase) + (voff)[_i]), (PG8_LAS unsigned*)(lds + (bufoff) + ldsw + _i * 8192), 16, 0, 0); } while (0)
; #define PG8_LDA(dst, b, h) do { _Pragma("unroll") for (int m = 0; m < 4; ++m) _Pragma("unroll") for (int k = 0; k < 2; ++k) dst[m][k] = *(const PG8_LAS bf16x8*)(lds + PG8_SA(b, h) + aoff + m * 2048 + k * 1024); } while (0)
; #define PG8_LDB(dst, b, h) do { _Pragma("unroll") for (int n = 0; n < 2; ++n) _Pragma("unroll") for (int k = 0; k < 2; ++k) dst[n][k] = *(const PG8_LAS bf16x8*)(lds + PG8_SB(b, h) + boff + n * 2048 + k * 1024); } while (0)
; #define PG8_MMA(ai, bj, At, Bt) do { __builtin_amdgcn_s_setprio(1); _Pragma("unroll") for (int m = 0; m < 4; ++m) _Pragma("unroll") for (int n = 0; n < 2; ++n) _Pragma("unroll") for (int k = 0; k < 2; ++k) \
;         acc[ai][bj][m][n] = __builtin_amdgcn_mfma_f32_16x16x32_bf16(Bt[n][k], At[m][k], acc[ai][bj][m][n], 0, 0, 0); __builtin_amdgcn_s_setprio(0); } while (0)
; #define PG8_WAIT_V(n) asm volatile("s_waitcnt vmcnt(" #n ")" ::: "memory")
; #define PG8_WAIT_L(n) asm volatile("s_waitcnt lgkmcnt(" #n ")" ::: "memory")
; #define PG8_BAR __builtin_amdgcn_s_barrier()
; #define PG8_SCHED __builtin_amdgcn_sched_barrier(0)
; template <class Epi, class Sched, bool ALIGN_EPI = false, bool SP2 = false>
; __device__ __forceinline__ void gemm_phase(PG8_LAS unsigned char* lds, const Gemm g, const Sched& S, const Epi& E) {
;     ...
;             PG8_WAIT_V(8); PG8_WAIT_L(0); PG8_BAR; PG8_MMA(1, 0, At, B0); PG8_MMA(1, 1, At, B1); PG8_BAR; PG8_SCHED;
;             PG8_LDB(B0, 1, 0); PG8_LDB(B1, 1, 1); PG8_SCHED; PG8_LDA(At, 1, 0); PG8_STAGE(PG8_SA(0, 1), a2 + hstep, voffA);
;             PG8_WAIT_V(8); PG8_WAIT_L(0); PG8_BAR; PG8_MMA(0, 0, At, B0); PG8_MMA(0, 1, At, B1); PG8_BAR; PG8_SCHED;
;             PG8_LDA(At, 1, 1); PG8_STAGE(PG8_SB(1, 0), b3, voffB); PG8_STAGE(PG8_SB(1, 1), b3 + hstep, voffB); PG8_STAGE(PG8_SA(1, 0), a3, voffA);
;             PG8_WAIT_V(8); PG8_WAIT_L(0); PG8_BAR; PG8_MMA(1, 0, At, B0); PG8_MMA(1, 1, At, B1); PG8_BAR; PG8_SCHED;
.Lrw_p2_1_z:
	s_waitcnt lgkmcnt(0)
	s_barrier
	s_setprio 1
	s_waitcnt lgkmcnt(0)
	v_mfma_f32_16x16x32_bf16 v[62:65], v[152:155], v[202:205], 0
	v_mfma_f32_16x16x32_bf16 v[58:61], v[160:163], v[202:205], 0
	v_mfma_f32_16x16x32_bf16 v[50:53], v[152:155], v[210:213], 0
	v_mfma_f32_16x16x32_bf16 v[46:49], v[160:163], v[210:213], 0
	v_mfma_f32_16x16x32_bf16 v[34:37], v[152:155], v[218:221], 0
	v_mfma_f32_16x16x32_bf16 v[30:33], v[160:163], v[218:221], 0
	v_mfma_f32_16x16x32_bf16 v[18:21], v[152:155], v[226:229], 0
	v_mfma_f32_16x16x32_bf16 v[14:17], v[160:163], v[226:229], 0
	v_mfma_f32_16x16x32_bf16 v[62:65], v[156:159], v[206:209], v[62:65]
	v_mfma_f32_16x16x32_bf16 v[58:61], v[182:185], v[206:209], v[58:61]
	v_mfma_f32_16x16x32_bf16 v[50:53], v[156:159], v[214:217], v[50:53]
	v_mfma_f32_16x16x32_bf16 v[46:49], v[182:185], v[214:217], v[46:49]
	v_mfma_f32_16x16x32_bf16 v[34:37], v[156:159], v[222:225], v[34:37]
	v_mfma_f32_16x16x32_bf16 v[30:33], v[182:185], v[222:225], v[30:33]
	v_mfma_f32_16x16x32_bf16 v[18:21], v[156:159], v[230:233], v[18:21]
	v_mfma_f32_16x16x32_bf16 v[14:17], v[182:185], v[230:233], v[14:17]
	s_setprio 0
	s_setprio 1
	v_mfma_f32_16x16x32_bf16 v[54:57], v[186:189], v[202:205], 0
	v_mfma_f32_16x16x32_bf16 v[42:45], v[194:197], v[202:205], 0
	v_mfma_f32_16x16x32_bf16 v[38:41], v[186:189], v[210:213], 0
	v_mfma_f32_16x16x32_bf16 v[26:29], v[194:197], v[210:213], 0
	v_mfma_f32_16x16x32_bf16 v[22:25], v[186:189], v[218:221], 0
	v_mfma_f32_16x16x32_bf16 v[10:13], v[194:197], v[218:221], 0
	v_mfma_f32_16x16x32_bf16 v[6:9], v[186:189], v[226:229], 0
	v_mfma_f32_16x16x32_bf16 v[2:5], v[194:197], v[226:229], 0
	v_mfma_f32_16x16x32_bf16 v[54:57], v[190:193], v[206:209], v[54:57]
	v_mfma_f32_16x16x32_bf16 v[42:45], v[198:201], v[206:209], v[42:45]
	v_mfma_f32_16x16x32_bf16 v[38:41], v[190:193], v[214:217], v[38:41]
	v_mfma_f32_16x16x32_bf16 v[26:29], v[198:201], v[214:217], v[26:29]
	v_mfma_f32_16x16x32_bf16 v[22:25], v[190:193], v[222:225], v[22:25]
	v_mfma_f32_16x16x32_bf16 v[10:13], v[198:201], v[222:225], v[10:13]
	v_mfma_f32_16x16x32_bf16 v[6:9], v[190:193], v[230:233], v[6:9]
	v_mfma_f32_16x16x32_bf16 v[2:5], v[198:201], v[230:233], v[2:5]
	s_setprio 0
	s_barrier
	s_add_i32 s81, 0, 0x18000
	v_add_u32_e32 v138, s81, v172
	s_add_i32 s82, 0, 0x1c000
	ds_read_b128 v[152:155], v138
	ds_read_b128 v[156:159], v138 offset:1024
	ds_read_b128 v[160:163], v138 offset:2048
	ds_read_b128 v[182:185], v138 offset:3072
	v_add_u32_e32 v138, s82, v172
	ds_read_b128 v[186:189], v138
	ds_read_b128 v[190:193], v138 offset:1024
	ds_read_b128 v[194:197], v138 offset:2048
	ds_read_b128 v[198:201], v138 offset:3072
	s_add_u32 s46, s46, 0x40000
	s_addc_u32 s47, s47, 0
	s_mov_b32 m0, s52
	v_lshl_add_u64 v[242:243], s[46:47], 0, v[130:131]
	ds_read_b128 v[202:205], v178 offset:32768
	ds_read_b128 v[206:209], v178 offset:33792
	ds_read_b128 v[210:213], v178 offset:34816
	ds_read_b128 v[214:217], v178 offset:35840
	ds_read_b128 v[218:221], v178 offset:36864
	ds_read_b128 v[222:225], v178 offset:37888
	ds_read_b128 v[226:229], v178 offset:38912
	ds_read_b128 v[230:233], v178 offset:39936
	global_load_lds_dwordx4 v[242:243], off
	v_lshl_add_u64 v[242:243], s[46:47], 0, v[134:135]
	s_mov_b32 m0, s53
	s_nop 0
	global_load_lds_dwordx4 v[242:243], off
	s_waitcnt vmcnt(8)
	s_waitcnt lgkmcnt(0)
	s_barrier
	s_setprio 1
	s_waitcnt lgkmcnt(0)
	v_mfma_f32_16x16x32_bf16 v[126:129], v[152:155], v[202:205], v[126:129]
	v_mfma_f32_16x16x32_bf16 v[122:125], v[160:163], v[202:205], v[122:125]
	v_mfma_f32_16x16x32_bf16 v[114:117], v[152:155], v[210:213], v[114:117]
	v_mfma_f32_16x16x32_bf16 v[110:113], v[160:163], v[210:213], v[110:113]
	v_mfma_f32_16x16x32_bf16 v[98:101], v[152:155], v[218:221], v[98:101]
	v_mfma_f32_16x16x32_bf16 v[94:97], v[160:163], v[218:221], v[94:97]
	v_mfma_f32_16x16x32_bf16 v[82:85], v[152:155], v[226:229], v[82:85]
	v_mfma_f32_16x16x32_bf16 v[78:81], v[160:163], v[226:229], v[78:81]
	v_mfma_f32_16x16x32_bf16 v[126:129], v[156:159], v[206:209], v[126:129]
	v_mfma_f32_16x16x32_bf16 v[122:125], v[182:185], v[206:209], v[122:125]
	v_mfma_f32_16x16x32_bf16 v[114:117], v[156:159], v[214:217], v[114:117]
	v_mfma_f32_16x16x32_bf16 v[110:113], v[182:185], v[214:217], v[110:113]
	v_mfma_f32_16x16x32_bf16 v[98:101], v[156:159], v[222:225], v[98:101]
	v_mfma_f32_16x16x32_bf16 v[94:97], v[182:185], v[222:225], v[94:97]
	v_mfma_f32_16x16x32_bf16 v[82:85], v[156:159], v[230:233], v[82:85]
	v_mfma_f32_16x16x32_bf16 v[78:81], v[182:185], v[230:233], v[78:81]
	s_setprio 0
	s_setprio 1
	v_mfma_f32_16x16x32_bf16 v[118:121], v[186:189], v[202:205], v[118:121]
	v_mfma_f32_16x16x32_bf16 v[106:109], v[194:197], v[202:205], v[106:109]
	v_mfma_f32_16x16x32_bf16 v[102:105], v[186:189], v[210:213], v[102:105]
	v_mfma_f32_16x16x32_bf16 v[90:93], v[194:197], v[210:213], v[90:93]
	v_mfma_f32_16x16x32_bf16 v[86:89], v[186:189], v[218:221], v[86:89]
	v_mfma_f32_16x16x32_bf16 v[74:77], v[194:197], v[218:221], v[74:77]
	v_mfma_f32_16x16x32_bf16 v[70:73], v[186:189], v[226:229], v[70:73]
	v_mfma_f32_16x16x32_bf16 v[66:69], v[194:197], v[226:229], v[66:69]
	v_mfma_f32_16x16x32_bf16 v[118:121], v[190:193], v[206:209], v[118:121]
	v_mfma_f32_16x16x32_bf16 v[106:109], v[198:201], v[206:209], v[106:109]
	v_mfma_f32_16x16x32_bf16 v[102:105], v[190:193], v[214:217], v[102:105]
	v_mfma_f32_16x16x32_bf16 v[90:93], v[198:201], v[214:217], v[90:93]
	v_mfma_f32_16x16x32_bf16 v[86:89], v[190:193], v[222:225], v[86:89]
	v_mfma_f32_16x16x32_bf16 v[74:77], v[198:201], v[222:225], v[74:77]
	v_mfma_f32_16x16x32_bf16 v[70:73], v[190:193], v[230:233], v[70:73]
	v_mfma_f32_16x16x32_bf16 v[66:69], v[198:201], v[230:233], v[66:69]
	s_setprio 0
	s_barrier
; #define PG8_STAGE(bufoff, gbase, voff) do { _Pragma("unroll") for (int _i = 0; _i < 2; ++_i) \
;         __builtin_amdgcn_global_load_lds((const unsigned*)((const char*)(gbase) + (voff)[_i]), (PG8_LAS unsigned*)(lds + (bufoff) + ldsw + _i * 8192), 16, 0, 0); } while (0)
; #define PG8_LDA(dst, b, h) do { _Pragma("unroll") for (int m = 0; m < 4; ++m) _Pragma("unroll") for (int k = 0; k < 2; ++k) dst[m][k] = *(const PG8_LAS bf16x8*)(lds + PG8_SA(b, h) + aoff + m * 2048 + k * 1024); } while (0)
; #define PG8_MMA(ai, bj, At, Bt) do { __builtin_amdgcn_s_setprio(1); _Pragma("unroll") for (int m = 0; m < 4; ++m) _Pragma("unroll") for (int n = 0; n < 2; ++n) _Pragma("unroll") for (int k = 0; k < 2; ++k) \
;         acc[ai][bj][m][n] = __builtin_amdgcn_mfma_f32_16x16x32_bf16(Bt[n][k], At[m][k], acc[ai][bj][m][n], 0, 0, 0); __builtin_amdgcn_s_setprio(0); } while (0)
; #define PG8_WAIT_V(n) asm volatile("s_waitcnt vmcnt(" #n ")" ::: "memory")
; #define PG8_WAIT_L(n) asm volatile("s_waitcnt lgkmcnt(" #n ")" ::: "memory")
; #define PG8_BAR __builtin_amdgcn_s_barrier()
; #define PG8_SCHED __builtin_amdgcn_sched_barrier(0)
; template <class Epi, class Sched, bool ALIGN_EPI = false, bool SP2 = false>
; __device__ __forceinline__ void gemm_phase(PG8_LAS unsigned char* lds, const Gemm g, const Sched& S, const Epi& E) {
;     ...
;         for (int t = 0; t < nt; t += 2) {
;     ...
;             PG8_LDA(At, 1, 1); PG8_STAGE(PG8_SB(1, 0), b3, voffB); PG8_STAGE(PG8_SB(1, 1), b3 + hstep, voffB); PG8_STAGE(PG8_SA(1, 0), a3, voffA);
;             PG8_WAIT_V(8); PG8_WAIT_L(0); PG8_BAR; PG8_MMA(1, 0, At, B0); PG8_MMA(1, 1, At, B1); PG8_BAR; PG8_SCHED;
	s_add_i32 s46, s81, s15
	v_lshl_add_u64 v[234:235], v[234:235], 0, s[20:21]
	s_mov_b32 m0, s46
	ds_read_b128 v[202:205], v178 offset:49152
	ds_read_b128 v[206:209], v178 offset:50176
	ds_read_b128 v[210:213], v178 offset:51200
	ds_read_b128 v[214:217], v178 offset:52224
	ds_read_b128 v[218:221], v178 offset:53248
	ds_read_b128 v[222:225], v178 offset:54272
	ds_read_b128 v[226:229], v178 offset:55296
	ds_read_b128 v[230:233], v178 offset:56320
	global_load_lds_dwordx4 v[234:235], off
	s_add_i32 m0, s46, 0x2000
	s_add_u32 s44, s44, 0x40080
	v_lshl_add_u64 v[234:235], v[236:237], 0, s[20:21]
	s_addc_u32 s45, s45, 0
	s_add_i32 s46, s82, s15
	global_load_lds_dwordx4 v[234:235], off
	v_lshl_add_u64 v[234:235], s[44:45], 0, v[132:133]
	s_mov_b32 m0, s46
	s_nop 0
	global_load_lds_dwordx4 v[234:235], off
	v_lshl_add_u64 v[234:235], s[44:45], 0, v[136:137]
	s_add_i32 m0, s46, 0x2000
	s_nop 0
	global_load_lds_dwordx4 v[234:235], off
	v_lshl_add_u64 v[234:235], v[238:239], 0, s[20:21]
	s_mov_b32 m0, s57
	s_nop 0
	global_load_lds_dwordx4 v[234:235], off
	v_lshl_add_u64 v[234:235], v[240:241], 0, s[20:21]
	s_mov_b32 m0, s58
	s_nop 0
	global_load_lds_dwordx4 v[234:235], off
	s_waitcnt vmcnt(8)
	s_waitcnt lgkmcnt(0)
	s_barrier
	s_setprio 1
	s_waitcnt lgkmcnt(0)
	v_mfma_f32_16x16x32_bf16 v[62:65], v[152:155], v[202:205], v[62:65]
	v_mfma_f32_16x16x32_bf16 v[58:61], v[160:163], v[202:205], v[58:61]
	v_mfma_f32_16x16x32_bf16 v[50:53], v[152:155], v[210:213], v[50:53]
	v_mfma_f32_16x16x32_bf16 v[46:49], v[160:163], v[210:213], v[46:49]
	v_mfma_f32_16x16x32_bf16 v[34:37], v[152:155], v[218:221], v[34:37]
	v_mfma_f32_16x16x32_bf16 v[30:33], v[160:163], v[218:221], v[30:33]
	v_mfma_f32_16x16x32_bf16 v[18:21], v[152:155], v[226:229], v[18:21]
	v_mfma_f32_16x16x32_bf16 v[14:17], v[160:163], v[226:229], v[14:17]
	v_mfma_f32_16x16x32_bf16 v[62:65], v[156:159], v[206:209], v[62:65]
	v_mfma_f32_16x16x32_bf16 v[58:61], v[182:185], v[206:209], v[58:61]
	v_mfma_f32_16x16x32_bf16 v[50:53], v[156:159], v[214:217], v[50:53]
	v_mfma_f32_16x16x32_bf16 v[46:49], v[182:185], v[214:217], v[46:49]
	v_mfma_f32_16x16x32_bf16 v[34:37], v[156:159], v[222:225], v[34:37]
	v_mfma_f32_16x16x32_bf16 v[30:33], v[182:185], v[222:225], v[30:33]
	v_mfma_f32_16x16x32_bf16 v[18:21], v[156:159], v[230:233], v[18:21]
	v_mfma_f32_16x16x32_bf16 v[14:17], v[182:185], v[230:233], v[14:17]
	s_setprio 0
	s_setprio 1
	v_mfma_f32_16x16x32_bf16 v[54:57], v[186:189], v[202:205], v[54:57]
	v_mfma_f32_16x16x32_bf16 v[42:45], v[194:197], v[202:205], v[42:45]
	v_mfma_f32_16x16x32_bf16 v[38:41], v[186:189], v[210:213], v[38:41]
	v_mfma_f32_16x16x32_bf16 v[26:29], v[194:197], v[210:213], v[26:29]
	v_mfma_f32_16x16x32_bf16 v[22:25], v[186:189], v[218:221], v[22:25]
	v_mfma_f32_16x16x32_bf16 v[10:13], v[194:197], v[218:221], v[10:13]
	v_mfma_f32_16x16x32_bf16 v[6:9], v[186:189], v[226:229], v[6:9]
	v_mfma_f32_16x16x32_bf16 v[2:5], v[194:197], v[226:229], v[2:5]
	v_mfma_f32_16x16x32_bf16 v[54:57], v[190:193], v[206:209], v[54:57]
	v_mfma_f32_16x16x32_bf16 v[42:45], v[198:201], v[206:209], v[42:45]
	v_mfma_f32_16x16x32_bf16 v[38:41], v[190:193], v[214:217], v[38:41]
	v_mfma_f32_16x16x32_bf16 v[26:29], v[198:201], v[214:217], v[26:29]
	v_mfma_f32_16x16x32_bf16 v[22:25], v[190:193], v[222:225], v[22:25]
	v_mfma_f32_16x16x32_bf16 v[10:13], v[198:201], v[222:225], v[10:13]
	v_mfma_f32_16x16x32_bf16 v[6:9], v[190:193], v[230:233], v[6:9]
	v_mfma_f32_16x16x32_bf16 v[2:5], v[198:201], v[230:233], v[2:5]
	s_setprio 0
	s_barrier
	s_add_i32 s80, s80, 2
	s_add_u32 s42, s42, 0x100
	s_addc_u32 s43, s43, 0
	s_add_u32 s78, s78, 0x100
	s_addc_u32 s79, s79, 0
	s_cmp_gt_u32 s80, 13

;     __device__ __forceinline__ void operator()(const f32x4 (&acc)[2][2][4][2], const Unit& u, int wr, int wc, int fr, int fq) const {
;         const int pn = u.pn; const size_t row0 = (size_t)u.pm * BM + wr * 64 + fr;
;         if (pn < 4) {
.LBB0_237:
	s_mov_b32 s89, 1
	s_ashr_i32 s7, s6, 31
	s_lshl_b64 s[6:7], s[6:7], 8
	v_lshl_add_u64 v[152:153], s[6:7], 0, v[140:141]
	s_cmp_gt_i32 s40, 3
	s_mov_b64 s[6:7], -1
	s_cbranch_scc1 .LBB0_240
	s_andn2_b64 vcc, exec, s[6:7]
	s_cbranch_vccz .LBB0_281

; __device__ __forceinline__ float silu(float x) { return x * sigm(x); }
;     __device__ __forceinline__ void operator()(const f32x4 (&acc)[2][2][4][2], const Unit& u, int wr, int wc, int fr, int fq) const {
;     ...
;         } else {
;             size_t doff; int ld, tcol, act;
;             if (pn < 6) { doff = OFF_V; ld = 512; tcol = (pn - 4) * 256; act = 0; }
;             else { doff = OFF_SZA; ld = 512; tcol = (pn - 6) * 256; act = 1; }
;             bf16_t* dst = (bf16_t*)(ws + doff);
;             const int colb = tcol + 64 * wc + 8 * fq;
; #pragma unroll
;             for (int ai = 0; ai < 2; ++ai)
; #pragma unroll
;                 for (int m = 0; m < 4; ++m) { bf16_t* rowp = dst + (row0 + ai * HALF + m * 16) * ld + colb;
; #pragma unroll
;                     for (int bj = 0; bj < 2; ++bj) { f32x4 v0 = acc[ai][bj][m][0], v1 = acc[ai][bj][m][1];
;                         if (act == 1) { v0[0] = silu(v0[0]); v0[1] = silu(v0[1]); v0[2] = silu(v0[2]); v0[3] = silu(v0[3]); v1[0] = silu(v1[0]); v1[1] = silu(v1[1]); v1[2] = silu(v1[2]); v1[3] = silu(v1[3]); }
.LBB0_240:
	s_and_b32 s6, s40, 0x7ffffff8
	s_cmp_lg_u32 s6, 8
	s_mov_b64 s[6:7], -1
	s_cbranch_scc0 .LBB0_278
	s_cmp_lt_u32 s40, 16
	s_cbranch_scc0 .LBB0_275
	s_mov_b32 s89, 2
	s_cmp_gt_u32 s40, 5
	s_cselect_b64 s[42:43], -1, 0
	s_cmp_lt_u32 s40, 6
	v_mov_b32_e32 v159, v125
	v_mov_b32_e32 v158, v124
	v_mov_b32_e32 v163, v123
	v_mov_b32_e32 v162, v122
	v_mov_b32_e32 v157, v129
	v_mov_b32_e32 v156, v128
	v_mov_b32_e32 v161, v127
	v_mov_b32_e32 v160, v126
	s_cbranch_scc1 .LBB0_244
	v_mul_f32_e32 v138, 0xbfb8aa3b, v126
	v_exp_f32_e32 v138, v138
	v_mul_f32_e32 v154, 0xbfb8aa3b, v127
	v_mul_f32_e32 v155, 0xbfb8aa3b, v128
	v_exp_f32_e32 v156, v154
	v_exp_f32_e32 v157, v155
	v_add_f32_e32 v138, 1.0, v138
	v_rcp_f32_e32 v154, v138
	v_add_f32_e32 v138, 1.0, v156
	v_mul_f32_e32 v156, 0xbfb8aa3b, v129
	v_rcp_f32_e32 v155, v138
	v_add_f32_e32 v138, 1.0, v157
	v_exp_f32_e32 v157, v156
	v_mul_f32_e32 v156, 0xbfb8aa3b, v122
	v_exp_f32_e32 v158, v156
	v_rcp_f32_e32 v156, v138
	v_add_f32_e32 v138, 1.0, v157
	v_rcp_f32_e32 v157, v138
	v_add_f32_e32 v138, 1.0, v158
	v_rcp_f32_e32 v162, v138
	v_mul_f32_e32 v138, 0xbfb8aa3b, v123
	v_mul_f32_e32 v158, 0xbfb8aa3b, v124
	v_mul_f32_e32 v159, 0xbfb8aa3b, v125
	v_exp_f32_e32 v138, v138
	v_exp_f32_e32 v158, v158
	v_exp_f32_e32 v159, v159
	v_pk_mul_f32 v[156:157], v[128:129], v[156:157]
	v_add_f32_e32 v138, 1.0, v138
	v_add_f32_e32 v158, 1.0, v158
	v_add_f32_e32 v159, 1.0, v159
	v_rcp_f32_e32 v158, v158
	v_rcp_f32_e32 v159, v159
	v_rcp_f32_e32 v163, v138
	v_pk_mul_f32 v[160:161], v[126:127], v[154:155]
	v_pk_mul_f32 v[158:159], v[124:125], v[158:159]
	v_pk_mul_f32 v[162:163], v[122:123], v[162:163]

; __device__ __forceinline__ float sigm(float x) { return __builtin_amdgcn_rcpf(1.0f + __builtin_amdgcn_exp2f(x * -1.4426950408889634f)); }
;     __device__ __forceinline__ void operator()(const f32x4 (&acc)[2][2][4][2], const Unit& u, int wr, int wc, int fr, int fq) const {
;     ...
;         } else if (pn >= 16) {
;             const int col = 128 * (pn - 16) + 32 * wc + 8 * fq; unsigned short* AB = (unsigned short*)(ws + OFF_SGA);
; #pragma unroll
;             for (int ai = 0; ai < 2; ++ai)
; #pragma unroll
;                 for (int m = 0; m < 4; ++m) { const size_t off = (row0 + ai * HALF + m * 16) * 1024 + col;
;                     unsigned wd[4];
; #pragma unroll
;                     for (int n = 0; n < 2; ++n)
; #pragma unroll
;                         for (int h = 0; h < 2; ++h) { unsigned d = 0u;
; #pragma unroll
;                             for (int e = 0; e < 2; ++e) { const int i = 2 * h + e; const unsigned ta = (unsigned)(sigm(acc[ai][0][m][n][i]) * 255.0f + 0.5f); unsigned tb = (unsigned)(sigm(acc[ai][1][m][n][i]) * 255.0f + 0.5f); tb = tb < 1u ? 1u : tb;
;                                 d |= (ta | (tb << 8)) << (16 * e); }
;                             wd[2 * n + h] = d; }
;                     *(u32x4*)(AB + off) = (u32x4){wd[0], wd[1], wd[2], wd[3]};
;                     asm volatile("" ::: "memory"); }
.LBB0_275:
	s_and_b64 vcc, exec, s[6:7]
	s_cbranch_vccz .LBB0_277
	s_mov_b32 s89, 1
	v_mul_f32_e32 v154, 0xbfb8aa3b, v126
	v_exp_f32_e32 v156, v154
	v_mul_f32_e32 v154, 0xbfb8aa3b, v118
	v_exp_f32_e32 v157, v154
	v_lshl_add_u32 v138, s40, 7, v173
	v_lshl_add_u64 v[154:155], v[138:139], 1, s[26:27]
	v_add_f32_e32 v138, 1.0, v156
	v_rcp_f32_e32 v156, v138
	v_add_f32_e32 v138, 1.0, v157
	v_mul_f32_e32 v157, 0xbfb8aa3b, v127
	v_exp_f32_e32 v157, v157
	v_mul_f32_e32 v158, 0xbfb8aa3b, v119
	v_exp_f32_e32 v159, v158
	v_rcp_f32_e32 v158, v138
	v_add_f32_e32 v138, 1.0, v157
	v_mul_f32_e32 v157, 0xbfb8aa3b, v128
	v_rcp_f32_e32 v160, v138
	v_add_f32_e32 v138, 1.0, v159
	v_exp_f32_e32 v157, v157
	v_mul_f32_e32 v159, 0xbfb8aa3b, v120
	v_exp_f32_e32 v159, v159
	v_rcp_f32_e32 v162, v138
	v_add_f32_e32 v138, 1.0, v157
	v_rcp_f32_e32 v157, v138
	v_add_f32_e32 v138, 1.0, v159
	v_mul_f32_e32 v159, 0xbfb8aa3b, v129
	v_exp_f32_e32 v161, v159
	v_mul_f32_e32 v159, 0xbfb8aa3b, v121
	v_exp_f32_e32 v163, v159
	v_rcp_f32_e32 v159, v138
	v_add_f32_e32 v138, 1.0, v161
	v_rcp_f32_e32 v161, v138
	v_add_f32_e32 v138, 1.0, v163
	v_pk_fma_f32 v[158:159], v[158:159], s[28:29], 0.5 op_sel_hi:[1,0,0]
	v_rcp_f32_e32 v163, v138
	v_cvt_u32_f32_e32 v138, v158
	v_cvt_u32_f32_e32 v158, v159
	v_pk_fma_f32 v[156:157], v[156:157], s[28:29], 0.5 op_sel_hi:[1,0,0]
	v_max_u32_e32 v138, 1, v138
	v_cvt_u32_f32_e32 v183, v156
	v_max_u32_e32 v156, 1, v158
	v_cvt_u32_f32_e32 v182, v157
	v_lshlrev_b32_e32 v184, 8, v156
	v_pk_fma_f32 v[156:157], v[160:161], s[28:29], 0.5 op_sel_hi:[1,0,0]
	v_pk_fma_f32 v[158:159], v[162:163], s[28:29], 0.5 op_sel_hi:[1,0,0]
	v_cvt_u32_f32_sdwa v156, v156 dst_sel:WORD_1 dst_unused:UNUSED_PAD src0_sel:DWORD
	v_cvt_u32_f32_e32 v158, v158
	v_cvt_u32_f32_e32 v159, v159
	v_cvt_u32_f32_sdwa v157, v157 dst_sel:WORD_1 dst_unused:UNUSED_PAD src0_sel:DWORD
	v_or_b32_e32 v156, v156, v183
	v_max_u32_sdwa v158, v158, v171 dst_sel:BYTE_3 dst_unused:UNUSED_PAD src0_sel:DWORD src1_sel:DWORD
	v_max_u32_sdwa v159, v159, v171 dst_sel:BYTE_3 dst_unused:UNUSED_PAD src0_sel:DWORD src1_sel:DWORD
	v_or_b32_e32 v157, v157, v182
	v_or_b32_e32 v156, v156, v158
	v_mul_f32_e32 v158, 0xbfb8aa3b, v122
	v_or_b32_e32 v157, v157, v159
	v_exp_f32_e32 v158, v158
	v_mul_f32_e32 v159, 0xbfb8aa3b, v106
	v_exp_f32_e32 v159, v159
	v_lshlrev_b32_e32 v138, 8, v138
	v_or_b32_e32 v156, v156, v138
	v_add_f32_e32 v138, 1.0, v158
	v_rcp_f32_e32 v158, v138
	v_add_f32_e32 v138, 1.0, v159
	v_mul_f32_e32 v159, 0xbfb8aa3b, v123
	v_exp_f32_e32 v159, v159
	v_mul_f32_e32 v160, 0xbfb8aa3b, v107
	v_exp_f32_e32 v161, v160
	v_rcp_f32_e32 v160, v138
	v_add_f32_e32 v138, 1.0, v159
	v_mul_f32_e32 v159, 0xbfb8aa3b, v124
	v_rcp_f32_e32 v162, v138
	v_add_f32_e32 v138, 1.0, v161
	v_exp_f32_e32 v159, v159
	v_mul_f32_e32 v161, 0xbfb8aa3b, v108
	v_exp_f32_e32 v161, v161
	v_rcp_f32_e32 v182, v138
	v_add_f32_e32 v138, 1.0, v159
	v_rcp_f32_e32 v159, v138
	v_add_f32_e32 v138, 1.0, v161
	v_mul_f32_e32 v161, 0xbfb8aa3b, v125
	v_exp_f32_e32 v163, v161
	v_mul_f32_e32 v161, 0xbfb8aa3b, v109
	v_exp_f32_e32 v183, v161
	v_rcp_f32_e32 v161, v138
	v_add_f32_e32 v138, 1.0, v163
	v_rcp_f32_e32 v163, v138
	v_add_f32_e32 v138, 1.0, v183
	v_pk_fma_f32 v[160:161], v[160:161], s[28:29], 0.5 op_sel_hi:[1,0,0]
	v_rcp_f32_e32 v183, v138
	v_cvt_u32_f32_e32 v138, v160
	v_cvt_u32_f32_e32 v160, v161
	v_pk_fma_f32 v[158:159], v[158:159], s[28:29], 0.5 op_sel_hi:[1,0,0]
	v_or_b32_e32 v157, v157, v184
	v_cvt_u32_f32_e32 v185, v158
	v_max_u32_e32 v158, 1, v160
	v_cvt_u32_f32_e32 v184, v159
	v_lshlrev_b32_e32 v186, 8, v158
	v_pk_fma_f32 v[158:159], v[162:163], s[28:29], 0.5 op_sel_hi:[1,0,0]
	v_pk_fma_f32 v[160:161], v[182:183], s[28:29], 0.5 op_sel_hi:[1,0,0]
	v_cvt_u32_f32_sdwa v159, v159 dst_sel:WORD_1 dst_unused:UNUSED_PAD src0_sel:DWORD
	v_cvt_u32_f32_e32 v160, v160
	v_cvt_u32_f32_e32 v161, v161
	v_cvt_u32_f32_sdwa v158, v158 dst_sel:WORD_1 dst_unused:UNUSED_PAD src0_sel:DWORD
	v_max_u32_e32 v138, 1, v138
	v_max_u32_sdwa v160, v160, v171 dst_sel:BYTE_3 dst_unused:UNUSED_PAD src0_sel:DWORD src1_sel:DWORD
	v_max_u32_sdwa v161, v161, v171 dst_sel:BYTE_3 dst_unused:UNUSED_PAD src0_sel:DWORD src1_sel:DWORD
	v_or_b32_e32 v159, v159, v184
	v_or_b32_e32 v158, v158, v185
	v_lshlrev_b32_e32 v138, 8, v138
	v_or_b32_e32 v159, v159, v161
	v_or_b32_e32 v158, v158, v160
	v_lshlrev_b64 v[160:161], 11, v[152:153]
	v_or_b32_e32 v159, v159, v186
	v_or_b32_e32 v158, v158, v138
	v_lshl_add_u64 v[154:155], v[154:155], 0, v[160:161]
	v_mul_f32_e32 v138, 0xbfb8aa3b, v114
	global_store_dwordx4 v[154:155], v[156:159], off
	v_exp_f32_e32 v138, v138
	s_nop 0
	v_mul_f32_e32 v156, 0xbfb8aa3b, v102
	v_exp_f32_e32 v157, v156
	v_add_f32_e32 v138, 1.0, v138
	v_rcp_f32_e32 v156, v138
	v_mul_f32_e32 v158, 0xbfb8aa3b, v103
	v_add_f32_e32 v138, 1.0, v157
	v_mul_f32_e32 v157, 0xbfb8aa3b, v115
	v_exp_f32_e32 v157, v157
	v_exp_f32_e32 v159, v158
	v_rcp_f32_e32 v158, v138
	v_add_f32_e32 v138, 1.0, v157
	v_mul_f32_e32 v157, 0xbfb8aa3b, v116
	v_rcp_f32_e32 v160, v138
	v_add_f32_e32 v138, 1.0, v159
	v_exp_f32_e32 v157, v157
	v_mul_f32_e32 v159, 0xbfb8aa3b, v104
	v_exp_f32_e32 v159, v159
	v_rcp_f32_e32 v162, v138
	v_add_f32_e32 v138, 1.0, v157
	v_rcp_f32_e32 v157, v138
	v_add_f32_e32 v138, 1.0, v159
	v_mul_f32_e32 v159, 0xbfb8aa3b, v117
	v_exp_f32_e32 v161, v159
	v_mul_f32_e32 v159, 0xbfb8aa3b, v105
	v_exp_f32_e32 v163, v159
	v_rcp_f32_e32 v159, v138
	v_add_f32_e32 v138, 1.0, v161
	v_rcp_f32_e32 v161, v138
	v_add_f32_e32 v138, 1.0, v163
	v_pk_fma_f32 v[158:159], v[158:159], s[28:29], 0.5 op_sel_hi:[1,0,0]
	v_rcp_f32_e32 v163, v138
	v_cvt_u32_f32_e32 v138, v158
	v_cvt_u32_f32_e32 v158, v159
; __device__ __forceinline__ float sigm(float x) { return __builtin_amdgcn_rcpf(1.0f + __builtin_amdgcn_exp2f(x * -1.4426950408889634f)); }
;     __device__ __forceinline__ void operator()(const f32x4 (&acc)[2][2][4][2], const Unit& u, int wr, int wc, int fr, int fq) const {
;     ...
;                 for (int m = 0; m < 4; ++m) { const size_t off = (row0 + ai * HALF + m * 16) * 1024 + col;
;                     unsigned wd[4];
; #pragma unroll
;                     for (int n = 0; n < 2; ++n)
; #pragma unroll
;                         for (int h = 0; h < 2; ++h) { unsigned d = 0u;
; #pragma unroll
;                             for (int e = 0; e < 2; ++e) { const int i = 2 * h + e; const unsigned ta = (unsigned)(sigm(acc[ai][0][m][n][i]) * 255.0f + 0.5f); unsigned tb = (unsigned)(sigm(acc[ai][1][m][n][i]) * 255.0f + 0.5f); tb = tb < 1u ? 1u : tb;
;                                 d |= (ta | (tb << 8)) << (16 * e); }
;                             wd[2 * n + h] = d; }
;                     *(u32x4*)(AB + off) = (u32x4){wd[0], wd[1], wd[2], wd[3]};
;                     asm volatile("" ::: "memory"); }
	v_pk_fma_f32 v[156:157], v[156:157], s[28:29], 0.5 op_sel_hi:[1,0,0]
	v_max_u32_e32 v138, 1, v138
	v_cvt_u32_f32_e32 v183, v156
	v_max_u32_e32 v156, 1, v158
	v_cvt_u32_f32_e32 v182, v157
	v_lshlrev_b32_e32 v184, 8, v156
	v_pk_fma_f32 v[156:157], v[160:161], s[28:29], 0.5 op_sel_hi:[1,0,0]
	v_pk_fma_f32 v[158:159], v[162:163], s[28:29], 0.5 op_sel_hi:[1,0,0]
	v_cvt_u32_f32_sdwa v156, v156 dst_sel:WORD_1 dst_unused:UNUSED_PAD src0_sel:DWORD
	v_cvt_u32_f32_e32 v158, v158
	v_cvt_u32_f32_e32 v159, v159
	v_cvt_u32_f32_sdwa v157, v157 dst_sel:WORD_1 dst_unused:UNUSED_PAD src0_sel:DWORD
	v_or_b32_e32 v156, v156, v183
	v_max_u32_sdwa v158, v158, v171 dst_sel:BYTE_3 dst_unused:UNUSED_PAD src0_sel:DWORD src1_sel:DWORD
	v_max_u32_sdwa v159, v159, v171 dst_sel:BYTE_3 dst_unused:UNUSED_PAD src0_sel:DWORD src1_sel:DWORD
	v_or_b32_e32 v157, v157, v182
	v_or_b32_e32 v156, v156, v158
	v_mul_f32_e32 v158, 0xbfb8aa3b, v110
	v_or_b32_e32 v157, v157, v159
	v_exp_f32_e32 v158, v158
	v_mul_f32_e32 v159, 0xbfb8aa3b, v90
	v_exp_f32_e32 v159, v159
	v_lshlrev_b32_e32 v138, 8, v138
	v_or_b32_e32 v156, v156, v138
	v_add_f32_e32 v138, 1.0, v158
	v_rcp_f32_e32 v158, v138
	v_add_f32_e32 v138, 1.0, v159
	v_mul_f32_e32 v159, 0xbfb8aa3b, v111
	v_exp_f32_e32 v159, v159
	v_mul_f32_e32 v160, 0xbfb8aa3b, v91
	v_exp_f32_e32 v161, v160
	v_rcp_f32_e32 v160, v138
	v_add_f32_e32 v138, 1.0, v159
	v_mul_f32_e32 v159, 0xbfb8aa3b, v112
	v_rcp_f32_e32 v162, v138
	v_add_f32_e32 v138, 1.0, v161
	v_exp_f32_e32 v159, v159
	v_mul_f32_e32 v161, 0xbfb8aa3b, v92
	v_exp_f32_e32 v161, v161
	v_rcp_f32_e32 v182, v138
	v_add_f32_e32 v138, 1.0, v159
	v_rcp_f32_e32 v159, v138
	v_add_f32_e32 v138, 1.0, v161
	v_mul_f32_e32 v161, 0xbfb8aa3b, v113
	v_exp_f32_e32 v163, v161
	v_mul_f32_e32 v161, 0xbfb8aa3b, v93
	v_exp_f32_e32 v183, v161
	v_rcp_f32_e32 v161, v138
	v_add_f32_e32 v138, 1.0, v163
	v_rcp_f32_e32 v163, v138
	v_add_f32_e32 v138, 1.0, v183
	v_pk_fma_f32 v[160:161], v[160:161], s[28:29], 0.5 op_sel_hi:[1,0,0]
	v_rcp_f32_e32 v183, v138
	v_cvt_u32_f32_e32 v138, v160
	v_cvt_u32_f32_e32 v160, v161
	v_pk_fma_f32 v[158:159], v[158:159], s[28:29], 0.5 op_sel_hi:[1,0,0]
	v_or_b32_e32 v157, v157, v184
	v_cvt_u32_f32_e32 v185, v158
	v_max_u32_e32 v158, 1, v160
	v_cvt_u32_f32_e32 v184, v159
	v_lshlrev_b32_e32 v186, 8, v158
	v_pk_fma_f32 v[158:159], v[162:163], s[28:29], 0.5 op_sel_hi:[1,0,0]
	v_pk_fma_f32 v[160:161], v[182:183], s[28:29], 0.5 op_sel_hi:[1,0,0]
	v_cvt_u32_f32_sdwa v159, v159 dst_sel:WORD_1 dst_unused:UNUSED_PAD src0_sel:DWORD
	v_cvt_u32_f32_e32 v160, v160
	v_cvt_u32_f32_e32 v161, v161
	v_cvt_u32_f32_sdwa v158, v158 dst_sel:WORD_1 dst_unused:UNUSED_PAD src0_sel:DWORD
	v_max_u32_e32 v138, 1, v138
	v_max_u32_sdwa v160, v160, v171 dst_sel:BYTE_3 dst_unused:UNUSED_PAD src0_sel:DWORD src1_sel:DWORD
	v_max_u32_sdwa v161, v161, v171 dst_sel:BYTE_3 dst_unused:UNUSED_PAD src0_sel:DWORD src1_sel:DWORD
	v_or_b32_e32 v159, v159, v184
	v_or_b32_e32 v158, v158, v185
	v_lshlrev_b32_e32 v138, 8, v138
	v_or_b32_e32 v159, v159, v161
	v_or_b32_e32 v158, v158, v160
	v_add_co_u32_e32 v160, vcc, s60, v154
	v_or_b32_e32 v159, v159, v186
	v_or_b32_e32 v158, v158, v138
	v_addc_co_u32_e32 v161, vcc, 0, v155, vcc
	v_mul_f32_e32 v138, 0xbfb8aa3b, v98
	global_store_dwordx4 v[160:161], v[156:159], off
	v_exp_f32_e32 v138, v138
	s_nop 0
	v_mul_f32_e32 v156, 0xbfb8aa3b, v86
	v_exp_f32_e32 v157, v156
	v_add_f32_e32 v138, 1.0, v138
	v_rcp_f32_e32 v156, v138
	v_mul_f32_e32 v158, 0xbfb8aa3b, v87
	v_add_f32_e32 v138, 1.0, v157
	v_mul_f32_e32 v157, 0xbfb8aa3b, v99
	v_exp_f32_e32 v157, v157
	v_exp_f32_e32 v159, v158
	v_rcp_f32_e32 v158, v138
	v_add_f32_e32 v138, 1.0, v157
	v_mul_f32_e32 v157, 0xbfb8aa3b, v100
	v_rcp_f32_e32 v160, v138
	v_add_f32_e32 v138, 1.0, v159
	v_exp_f32_e32 v157, v157
	v_mul_f32_e32 v159, 0xbfb8aa3b, v88
	v_exp_f32_e32 v159, v159
	v_rcp_f32_e32 v162, v138
	v_add_f32_e32 v138, 1.0, v157
	v_rcp_f32_e32 v157, v138
	v_add_f32_e32 v138, 1.0, v159
	v_mul_f32_e32 v159, 0xbfb8aa3b, v101
	v_exp_f32_e32 v161, v159
	v_mul_f32_e32 v159, 0xbfb8aa3b, v89
	v_exp_f32_e32 v163, v159
	v_rcp_f32_e32 v159, v138
	v_add_f32_e32 v138, 1.0, v161
	v_rcp_f32_e32 v161, v138
	v_add_f32_e32 v138, 1.0, v163
	v_pk_fma_f32 v[158:159], v[158:159], s[28:29], 0.5 op_sel_hi:[1,0,0]
	v_rcp_f32_e32 v163, v138
	v_cvt_u32_f32_e32 v138, v158
	v_cvt_u32_f32_e32 v158, v159
	v_pk_fma_f32 v[156:157], v[156:157], s[28:29], 0.5 op_sel_hi:[1,0,0]
	v_max_u32_e32 v138, 1, v138
	v_cvt_u32_f32_e32 v183, v156
	v_max_u32_e32 v156, 1, v158
	v_cvt_u32_f32_e32 v182, v157
	v_lshlrev_b32_e32 v184, 8, v156
	v_pk_fma_f32 v[156:157], v[160:161], s[28:29], 0.5 op_sel_hi:[1,0,0]
	v_pk_fma_f32 v[158:159], v[162:163], s[28:29], 0.5 op_sel_hi:[1,0,0]
	v_cvt_u32_f32_sdwa v156, v156 dst_sel:WORD_1 dst_unused:UNUSED_PAD src0_sel:DWORD
	v_cvt_u32_f32_e32 v158, v158
	v_cvt_u32_f32_e32 v159, v159
	v_cvt_u32_f32_sdwa v157, v157 dst_sel:WORD_1 dst_unused:UNUSED_PAD src0_sel:DWORD
	v_or_b32_e32 v156, v156, v183
	v_max_u32_sdwa v158, v158, v171 dst_sel:BYTE_3 dst_unused:UNUSED_PAD src0_sel:DWORD src1_sel:DWORD
	v_max_u32_sdwa v159, v159, v171 dst_sel:BYTE_3 dst_unused:UNUSED_PAD src0_sel:DWORD src1_sel:DWORD
	v_or_b32_e32 v157, v157, v182
	v_or_b32_e32 v156, v156, v158
	v_mul_f32_e32 v158, 0xbfb8aa3b, v94
	v_or_b32_e32 v157, v157, v159
	v_exp_f32_e32 v158, v158
	v_mul_f32_e32 v159, 0xbfb8aa3b, v74
	v_exp_f32_e32 v159, v159
	v_lshlrev_b32_e32 v138, 8, v138
	v_or_b32_e32 v156, v156, v138
	v_add_f32_e32 v138, 1.0, v158
	v_rcp_f32_e32 v158, v138
	v_add_f32_e32 v138, 1.0, v159
	v_mul_f32_e32 v159, 0xbfb8aa3b, v95
	v_exp_f32_e32 v159, v159
	v_mul_f32_e32 v160, 0xbfb8aa3b, v75
; __device__ __forceinline__ float sigm(float x) { return __builtin_amdgcn_rcpf(1.0f + __builtin_amdgcn_exp2f(x * -1.4426950408889634f)); }
;     __device__ __forceinline__ void operator()(const f32x4 (&acc)[2][2][4][2], const Unit& u, int wr, int wc, int fr, int fq) const {
;     ...
;                 for (int m = 0; m < 4; ++m) { const size_t off = (row0 + ai * HALF + m * 16) * 1024 + col;
;                     unsigned wd[4];
; #pragma unroll
;                     for (int n = 0; n < 2; ++n)
; #pragma unroll
;                         for (int h = 0; h < 2; ++h) { unsigned d = 0u;
; #pragma unroll
;                             for (int e = 0; e < 2; ++e) { const int i = 2 * h + e; const unsigned ta = (unsigned)(sigm(acc[ai][0][m][n][i]) * 255.0f + 0.5f); unsigned tb = (unsigned)(sigm(acc[ai][1][m][n][i]) * 255.0f + 0.5f); tb = tb < 1u ? 1u : tb;
;                                 d |= (ta | (tb << 8)) << (16 * e); }
;                             wd[2 * n + h] = d; }
;                     *(u32x4*)(AB + off) = (u32x4){wd[0], wd[1], wd[2], wd[3]};
;                     asm volatile("" ::: "memory"); }
	v_exp_f32_e32 v161, v160
	v_rcp_f32_e32 v160, v138
	v_add_f32_e32 v138, 1.0, v159
	v_mul_f32_e32 v159, 0xbfb8aa3b, v96
	v_rcp_f32_e32 v162, v138
	v_add_f32_e32 v138, 1.0, v161
	v_exp_f32_e32 v159, v159
	v_mul_f32_e32 v161, 0xbfb8aa3b, v76
	v_exp_f32_e32 v161, v161
	v_rcp_f32_e32 v182, v138
	v_add_f32_e32 v138, 1.0, v159
	v_rcp_f32_e32 v159, v138
	v_add_f32_e32 v138, 1.0, v161
	v_mul_f32_e32 v161, 0xbfb8aa3b, v97
	v_exp_f32_e32 v163, v161
	v_mul_f32_e32 v161, 0xbfb8aa3b, v77
	v_exp_f32_e32 v183, v161
	v_rcp_f32_e32 v161, v138
	v_add_f32_e32 v138, 1.0, v163
	v_rcp_f32_e32 v163, v138
	v_add_f32_e32 v138, 1.0, v183
	v_pk_fma_f32 v[160:161], v[160:161], s[28:29], 0.5 op_sel_hi:[1,0,0]
	v_rcp_f32_e32 v183, v138
	v_cvt_u32_f32_e32 v138, v160
	v_cvt_u32_f32_e32 v160, v161
	v_pk_fma_f32 v[158:159], v[158:159], s[28:29], 0.5 op_sel_hi:[1,0,0]
	v_or_b32_e32 v157, v157, v184
	v_cvt_u32_f32_e32 v185, v158
	v_max_u32_e32 v158, 1, v160
	v_cvt_u32_f32_e32 v184, v159
	v_lshlrev_b32_e32 v186, 8, v158
	v_pk_fma_f32 v[158:159], v[162:163], s[28:29], 0.5 op_sel_hi:[1,0,0]
	v_pk_fma_f32 v[160:161], v[182:183], s[28:29], 0.5 op_sel_hi:[1,0,0]
	v_cvt_u32_f32_sdwa v159, v159 dst_sel:WORD_1 dst_unused:UNUSED_PAD src0_sel:DWORD
	v_cvt_u32_f32_e32 v160, v160
	v_cvt_u32_f32_e32 v161, v161
	v_cvt_u32_f32_sdwa v158, v158 dst_sel:WORD_1 dst_unused:UNUSED_PAD src0_sel:DWORD
	v_max_u32_e32 v138, 1, v138
	v_max_u32_sdwa v160, v160, v171 dst_sel:BYTE_3 dst_unused:UNUSED_PAD src0_sel:DWORD src1_sel:DWORD
	v_max_u32_sdwa v161, v161, v171 dst_sel:BYTE_3 dst_unused:UNUSED_PAD src0_sel:DWORD src1_sel:DWORD
	v_or_b32_e32 v159, v159, v184
	v_or_b32_e32 v158, v158, v185
	v_lshlrev_b32_e32 v138, 8, v138
	v_or_b32_e32 v159, v159, v161
	v_or_b32_e32 v158, v158, v160
	v_add_co_u32_e32 v160, vcc, s55, v154
	v_or_b32_e32 v159, v159, v186
	v_or_b32_e32 v158, v158, v138
	v_addc_co_u32_e32 v161, vcc, 0, v155, vcc
	v_mul_f32_e32 v138, 0xbfb8aa3b, v82
	global_store_dwordx4 v[160:161], v[156:159], off
	v_exp_f32_e32 v138, v138
	s_nop 0
	v_mul_f32_e32 v156, 0xbfb8aa3b, v70
	v_exp_f32_e32 v157, v156
	v_add_f32_e32 v138, 1.0, v138
	v_rcp_f32_e32 v156, v138
	v_mul_f32_e32 v158, 0xbfb8aa3b, v71
	v_add_f32_e32 v138, 1.0, v157
	v_mul_f32_e32 v157, 0xbfb8aa3b, v83
	v_exp_f32_e32 v157, v157
	v_exp_f32_e32 v159, v158
	v_rcp_f32_e32 v158, v138
	v_add_f32_e32 v138, 1.0, v157
	v_mul_f32_e32 v157, 0xbfb8aa3b, v84
	v_rcp_f32_e32 v160, v138
	v_add_f32_e32 v138, 1.0, v159
	v_exp_f32_e32 v157, v157
	v_mul_f32_e32 v159, 0xbfb8aa3b, v72
	v_exp_f32_e32 v159, v159
	v_rcp_f32_e32 v162, v138
	v_add_f32_e32 v138, 1.0, v157
	v_rcp_f32_e32 v157, v138
	v_add_f32_e32 v138, 1.0, v159
	v_mul_f32_e32 v159, 0xbfb8aa3b, v85
	v_exp_f32_e32 v161, v159
	v_mul_f32_e32 v159, 0xbfb8aa3b, v73
	v_exp_f32_e32 v163, v159
	v_rcp_f32_e32 v159, v138
	v_add_f32_e32 v138, 1.0, v161
	v_rcp_f32_e32 v161, v138
	v_add_f32_e32 v138, 1.0, v163
	v_pk_fma_f32 v[158:159], v[158:159], s[28:29], 0.5 op_sel_hi:[1,0,0]
	v_rcp_f32_e32 v163, v138
	v_cvt_u32_f32_e32 v138, v158
	v_cvt_u32_f32_e32 v158, v159
	v_pk_fma_f32 v[156:157], v[156:157], s[28:29], 0.5 op_sel_hi:[1,0,0]
	v_max_u32_e32 v138, 1, v138
	v_cvt_u32_f32_e32 v183, v156
	v_max_u32_e32 v156, 1, v158
	v_cvt_u32_f32_e32 v182, v157
	v_lshlrev_b32_e32 v184, 8, v156
	v_pk_fma_f32 v[156:157], v[160:161], s[28:29], 0.5 op_sel_hi:[1,0,0]
	v_pk_fma_f32 v[158:159], v[162:163], s[28:29], 0.5 op_sel_hi:[1,0,0]
	v_cvt_u32_f32_sdwa v156, v156 dst_sel:WORD_1 dst_unused:UNUSED_PAD src0_sel:DWORD
	v_cvt_u32_f32_e32 v158, v158
	v_cvt_u32_f32_e32 v159, v159
	v_cvt_u32_f32_sdwa v157, v157 dst_sel:WORD_1 dst_unused:UNUSED_PAD src0_sel:DWORD
	v_or_b32_e32 v156, v156, v183
	v_max_u32_sdwa v158, v158, v171 dst_sel:BYTE_3 dst_unused:UNUSED_PAD src0_sel:DWORD src1_sel:DWORD
	v_max_u32_sdwa v159, v159, v171 dst_sel:BYTE_3 dst_unused:UNUSED_PAD src0_sel:DWORD src1_sel:DWORD
	v_or_b32_e32 v157, v157, v182
	v_or_b32_e32 v156, v156, v158
	v_mul_f32_e32 v158, 0xbfb8aa3b, v78
	v_or_b32_e32 v157, v157, v159
	v_exp_f32_e32 v158, v158
	v_mul_f32_e32 v159, 0xbfb8aa3b, v66
	v_exp_f32_e32 v159, v159
	v_lshlrev_b32_e32 v138, 8, v138
	v_or_b32_e32 v156, v156, v138
	v_add_f32_e32 v138, 1.0, v158
	v_rcp_f32_e32 v158, v138
	v_add_f32_e32 v138, 1.0, v159
	v_mul_f32_e32 v159, 0xbfb8aa3b, v79
	v_exp_f32_e32 v159, v159
	v_mul_f32_e32 v160, 0xbfb8aa3b, v67
	v_exp_f32_e32 v161, v160
	v_rcp_f32_e32 v160, v138
	v_add_f32_e32 v138, 1.0, v159
	v_mul_f32_e32 v159, 0xbfb8aa3b, v80
	v_rcp_f32_e32 v162, v138
	v_add_f32_e32 v138, 1.0, v161
	v_exp_f32_e32 v159, v159
	v_mul_f32_e32 v161, 0xbfb8aa3b, v68
	v_exp_f32_e32 v161, v161
	v_rcp_f32_e32 v182, v138
	v_add_f32_e32 v138, 1.0, v159
	v_rcp_f32_e32 v159, v138
	v_add_f32_e32 v138, 1.0, v161
	v_mul_f32_e32 v161, 0xbfb8aa3b, v81
	v_exp_f32_e32 v163, v161
	v_mul_f32_e32 v161, 0xbfb8aa3b, v69
	v_exp_f32_e32 v183, v161
	v_rcp_f32_e32 v161, v138
	v_add_f32_e32 v138, 1.0, v163
	v_rcp_f32_e32 v163, v138
	v_add_f32_e32 v138, 1.0, v183
	v_pk_fma_f32 v[160:161], v[160:161], s[28:29], 0.5 op_sel_hi:[1,0,0]
	v_rcp_f32_e32 v183, v138
	v_cvt_u32_f32_e32 v138, v160
	v_cvt_u32_f32_e32 v160, v161
	v_pk_fma_f32 v[158:159], v[158:159], s[28:29], 0.5 op_sel_hi:[1,0,0]
	v_or_b32_e32 v157, v157, v184
	v_cvt_u32_f32_e32 v185, v158
	v_max_u32_e32 v158, 1, v160
	v_cvt_u32_f32_e32 v184, v159
	v_lshlrev_b32_e32 v186, 8, v158
	v_pk_fma_f32 v[158:159], v[162:163], s[28:29], 0.5 op_sel_hi:[1,0,0]
	v_pk_fma_f32 v[160:161], v[182:183], s[28:29], 0.5 op_sel_hi:[1,0,0]
	v_cvt_u32_f32_sdwa v159, v159 dst_sel:WORD_1 dst_unused:UNUSED_PAD src0_sel:DWORD
	v_cvt_u32_f32_e32 v160, v160
	v_cvt_u32_f32_e32 v161, v161
; __device__ __forceinline__ float sigm(float x) { return __builtin_amdgcn_rcpf(1.0f + __builtin_amdgcn_exp2f(x * -1.4426950408889634f)); }
;     __device__ __forceinline__ void operator()(const f32x4 (&acc)[2][2][4][2], const Unit& u, int wr, int wc, int fr, int fq) const {
;     ...
;                 for (int m = 0; m < 4; ++m) { const size_t off = (row0 + ai * HALF + m * 16) * 1024 + col;
;                     unsigned wd[4];
; #pragma unroll
;                     for (int n = 0; n < 2; ++n)
; #pragma unroll
;                         for (int h = 0; h < 2; ++h) { unsigned d = 0u;
; #pragma unroll
;                             for (int e = 0; e < 2; ++e) { const int i = 2 * h + e; const unsigned ta = (unsigned)(sigm(acc[ai][0][m][n][i]) * 255.0f + 0.5f); unsigned tb = (unsigned)(sigm(acc[ai][1][m][n][i]) * 255.0f + 0.5f); tb = tb < 1u ? 1u : tb;
;                                 d |= (ta | (tb << 8)) << (16 * e); }
;                             wd[2 * n + h] = d; }
;                     *(u32x4*)(AB + off) = (u32x4){wd[0], wd[1], wd[2], wd[3]};
;                     asm volatile("" ::: "memory"); }
	v_cvt_u32_f32_sdwa v158, v158 dst_sel:WORD_1 dst_unused:UNUSED_PAD src0_sel:DWORD
	v_max_u32_e32 v138, 1, v138
	v_max_u32_sdwa v160, v160, v171 dst_sel:BYTE_3 dst_unused:UNUSED_PAD src0_sel:DWORD src1_sel:DWORD
	v_max_u32_sdwa v161, v161, v171 dst_sel:BYTE_3 dst_unused:UNUSED_PAD src0_sel:DWORD src1_sel:DWORD
	v_or_b32_e32 v159, v159, v184
	v_or_b32_e32 v158, v158, v185
	v_lshlrev_b32_e32 v138, 8, v138
	v_or_b32_e32 v159, v159, v161
	v_or_b32_e32 v158, v158, v160
	v_add_co_u32_e32 v160, vcc, s59, v154
	v_or_b32_e32 v159, v159, v186
	v_or_b32_e32 v158, v158, v138
	v_addc_co_u32_e32 v161, vcc, 0, v155, vcc
	v_mul_f32_e32 v138, 0xbfb8aa3b, v62
	global_store_dwordx4 v[160:161], v[156:159], off
	v_exp_f32_e32 v138, v138
	s_nop 0
	v_mul_f32_e32 v156, 0xbfb8aa3b, v54
	v_exp_f32_e32 v157, v156
	v_add_f32_e32 v138, 1.0, v138
	v_rcp_f32_e32 v156, v138
	v_mul_f32_e32 v158, 0xbfb8aa3b, v55
	v_add_f32_e32 v138, 1.0, v157
	v_mul_f32_e32 v157, 0xbfb8aa3b, v63
	v_exp_f32_e32 v157, v157
	v_exp_f32_e32 v159, v158
	v_rcp_f32_e32 v158, v138
	v_add_f32_e32 v138, 1.0, v157
	v_mul_f32_e32 v157, 0xbfb8aa3b, v64
	v_rcp_f32_e32 v160, v138
	v_add_f32_e32 v138, 1.0, v159
	v_exp_f32_e32 v157, v157
	v_mul_f32_e32 v159, 0xbfb8aa3b, v56
	v_exp_f32_e32 v159, v159
	v_rcp_f32_e32 v162, v138
	v_add_f32_e32 v138, 1.0, v157
	v_rcp_f32_e32 v157, v138
	v_add_f32_e32 v138, 1.0, v159
	v_mul_f32_e32 v159, 0xbfb8aa3b, v65
	v_exp_f32_e32 v161, v159
	v_mul_f32_e32 v159, 0xbfb8aa3b, v57
	v_exp_f32_e32 v163, v159
	v_rcp_f32_e32 v159, v138
	v_add_f32_e32 v138, 1.0, v161
	v_rcp_f32_e32 v161, v138
	v_add_f32_e32 v138, 1.0, v163
	v_pk_fma_f32 v[158:159], v[158:159], s[28:29], 0.5 op_sel_hi:[1,0,0]
	v_rcp_f32_e32 v163, v138
	v_cvt_u32_f32_e32 v138, v158
	v_cvt_u32_f32_e32 v158, v159
	v_pk_fma_f32 v[156:157], v[156:157], s[28:29], 0.5 op_sel_hi:[1,0,0]
	v_max_u32_e32 v138, 1, v138
	v_cvt_u32_f32_e32 v183, v156
	v_max_u32_e32 v156, 1, v158
	v_cvt_u32_f32_e32 v182, v157
	v_lshlrev_b32_e32 v184, 8, v156
	v_pk_fma_f32 v[156:157], v[160:161], s[28:29], 0.5 op_sel_hi:[1,0,0]
	v_pk_fma_f32 v[158:159], v[162:163], s[28:29], 0.5 op_sel_hi:[1,0,0]
	v_cvt_u32_f32_sdwa v156, v156 dst_sel:WORD_1 dst_unused:UNUSED_PAD src0_sel:DWORD
	v_cvt_u32_f32_e32 v158, v158
	v_cvt_u32_f32_e32 v159, v159
	v_cvt_u32_f32_sdwa v157, v157 dst_sel:WORD_1 dst_unused:UNUSED_PAD src0_sel:DWORD
	v_or_b32_e32 v156, v156, v183
	v_max_u32_sdwa v158, v158, v171 dst_sel:BYTE_3 dst_unused:UNUSED_PAD src0_sel:DWORD src1_sel:DWORD
	v_max_u32_sdwa v159, v159, v171 dst_sel:BYTE_3 dst_unused:UNUSED_PAD src0_sel:DWORD src1_sel:DWORD
	v_or_b32_e32 v157, v157, v182
	v_or_b32_e32 v156, v156, v158
	v_mul_f32_e32 v158, 0xbfb8aa3b, v58
	v_or_b32_e32 v157, v157, v159
	v_exp_f32_e32 v158, v158
	v_mul_f32_e32 v159, 0xbfb8aa3b, v42
	v_exp_f32_e32 v159, v159
	v_lshlrev_b32_e32 v138, 8, v138
	v_or_b32_e32 v156, v156, v138
	v_add_f32_e32 v138, 1.0, v158
	v_rcp_f32_e32 v158, v138
	v_add_f32_e32 v138, 1.0, v159
	v_mul_f32_e32 v159, 0xbfb8aa3b, v59
	v_exp_f32_e32 v159, v159
	v_mul_f32_e32 v160, 0xbfb8aa3b, v43
	v_exp_f32_e32 v161, v160
	v_rcp_f32_e32 v160, v138
	v_add_f32_e32 v138, 1.0, v159
	v_mul_f32_e32 v159, 0xbfb8aa3b, v60
	v_rcp_f32_e32 v162, v138
	v_add_f32_e32 v138, 1.0, v161
	v_exp_f32_e32 v159, v159
	v_mul_f32_e32 v161, 0xbfb8aa3b, v44
	v_exp_f32_e32 v161, v161
	v_rcp_f32_e32 v182, v138
	v_add_f32_e32 v138, 1.0, v159
	v_rcp_f32_e32 v159, v138
	v_add_f32_e32 v138, 1.0, v161
	v_mul_f32_e32 v161, 0xbfb8aa3b, v61
	v_exp_f32_e32 v163, v161
	v_mul_f32_e32 v161, 0xbfb8aa3b, v45
	v_exp_f32_e32 v183, v161
	v_rcp_f32_e32 v161, v138
	v_add_f32_e32 v138, 1.0, v163
	v_rcp_f32_e32 v163, v138
	v_add_f32_e32 v138, 1.0, v183
	v_pk_fma_f32 v[160:161], v[160:161], s[28:29], 0.5 op_sel_hi:[1,0,0]
	v_rcp_f32_e32 v183, v138
	v_cvt_u32_f32_e32 v138, v160
	v_cvt_u32_f32_e32 v160, v161
	v_pk_fma_f32 v[158:159], v[158:159], s[28:29], 0.5 op_sel_hi:[1,0,0]
	v_or_b32_e32 v157, v157, v184
	v_cvt_u32_f32_e32 v185, v158
	v_max_u32_e32 v158, 1, v160
	v_cvt_u32_f32_e32 v184, v159
	v_lshlrev_b32_e32 v186, 8, v158
	v_pk_fma_f32 v[158:159], v[162:163], s[28:29], 0.5 op_sel_hi:[1,0,0]
	v_pk_fma_f32 v[160:161], v[182:183], s[28:29], 0.5 op_sel_hi:[1,0,0]
	v_cvt_u32_f32_sdwa v159, v159 dst_sel:WORD_1 dst_unused:UNUSED_PAD src0_sel:DWORD
	v_cvt_u32_f32_e32 v160, v160
	v_cvt_u32_f32_e32 v161, v161
	v_cvt_u32_f32_sdwa v158, v158 dst_sel:WORD_1 dst_unused:UNUSED_PAD src0_sel:DWORD
	v_max_u32_e32 v138, 1, v138
	v_max_u32_sdwa v160, v160, v171 dst_sel:BYTE_3 dst_unused:UNUSED_PAD src0_sel:DWORD src1_sel:DWORD
	v_max_u32_sdwa v161, v161, v171 dst_sel:BYTE_3 dst_unused:UNUSED_PAD src0_sel:DWORD src1_sel:DWORD
	v_or_b32_e32 v159, v159, v184
	v_or_b32_e32 v158, v158, v185
	v_lshlrev_b32_e32 v138, 8, v138
	v_or_b32_e32 v159, v159, v161
	v_or_b32_e32 v158, v158, v160
	v_add_co_u32_e32 v160, vcc, s73, v154
	v_or_b32_e32 v159, v159, v186
	v_or_b32_e32 v158, v158, v138
	v_addc_co_u32_e32 v161, vcc, 0, v155, vcc
	v_mul_f32_e32 v138, 0xbfb8aa3b, v50
	global_store_dwordx4 v[160:161], v[156:159], off
	v_exp_f32_e32 v138, v138
	s_nop 0
	v_mul_f32_e32 v156, 0xbfb8aa3b, v38
	v_exp_f32_e32 v157, v156
	v_add_f32_e32 v138, 1.0, v138
	v_rcp_f32_e32 v156, v138
	v_mul_f32_e32 v158, 0xbfb8aa3b, v39
	v_add_f32_e32 v138, 1.0, v157
	v_mul_f32_e32 v157, 0xbfb8aa3b, v51
	v_exp_f32_e32 v157, v157
	v_exp_f32_e32 v159, v158
	v_rcp_f32_e32 v158, v138
	v_add_f32_e32 v138, 1.0, v157
	v_mul_f32_e32 v157, 0xbfb8aa3b, v52
	v_rcp_f32_e32 v160, v138
	v_add_f32_e32 v138, 1.0, v159
	v_exp_f32_e32 v157, v157
	v_mul_f32_e32 v159, 0xbfb8aa3b, v40
	v_exp_f32_e32 v159, v159
	v_rcp_f32_e32 v162, v138
	v_add_f32_e32 v138, 1.0, v157
; __device__ __forceinline__ float sigm(float x) { return __builtin_amdgcn_rcpf(1.0f + __builtin_amdgcn_exp2f(x * -1.4426950408889634f)); }
;     __device__ __forceinline__ void operator()(const f32x4 (&acc)[2][2][4][2], const Unit& u, int wr, int wc, int fr, int fq) const {
;     ...
;                 for (int m = 0; m < 4; ++m) { const size_t off = (row0 + ai * HALF + m * 16) * 1024 + col;
;                     unsigned wd[4];
; #pragma unroll
;                     for (int n = 0; n < 2; ++n)
; #pragma unroll
;                         for (int h = 0; h < 2; ++h) { unsigned d = 0u;
; #pragma unroll
;                             for (int e = 0; e < 2; ++e) { const int i = 2 * h + e; const unsigned ta = (unsigned)(sigm(acc[ai][0][m][n][i]) * 255.0f + 0.5f); unsigned tb = (unsigned)(sigm(acc[ai][1][m][n][i]) * 255.0f + 0.5f); tb = tb < 1u ? 1u : tb;
;                                 d |= (ta | (tb << 8)) << (16 * e); }
;                             wd[2 * n + h] = d; }
;                     *(u32x4*)(AB + off) = (u32x4){wd[0], wd[1], wd[2], wd[3]};
;                     asm volatile("" ::: "memory"); }
	v_rcp_f32_e32 v157, v138
	v_add_f32_e32 v138, 1.0, v159
	v_mul_f32_e32 v159, 0xbfb8aa3b, v53
	v_exp_f32_e32 v161, v159
	v_mul_f32_e32 v159, 0xbfb8aa3b, v41
	v_exp_f32_e32 v163, v159
	v_rcp_f32_e32 v159, v138
	v_add_f32_e32 v138, 1.0, v161
	v_rcp_f32_e32 v161, v138
	v_add_f32_e32 v138, 1.0, v163
	v_pk_fma_f32 v[158:159], v[158:159], s[28:29], 0.5 op_sel_hi:[1,0,0]
	v_rcp_f32_e32 v163, v138
	v_cvt_u32_f32_e32 v138, v158
	v_cvt_u32_f32_e32 v158, v159
	v_pk_fma_f32 v[156:157], v[156:157], s[28:29], 0.5 op_sel_hi:[1,0,0]
	v_max_u32_e32 v138, 1, v138
	v_cvt_u32_f32_e32 v183, v156
	v_max_u32_e32 v156, 1, v158
	v_cvt_u32_f32_e32 v182, v157
	v_lshlrev_b32_e32 v184, 8, v156
	v_pk_fma_f32 v[156:157], v[160:161], s[28:29], 0.5 op_sel_hi:[1,0,0]
	v_pk_fma_f32 v[158:159], v[162:163], s[28:29], 0.5 op_sel_hi:[1,0,0]
	v_cvt_u32_f32_sdwa v156, v156 dst_sel:WORD_1 dst_unused:UNUSED_PAD src0_sel:DWORD
	v_cvt_u32_f32_e32 v158, v158
	v_cvt_u32_f32_e32 v159, v159
	v_cvt_u32_f32_sdwa v157, v157 dst_sel:WORD_1 dst_unused:UNUSED_PAD src0_sel:DWORD
	v_or_b32_e32 v156, v156, v183
	v_max_u32_sdwa v158, v158, v171 dst_sel:BYTE_3 dst_unused:UNUSED_PAD src0_sel:DWORD src1_sel:DWORD
	v_max_u32_sdwa v159, v159, v171 dst_sel:BYTE_3 dst_unused:UNUSED_PAD src0_sel:DWORD src1_sel:DWORD
	v_or_b32_e32 v157, v157, v182
	v_or_b32_e32 v156, v156, v158
	v_mul_f32_e32 v158, 0xbfb8aa3b, v46
	v_or_b32_e32 v157, v157, v159
	v_exp_f32_e32 v158, v158
	v_mul_f32_e32 v159, 0xbfb8aa3b, v26
	v_exp_f32_e32 v159, v159
	v_lshlrev_b32_e32 v138, 8, v138
	v_or_b32_e32 v156, v156, v138
	v_add_f32_e32 v138, 1.0, v158
	v_rcp_f32_e32 v158, v138
	v_add_f32_e32 v138, 1.0, v159
	v_mul_f32_e32 v159, 0xbfb8aa3b, v47
	v_exp_f32_e32 v159, v159
	v_mul_f32_e32 v160, 0xbfb8aa3b, v27
	v_exp_f32_e32 v161, v160
	v_rcp_f32_e32 v160, v138
	v_add_f32_e32 v138, 1.0, v159
	v_mul_f32_e32 v159, 0xbfb8aa3b, v48
	v_rcp_f32_e32 v162, v138
	v_add_f32_e32 v138, 1.0, v161
	v_exp_f32_e32 v159, v159
	v_mul_f32_e32 v161, 0xbfb8aa3b, v28
	v_exp_f32_e32 v161, v161
	v_rcp_f32_e32 v182, v138
	v_add_f32_e32 v138, 1.0, v159
	v_rcp_f32_e32 v159, v138
	v_add_f32_e32 v138, 1.0, v161
	v_mul_f32_e32 v161, 0xbfb8aa3b, v49
	v_exp_f32_e32 v163, v161
	v_mul_f32_e32 v161, 0xbfb8aa3b, v29
	v_exp_f32_e32 v183, v161
	v_rcp_f32_e32 v161, v138
	v_add_f32_e32 v138, 1.0, v163
	v_rcp_f32_e32 v163, v138
	v_add_f32_e32 v138, 1.0, v183
	v_pk_fma_f32 v[160:161], v[160:161], s[28:29], 0.5 op_sel_hi:[1,0,0]
	v_rcp_f32_e32 v183, v138
	v_cvt_u32_f32_e32 v138, v160
	v_cvt_u32_f32_e32 v160, v161
	v_pk_fma_f32 v[158:159], v[158:159], s[28:29], 0.5 op_sel_hi:[1,0,0]
	v_or_b32_e32 v157, v157, v184
	v_cvt_u32_f32_e32 v185, v158
	v_max_u32_e32 v158, 1, v160
	v_cvt_u32_f32_e32 v184, v159
	v_lshlrev_b32_e32 v186, 8, v158
	v_pk_fma_f32 v[158:159], v[162:163], s[28:29], 0.5 op_sel_hi:[1,0,0]
	v_pk_fma_f32 v[160:161], v[182:183], s[28:29], 0.5 op_sel_hi:[1,0,0]
	v_cvt_u32_f32_sdwa v159, v159 dst_sel:WORD_1 dst_unused:UNUSED_PAD src0_sel:DWORD
	v_cvt_u32_f32_e32 v160, v160
	v_cvt_u32_f32_e32 v161, v161
	v_cvt_u32_f32_sdwa v158, v158 dst_sel:WORD_1 dst_unused:UNUSED_PAD src0_sel:DWORD
	v_max_u32_e32 v138, 1, v138
	v_max_u32_sdwa v160, v160, v171 dst_sel:BYTE_3 dst_unused:UNUSED_PAD src0_sel:DWORD src1_sel:DWORD
	v_max_u32_sdwa v161, v161, v171 dst_sel:BYTE_3 dst_unused:UNUSED_PAD src0_sel:DWORD src1_sel:DWORD
	v_or_b32_e32 v159, v159, v184
	v_or_b32_e32 v158, v158, v185
	v_lshlrev_b32_e32 v138, 8, v138
	v_or_b32_e32 v159, v159, v161
	v_or_b32_e32 v158, v158, v160
	v_add_co_u32_e32 v160, vcc, s74, v154
	v_or_b32_e32 v159, v159, v186
	v_or_b32_e32 v158, v158, v138
	v_addc_co_u32_e32 v161, vcc, 0, v155, vcc
	v_mul_f32_e32 v138, 0xbfb8aa3b, v34
	global_store_dwordx4 v[160:161], v[156:159], off
	v_exp_f32_e32 v138, v138
	s_nop 0
	v_mul_f32_e32 v156, 0xbfb8aa3b, v22
	v_exp_f32_e32 v157, v156
	v_add_f32_e32 v138, 1.0, v138
	v_rcp_f32_e32 v156, v138
	v_mul_f32_e32 v158, 0xbfb8aa3b, v23
	v_add_f32_e32 v138, 1.0, v157
	v_mul_f32_e32 v157, 0xbfb8aa3b, v35
	v_exp_f32_e32 v157, v157
	v_exp_f32_e32 v159, v158
	v_rcp_f32_e32 v158, v138
	v_add_f32_e32 v138, 1.0, v157
	v_mul_f32_e32 v157, 0xbfb8aa3b, v36
	v_rcp_f32_e32 v160, v138
	v_add_f32_e32 v138, 1.0, v159
	v_exp_f32_e32 v157, v157
	v_mul_f32_e32 v159, 0xbfb8aa3b, v24
	v_exp_f32_e32 v159, v159
	v_rcp_f32_e32 v162, v138
	v_add_f32_e32 v138, 1.0, v157
	v_rcp_f32_e32 v157, v138
	v_add_f32_e32 v138, 1.0, v159
	v_mul_f32_e32 v159, 0xbfb8aa3b, v37
	v_exp_f32_e32 v161, v159
	v_mul_f32_e32 v159, 0xbfb8aa3b, v25
	v_exp_f32_e32 v163, v159
	v_rcp_f32_e32 v159, v138
	v_add_f32_e32 v138, 1.0, v161
	v_rcp_f32_e32 v161, v138
	v_add_f32_e32 v138, 1.0, v163
	v_pk_fma_f32 v[158:159], v[158:159], s[28:29], 0.5 op_sel_hi:[1,0,0]
	v_rcp_f32_e32 v163, v138
	v_cvt_u32_f32_e32 v138, v158
	v_cvt_u32_f32_e32 v158, v159
	v_pk_fma_f32 v[156:157], v[156:157], s[28:29], 0.5 op_sel_hi:[1,0,0]
	v_max_u32_e32 v138, 1, v138
	v_cvt_u32_f32_e32 v183, v156
	v_max_u32_e32 v156, 1, v158
	v_cvt_u32_f32_e32 v182, v157
	v_lshlrev_b32_e32 v184, 8, v156
	v_pk_fma_f32 v[156:157], v[160:161], s[28:29], 0.5 op_sel_hi:[1,0,0]
	v_pk_fma_f32 v[158:159], v[162:163], s[28:29], 0.5 op_sel_hi:[1,0,0]
	v_cvt_u32_f32_sdwa v156, v156 dst_sel:WORD_1 dst_unused:UNUSED_PAD src0_sel:DWORD
	v_cvt_u32_f32_e32 v158, v158
	v_cvt_u32_f32_e32 v159, v159
	v_cvt_u32_f32_sdwa v157, v157 dst_sel:WORD_1 dst_unused:UNUSED_PAD src0_sel:DWORD
	v_or_b32_e32 v156, v156, v183
	v_max_u32_sdwa v158, v158, v171 dst_sel:BYTE_3 dst_unused:UNUSED_PAD src0_sel:DWORD src1_sel:DWORD
	v_max_u32_sdwa v159, v159, v171 dst_sel:BYTE_3 dst_unused:UNUSED_PAD src0_sel:DWORD src1_sel:DWORD
	v_or_b32_e32 v157, v157, v182
; __device__ __forceinline__ float sigm(float x) { return __builtin_amdgcn_rcpf(1.0f + __builtin_amdgcn_exp2f(x * -1.4426950408889634f)); }
;     __device__ __forceinline__ void operator()(const f32x4 (&acc)[2][2][4][2], const Unit& u, int wr, int wc, int fr, int fq) const {
;     ...
;                 for (int m = 0; m < 4; ++m) { const size_t off = (row0 + ai * HALF + m * 16) * 1024 + col;
;                     unsigned wd[4];
; #pragma unroll
;                     for (int n = 0; n < 2; ++n)
; #pragma unroll
;                         for (int h = 0; h < 2; ++h) { unsigned d = 0u;
; #pragma unroll
;                             for (int e = 0; e < 2; ++e) { const int i = 2 * h + e; const unsigned ta = (unsigned)(sigm(acc[ai][0][m][n][i]) * 255.0f + 0.5f); unsigned tb = (unsigned)(sigm(acc[ai][1][m][n][i]) * 255.0f + 0.5f); tb = tb < 1u ? 1u : tb;
;                                 d |= (ta | (tb << 8)) << (16 * e); }
;                             wd[2 * n + h] = d; }
;                     *(u32x4*)(AB + off) = (u32x4){wd[0], wd[1], wd[2], wd[3]};
;                     asm volatile("" ::: "memory"); }
	v_or_b32_e32 v156, v156, v158
	v_mul_f32_e32 v158, 0xbfb8aa3b, v30
	v_or_b32_e32 v157, v157, v159
	v_exp_f32_e32 v158, v158
	v_mul_f32_e32 v159, 0xbfb8aa3b, v10
	v_exp_f32_e32 v159, v159
	v_lshlrev_b32_e32 v138, 8, v138
	v_or_b32_e32 v156, v156, v138
	v_add_f32_e32 v138, 1.0, v158
	v_rcp_f32_e32 v158, v138
	v_add_f32_e32 v138, 1.0, v159
	v_mul_f32_e32 v159, 0xbfb8aa3b, v31
	v_exp_f32_e32 v159, v159
	v_mul_f32_e32 v160, 0xbfb8aa3b, v11
	v_exp_f32_e32 v161, v160
	v_rcp_f32_e32 v160, v138
	v_add_f32_e32 v138, 1.0, v159
	v_mul_f32_e32 v159, 0xbfb8aa3b, v32
	v_rcp_f32_e32 v162, v138
	v_add_f32_e32 v138, 1.0, v161
	v_exp_f32_e32 v159, v159
	v_mul_f32_e32 v161, 0xbfb8aa3b, v12
	v_exp_f32_e32 v161, v161
	v_rcp_f32_e32 v182, v138
	v_add_f32_e32 v138, 1.0, v159
	v_rcp_f32_e32 v159, v138
	v_add_f32_e32 v138, 1.0, v161
	v_mul_f32_e32 v161, 0xbfb8aa3b, v33
	v_exp_f32_e32 v163, v161
	v_mul_f32_e32 v161, 0xbfb8aa3b, v13
	v_exp_f32_e32 v183, v161
	v_rcp_f32_e32 v161, v138
	v_add_f32_e32 v138, 1.0, v163
	v_rcp_f32_e32 v163, v138
	v_add_f32_e32 v138, 1.0, v183
	v_pk_fma_f32 v[160:161], v[160:161], s[28:29], 0.5 op_sel_hi:[1,0,0]
	v_rcp_f32_e32 v183, v138
	v_cvt_u32_f32_e32 v138, v160
	v_cvt_u32_f32_e32 v160, v161
	v_pk_fma_f32 v[158:159], v[158:159], s[28:29], 0.5 op_sel_hi:[1,0,0]
	v_or_b32_e32 v157, v157, v184
	v_cvt_u32_f32_e32 v185, v158
	v_max_u32_e32 v158, 1, v160
	v_cvt_u32_f32_e32 v184, v159
	v_lshlrev_b32_e32 v186, 8, v158
	v_pk_fma_f32 v[158:159], v[162:163], s[28:29], 0.5 op_sel_hi:[1,0,0]
	v_pk_fma_f32 v[160:161], v[182:183], s[28:29], 0.5 op_sel_hi:[1,0,0]
	v_cvt_u32_f32_sdwa v159, v159 dst_sel:WORD_1 dst_unused:UNUSED_PAD src0_sel:DWORD
	v_cvt_u32_f32_e32 v160, v160
	v_cvt_u32_f32_e32 v161, v161
	v_cvt_u32_f32_sdwa v158, v158 dst_sel:WORD_1 dst_unused:UNUSED_PAD src0_sel:DWORD
	v_max_u32_e32 v138, 1, v138
	v_max_u32_sdwa v160, v160, v171 dst_sel:BYTE_3 dst_unused:UNUSED_PAD src0_sel:DWORD src1_sel:DWORD
	v_max_u32_sdwa v161, v161, v171 dst_sel:BYTE_3 dst_unused:UNUSED_PAD src0_sel:DWORD src1_sel:DWORD
	v_or_b32_e32 v159, v159, v184
	v_or_b32_e32 v158, v158, v185
	v_lshlrev_b32_e32 v138, 8, v138
	v_or_b32_e32 v159, v159, v161
	v_or_b32_e32 v158, v158, v160
	v_add_co_u32_e32 v160, vcc, s75, v154
	v_or_b32_e32 v159, v159, v186
	v_or_b32_e32 v158, v158, v138
	v_addc_co_u32_e32 v161, vcc, 0, v155, vcc
	v_mul_f32_e32 v138, 0xbfb8aa3b, v18
	global_store_dwordx4 v[160:161], v[156:159], off
	v_exp_f32_e32 v138, v138
	v_add_co_u32_e32 v154, vcc, 0x58000, v154
	v_mul_f32_e32 v156, 0xbfb8aa3b, v6
	v_exp_f32_e32 v157, v156
	v_add_f32_e32 v138, 1.0, v138
	v_rcp_f32_e32 v156, v138
	v_mul_f32_e32 v158, 0xbfb8aa3b, v7
	v_add_f32_e32 v138, 1.0, v157
	v_mul_f32_e32 v157, 0xbfb8aa3b, v19
	v_exp_f32_e32 v157, v157
	v_exp_f32_e32 v159, v158
	v_rcp_f32_e32 v158, v138
	v_addc_co_u32_e32 v155, vcc, 0, v155, vcc
	v_add_f32_e32 v138, 1.0, v157
	v_mul_f32_e32 v157, 0xbfb8aa3b, v20
	v_rcp_f32_e32 v160, v138
	v_add_f32_e32 v138, 1.0, v159
	v_exp_f32_e32 v157, v157
	v_mul_f32_e32 v159, 0xbfb8aa3b, v8
	v_exp_f32_e32 v159, v159
	v_rcp_f32_e32 v162, v138
	v_add_f32_e32 v138, 1.0, v157
	v_rcp_f32_e32 v157, v138
	v_add_f32_e32 v138, 1.0, v159
	v_mul_f32_e32 v159, 0xbfb8aa3b, v21
	v_exp_f32_e32 v161, v159
	v_mul_f32_e32 v159, 0xbfb8aa3b, v9
	v_exp_f32_e32 v163, v159
	v_rcp_f32_e32 v159, v138
	v_add_f32_e32 v138, 1.0, v161
	v_rcp_f32_e32 v161, v138
	v_add_f32_e32 v138, 1.0, v163
	v_pk_fma_f32 v[158:159], v[158:159], s[28:29], 0.5 op_sel_hi:[1,0,0]
	v_rcp_f32_e32 v163, v138
	v_cvt_u32_f32_e32 v138, v158
	v_cvt_u32_f32_e32 v158, v159
	v_pk_fma_f32 v[156:157], v[156:157], s[28:29], 0.5 op_sel_hi:[1,0,0]
	v_max_u32_e32 v138, 1, v138
	v_cvt_u32_f32_e32 v183, v156
	v_max_u32_e32 v156, 1, v158
	v_cvt_u32_f32_e32 v182, v157
	v_lshlrev_b32_e32 v184, 8, v156
	v_pk_fma_f32 v[156:157], v[160:161], s[28:29], 0.5 op_sel_hi:[1,0,0]
	v_pk_fma_f32 v[158:159], v[162:163], s[28:29], 0.5 op_sel_hi:[1,0,0]
	v_cvt_u32_f32_sdwa v156, v156 dst_sel:WORD_1 dst_unused:UNUSED_PAD src0_sel:DWORD
	v_cvt_u32_f32_e32 v158, v158
	v_cvt_u32_f32_e32 v159, v159
	v_cvt_u32_f32_sdwa v157, v157 dst_sel:WORD_1 dst_unused:UNUSED_PAD src0_sel:DWORD
	v_or_b32_e32 v156, v156, v183
	v_max_u32_sdwa v158, v158, v171 dst_sel:BYTE_3 dst_unused:UNUSED_PAD src0_sel:DWORD src1_sel:DWORD
	v_max_u32_sdwa v159, v159, v171 dst_sel:BYTE_3 dst_unused:UNUSED_PAD src0_sel:DWORD src1_sel:DWORD
	v_or_b32_e32 v157, v157, v182
	v_or_b32_e32 v156, v156, v158
	v_mul_f32_e32 v158, 0xbfb8aa3b, v14
	v_or_b32_e32 v157, v157, v159
	v_exp_f32_e32 v158, v158
	v_mul_f32_e32 v159, 0xbfb8aa3b, v2
	v_exp_f32_e32 v159, v159
	v_lshlrev_b32_e32 v138, 8, v138
	v_or_b32_e32 v156, v156, v138
	v_add_f32_e32 v138, 1.0, v158
	v_rcp_f32_e32 v158, v138
	v_add_f32_e32 v138, 1.0, v159
	v_mul_f32_e32 v159, 0xbfb8aa3b, v15
	v_exp_f32_e32 v159, v159
	v_mul_f32_e32 v160, 0xbfb8aa3b, v3
	v_exp_f32_e32 v161, v160
	v_rcp_f32_e32 v160, v138
	v_add_f32_e32 v138, 1.0, v159
	v_mul_f32_e32 v159, 0xbfb8aa3b, v16
	v_rcp_f32_e32 v162, v138
	v_add_f32_e32 v138, 1.0, v161
	v_exp_f32_e32 v159, v159
	v_mul_f32_e32 v161, 0xbfb8aa3b, v4
	v_exp_f32_e32 v161, v161
	v_rcp_f32_e32 v182, v138
	v_add_f32_e32 v138, 1.0, v159
	v_rcp_f32_e32 v159, v138
	v_add_f32_e32 v138, 1.0, v161
	v_mul_f32_e32 v161, 0xbfb8aa3b, v17
	v_exp_f32_e32 v163, v161
	v_mul_f32_e32 v161, 0xbfb8aa3b, v5
	v_exp_f32_e32 v183, v161
	v_rcp_f32_e32 v161, v138
	v_add_f32_e32 v138, 1.0, v163
	v_rcp_f32_e32 v163, v138
	v_add_f32_e32 v138, 1.0, v183
	v_pk_fma_f32 v[160:161], v[160:161], s[28:29], 0.5 op_sel_hi:[1,0,0]
	v_rcp_f32_e32 v183, v138
	v_cvt_u32_f32_e32 v138, v160
	v_cvt_u32_f32_e32 v160, v161
	v_pk_fma_f32 v[158:159], v[158:159], s[28:29], 0.5 op_sel_hi:[1,0,0]
	v_or_b32_e32 v157, v157, v184
	v_cvt_u32_f32_e32 v185, v158
	v_max_u32_e32 v158, 1, v160
	v_cvt_u32_f32_e32 v184, v159
	v_lshlrev_b32_e32 v186, 8, v158
	v_pk_fma_f32 v[158:159], v[162:163], s[28:29], 0.5 op_sel_hi:[1,0,0]
	v_pk_fma_f32 v[160:161], v[182:183], s[28:29], 0.5 op_sel_hi:[1,0,0]
	v_cvt_u32_f32_sdwa v159, v159 dst_sel:WORD_1 dst_unused:UNUSED_PAD src0_sel:DWORD
	v_cvt_u32_f32_e32 v160, v160
	v_cvt_u32_f32_e32 v161, v161
	v_cvt_u32_f32_sdwa v158, v158 dst_sel:WORD_1 dst_unused:UNUSED_PAD src0_sel:DWORD
	v_max_u32_e32 v138, 1, v138
	v_max_u32_sdwa v160, v160, v171 dst_sel:BYTE_3 dst_unused:UNUSED_PAD src0_sel:DWORD src1_sel:DWORD
	v_max_u32_sdwa v161, v161, v171 dst_sel:BYTE_3 dst_unused:UNUSED_PAD src0_sel:DWORD src1_sel:DWORD
	v_or_b32_e32 v159, v159, v184
	v_or_b32_e32 v158, v158, v185
	v_lshlrev_b32_e32 v138, 8, v138
	v_or_b32_e32 v159, v159, v161
	v_or_b32_e32 v158, v158, v160
	v_or_b32_e32 v159, v159, v186
	v_or_b32_e32 v158, v158, v138
	global_store_dwordx4 v[154:155], v[156:159], off

; __device__ __forceinline__ unsigned cvt_pk_bf16(float lo, float hi) { unsigned r; asm volatile("v_cvt_pk_bf16_f32 %0, %1, %2" : "=v"(r) : "v"(lo), "v"(hi)); return r; }
; __device__ __forceinline__ float silu(float x) { return x * sigm(x); }
;     __device__ __forceinline__ void operator()(const f32x4 (&acc)[2][2][4][2], const Unit& u, int wr, int wc, int fr, int fq) const {
;     ...
;         } else if (pn >= 8 && pn < 16) {
;             const int col = 64 * (pn - 8) + 16 * wc + 8 * (fq >> 1); bf16_t* dstb = (bf16_t*)(ws + ((fq & 1) ? OFF_GZ : OFF_CU));
; #pragma unroll
;             for (int ai = 0; ai < 2; ++ai)
; #pragma unroll
;                 for (int m = 0; m < 4; ++m) { const size_t off = (row0 + ai * HALF + m * 16) * 512 + col;
;                     const f32x4 gb = acc[ai][0][m][0], gc = acc[ai][0][m][1], uu = acc[ai][1][m][0], zb = acc[ai][1][m][1];
;                     const f32x4 cu = gc * uu; f32x4 gz; gz[0] = gb[0] * silu(zb[0]); gz[1] = gb[1] * silu(zb[1]); gz[2] = gb[2] * silu(zb[2]); gz[3] = gb[3] * silu(zb[3]);
;                     u32x2 a, b; a.x = cvt_pk_bf16(cu[0], cu[1]); a.y = cvt_pk_bf16(cu[2], cu[3]); b.x = cvt_pk_bf16(gz[0], gz[1]); b.y = cvt_pk_bf16(gz[2], gz[3]);
;                     const auto rx = __builtin_amdgcn_permlane16_swap(a.x, b.x, false, false), ry = __builtin_amdgcn_permlane16_swap(a.y, b.y, false, false);
;                     u32x4 w; w.x = rx[0]; w.y = ry[0]; w.z = rx[1]; w.w = ry[1];
;                     *(u32x4*)(dstb + off) = w; }
.LBB0_278:
	s_andn2_b64 vcc, exec, s[6:7]
	s_cbranch_vccnz .LBB0_280
	s_mov_b32 s89, 1
	v_mul_f32_e32 v138, 0xbfb8aa3b, v106
	v_exp_f32_e32 v158, v138
	v_mul_f32_e32 v159, 0xbfb8aa3b, v107
	v_exp_f32_e32 v159, v159
	v_lshl_add_u32 v138, s40, 6, v174
	v_add_f32_e32 v158, 1.0, v158
	v_rcp_f32_e32 v158, v158
	v_lshl_add_u64 v[160:161], v[138:139], 1, v[142:143]
	v_mul_f32_e32 v162, 0xbfb8aa3b, v109
	v_exp_f32_e32 v162, v162
	v_mul_f32_e32 v138, v106, v158
	v_add_f32_e32 v158, 1.0, v159
	v_mul_f32_e32 v159, 0xbfb8aa3b, v108
	v_exp_f32_e32 v159, v159
	v_rcp_f32_e32 v158, v158
	v_add_f32_e32 v162, 1.0, v162
	v_rcp_f32_e32 v162, v162
	v_add_f32_e32 v159, 1.0, v159
	v_rcp_f32_e32 v159, v159
	v_mul_f32_e32 v158, v107, v158
	v_pk_mul_f32 v[154:155], v[124:125], v[120:121]
	v_pk_mul_f32 v[156:157], v[122:123], v[118:119]
	v_mul_f32_e32 v159, v108, v159
	v_mul_f32_e32 v158, v127, v158
	v_mul_f32_e32 v159, v128, v159
	v_mul_f32_e32 v162, v109, v162
	v_mul_f32_e32 v138, v126, v138
	v_mul_f32_e32 v162, v129, v162
	v_cvt_pk_bf16_f32 v156, v156, v157
	v_cvt_pk_bf16_f32 v157, v154, v155
	v_cvt_pk_bf16_f32 v158, v138, v158
	v_cvt_pk_bf16_f32 v159, v159, v162
	v_lshlrev_b64 v[154:155], 10, v[152:153]
	v_permlane16_swap_b32_e32 v156, v158
	v_permlane16_swap_b32_e32 v157, v159
	v_lshl_add_u64 v[154:155], v[160:161], 0, v[154:155]
	global_store_dwordx4 v[154:155], v[156:159], off
	v_mul_f32_e32 v138, 0xbfb8aa3b, v90
	v_mul_f32_e32 v161, 0xbfb8aa3b, v92
	v_mul_f32_e32 v156, 0xbfb8aa3b, v91
	v_exp_f32_e32 v160, v156
	v_mul_f32_e32 v162, 0xbfb8aa3b, v93
	v_exp_f32_e32 v138, v138
	v_exp_f32_e32 v161, v161
	v_exp_f32_e32 v162, v162
	v_add_f32_e32 v160, 1.0, v160
	v_add_f32_e32 v138, 1.0, v138
	v_rcp_f32_e32 v160, v160
	v_add_f32_e32 v161, 1.0, v161
	v_add_f32_e32 v162, 1.0, v162
	v_rcp_f32_e32 v138, v138
	v_rcp_f32_e32 v161, v161
	v_rcp_f32_e32 v162, v162
	v_mul_f32_e32 v160, v91, v160
	v_pk_mul_f32 v[158:159], v[112:113], v[104:105]
	v_pk_mul_f32 v[156:157], v[110:111], v[102:103]
	v_mul_f32_e32 v138, v90, v138
	v_mul_f32_e32 v160, v115, v160
	v_mul_f32_e32 v161, v92, v161
	v_mul_f32_e32 v162, v93, v162
	v_mul_f32_e32 v138, v114, v138
	v_mul_f32_e32 v161, v116, v161
	v_mul_f32_e32 v162, v117, v162
	v_cvt_pk_bf16_f32 v156, v156, v157
	v_cvt_pk_bf16_f32 v157, v158, v159
	v_cvt_pk_bf16_f32 v158, v138, v160
	v_cvt_pk_bf16_f32 v159, v161, v162
	v_add_co_u32_e32 v160, vcc, s56, v154
	v_permlane16_swap_b32_e32 v156, v158
	v_permlane16_swap_b32_e32 v157, v159
	v_addc_co_u32_e32 v161, vcc, 0, v155, vcc
	global_store_dwordx4 v[160:161], v[156:159], off
	v_mul_f32_e32 v138, 0xbfb8aa3b, v74
	v_mul_f32_e32 v161, 0xbfb8aa3b, v76
	v_mul_f32_e32 v156, 0xbfb8aa3b, v75
	v_exp_f32_e32 v160, v156
	v_mul_f32_e32 v162, 0xbfb8aa3b, v77
	v_exp_f32_e32 v138, v138
	v_exp_f32_e32 v161, v161
	v_exp_f32_e32 v162, v162
	v_add_f32_e32 v160, 1.0, v160
	v_add_f32_e32 v138, 1.0, v138
	v_rcp_f32_e32 v160, v160
	v_add_f32_e32 v161, 1.0, v161
	v_add_f32_e32 v162, 1.0, v162
	v_rcp_f32_e32 v138, v138
	v_rcp_f32_e32 v161, v161
	v_rcp_f32_e32 v162, v162
	v_mul_f32_e32 v160, v75, v160
	v_pk_mul_f32 v[158:159], v[96:97], v[88:89]
	v_pk_mul_f32 v[156:157], v[94:95], v[86:87]
	v_mul_f32_e32 v138, v74, v138
	v_mul_f32_e32 v160, v99, v160
	v_mul_f32_e32 v161, v76, v161
	v_mul_f32_e32 v162, v77, v162
	v_mul_f32_e32 v138, v98, v138
	v_mul_f32_e32 v161, v100, v161
	v_mul_f32_e32 v162, v101, v162
	v_cvt_pk_bf16_f32 v156, v156, v157
	v_cvt_pk_bf16_f32 v157, v158, v159
	v_cvt_pk_bf16_f32 v158, v138, v160
	v_cvt_pk_bf16_f32 v159, v161, v162
	v_add_co_u32_e32 v160, vcc, s60, v154
	v_permlane16_swap_b32_e32 v156, v158
	v_permlane16_swap_b32_e32 v157, v159
	v_addc_co_u32_e32 v161, vcc, 0, v155, vcc
	global_store_dwordx4 v[160:161], v[156:159], off
	v_mul_f32_e32 v138, 0xbfb8aa3b, v66
	v_mul_f32_e32 v161, 0xbfb8aa3b, v68
	v_mul_f32_e32 v156, 0xbfb8aa3b, v67
	v_exp_f32_e32 v160, v156
	v_mul_f32_e32 v162, 0xbfb8aa3b, v69
	v_exp_f32_e32 v138, v138
	v_exp_f32_e32 v161, v161
	v_exp_f32_e32 v162, v162
	v_add_f32_e32 v160, 1.0, v160
	v_add_f32_e32 v138, 1.0, v138
	v_rcp_f32_e32 v160, v160
	v_add_f32_e32 v161, 1.0, v161
	v_add_f32_e32 v162, 1.0, v162
	v_rcp_f32_e32 v138, v138
	v_rcp_f32_e32 v161, v161
	v_rcp_f32_e32 v162, v162
	v_mul_f32_e32 v160, v67, v160
	v_pk_mul_f32 v[158:159], v[80:81], v[72:73]
	v_pk_mul_f32 v[156:157], v[78:79], v[70:71]
	v_mul_f32_e32 v138, v66, v138
	v_mul_f32_e32 v160, v83, v160
	v_mul_f32_e32 v161, v68, v161
	v_mul_f32_e32 v162, v69, v162
	v_mul_f32_e32 v138, v82, v138
	v_mul_f32_e32 v161, v84, v161
	v_mul_f32_e32 v162, v85, v162
	v_cvt_pk_bf16_f32 v156, v156, v157
	v_cvt_pk_bf16_f32 v157, v158, v159
	v_cvt_pk_bf16_f32 v158, v138, v160
	v_cvt_pk_bf16_f32 v159, v161, v162
	v_add_co_u32_e32 v160, vcc, s66, v154
	v_permlane16_swap_b32_e32 v156, v158
; __device__ __forceinline__ unsigned cvt_pk_bf16(float lo, float hi) { unsigned r; asm volatile("v_cvt_pk_bf16_f32 %0, %1, %2" : "=v"(r) : "v"(lo), "v"(hi)); return r; }
; __device__ __forceinline__ float silu(float x) { return x * sigm(x); }
;     __device__ __forceinline__ void operator()(const f32x4 (&acc)[2][2][4][2], const Unit& u, int wr, int wc, int fr, int fq) const {
;     ...
;                 for (int m = 0; m < 4; ++m) { const size_t off = (row0 + ai * HALF + m * 16) * 512 + col;
;                     const f32x4 gb = acc[ai][0][m][0], gc = acc[ai][0][m][1], uu = acc[ai][1][m][0], zb = acc[ai][1][m][1];
;                     const f32x4 cu = gc * uu; f32x4 gz; gz[0] = gb[0] * silu(zb[0]); gz[1] = gb[1] * silu(zb[1]); gz[2] = gb[2] * silu(zb[2]); gz[3] = gb[3] * silu(zb[3]);
;                     u32x2 a, b; a.x = cvt_pk_bf16(cu[0], cu[1]); a.y = cvt_pk_bf16(cu[2], cu[3]); b.x = cvt_pk_bf16(gz[0], gz[1]); b.y = cvt_pk_bf16(gz[2], gz[3]);
;                     const auto rx = __builtin_amdgcn_permlane16_swap(a.x, b.x, false, false), ry = __builtin_amdgcn_permlane16_swap(a.y, b.y, false, false);
;                     u32x4 w; w.x = rx[0]; w.y = ry[0]; w.z = rx[1]; w.w = ry[1];
;                     *(u32x4*)(dstb + off) = w; }
	v_permlane16_swap_b32_e32 v157, v159
	v_addc_co_u32_e32 v161, vcc, 0, v155, vcc
	global_store_dwordx4 v[160:161], v[156:159], off
	v_mul_f32_e32 v138, 0xbfb8aa3b, v42
	v_mul_f32_e32 v161, 0xbfb8aa3b, v44
	v_mul_f32_e32 v156, 0xbfb8aa3b, v43
	v_exp_f32_e32 v160, v156
	v_mul_f32_e32 v162, 0xbfb8aa3b, v45
	v_exp_f32_e32 v138, v138
	v_exp_f32_e32 v161, v161
	v_exp_f32_e32 v162, v162
	v_add_f32_e32 v160, 1.0, v160
	v_add_f32_e32 v138, 1.0, v138
	v_rcp_f32_e32 v160, v160
	v_add_f32_e32 v161, 1.0, v161
	v_add_f32_e32 v162, 1.0, v162
	v_rcp_f32_e32 v138, v138
	v_rcp_f32_e32 v161, v161
	v_rcp_f32_e32 v162, v162
	v_mul_f32_e32 v160, v43, v160
	v_pk_mul_f32 v[158:159], v[60:61], v[56:57]
	v_pk_mul_f32 v[156:157], v[58:59], v[54:55]
	v_mul_f32_e32 v138, v42, v138
	v_mul_f32_e32 v160, v63, v160
	v_mul_f32_e32 v161, v44, v161
	v_mul_f32_e32 v162, v45, v162
	v_mul_f32_e32 v138, v62, v138
	v_mul_f32_e32 v161, v64, v161
	v_mul_f32_e32 v162, v65, v162
	v_cvt_pk_bf16_f32 v156, v156, v157
	v_cvt_pk_bf16_f32 v157, v158, v159
	v_cvt_pk_bf16_f32 v158, v138, v160
	v_cvt_pk_bf16_f32 v159, v161, v162
	v_add_co_u32_e32 v160, vcc, s69, v154
	v_permlane16_swap_b32_e32 v156, v158
	v_permlane16_swap_b32_e32 v157, v159
	v_addc_co_u32_e32 v161, vcc, 0, v155, vcc
	global_store_dwordx4 v[160:161], v[156:159], off
	v_mul_f32_e32 v138, 0xbfb8aa3b, v26
	v_mul_f32_e32 v161, 0xbfb8aa3b, v28
	v_mul_f32_e32 v156, 0xbfb8aa3b, v27
	v_exp_f32_e32 v160, v156
	v_mul_f32_e32 v162, 0xbfb8aa3b, v29
	v_exp_f32_e32 v138, v138
	v_exp_f32_e32 v161, v161
	v_exp_f32_e32 v162, v162
	v_add_f32_e32 v160, 1.0, v160
	v_add_f32_e32 v138, 1.0, v138
	v_rcp_f32_e32 v160, v160
	v_add_f32_e32 v161, 1.0, v161
	v_add_f32_e32 v162, 1.0, v162
	v_rcp_f32_e32 v138, v138
	v_rcp_f32_e32 v161, v161
	v_rcp_f32_e32 v162, v162
	v_mul_f32_e32 v160, v27, v160
	v_pk_mul_f32 v[158:159], v[48:49], v[40:41]
	v_pk_mul_f32 v[156:157], v[46:47], v[38:39]
	v_mul_f32_e32 v138, v26, v138
	v_mul_f32_e32 v160, v51, v160
	v_mul_f32_e32 v161, v28, v161
	v_mul_f32_e32 v162, v29, v162
	v_mul_f32_e32 v138, v50, v138
	v_mul_f32_e32 v161, v52, v161
	v_mul_f32_e32 v162, v53, v162
	v_cvt_pk_bf16_f32 v156, v156, v157
	v_cvt_pk_bf16_f32 v157, v158, v159
	v_cvt_pk_bf16_f32 v158, v138, v160
	v_cvt_pk_bf16_f32 v159, v161, v162
	v_add_co_u32_e32 v160, vcc, s70, v154
	v_permlane16_swap_b32_e32 v156, v158
	v_permlane16_swap_b32_e32 v157, v159
	v_addc_co_u32_e32 v161, vcc, 0, v155, vcc
	global_store_dwordx4 v[160:161], v[156:159], off
	v_mul_f32_e32 v138, 0xbfb8aa3b, v10
	v_mul_f32_e32 v161, 0xbfb8aa3b, v12
	v_mul_f32_e32 v156, 0xbfb8aa3b, v11
	v_exp_f32_e32 v160, v156
	v_mul_f32_e32 v162, 0xbfb8aa3b, v13
	v_exp_f32_e32 v138, v138
	v_exp_f32_e32 v161, v161
	v_exp_f32_e32 v162, v162
	v_add_f32_e32 v160, 1.0, v160
	v_add_f32_e32 v138, 1.0, v138
	v_rcp_f32_e32 v160, v160
	v_add_f32_e32 v161, 1.0, v161
	v_add_f32_e32 v162, 1.0, v162
	v_rcp_f32_e32 v138, v138
	v_rcp_f32_e32 v161, v161
	v_rcp_f32_e32 v162, v162
	v_mul_f32_e32 v160, v11, v160
	v_pk_mul_f32 v[158:159], v[32:33], v[24:25]
	v_pk_mul_f32 v[156:157], v[30:31], v[22:23]
	v_mul_f32_e32 v138, v10, v138
	v_mul_f32_e32 v160, v35, v160
	v_mul_f32_e32 v161, v12, v161
	v_mul_f32_e32 v162, v13, v162
	v_mul_f32_e32 v138, v34, v138
	v_mul_f32_e32 v161, v36, v161
	v_mul_f32_e32 v162, v37, v162
	v_cvt_pk_bf16_f32 v156, v156, v157
	v_cvt_pk_bf16_f32 v157, v158, v159
	v_cvt_pk_bf16_f32 v158, v138, v160
	v_cvt_pk_bf16_f32 v159, v161, v162
	v_add_co_u32_e32 v160, vcc, s71, v154
	v_permlane16_swap_b32_e32 v156, v158
	v_permlane16_swap_b32_e32 v157, v159
	v_addc_co_u32_e32 v161, vcc, 0, v155, vcc
	v_mul_f32_e32 v138, 0xbfb8aa3b, v2
	global_store_dwordx4 v[160:161], v[156:159], off
	v_mul_f32_e32 v161, 0xbfb8aa3b, v4
	v_mul_f32_e32 v162, 0xbfb8aa3b, v5
	v_mul_f32_e32 v156, 0xbfb8aa3b, v3
	v_exp_f32_e32 v138, v138
	v_exp_f32_e32 v160, v156
	v_exp_f32_e32 v161, v161
	v_exp_f32_e32 v162, v162
	v_add_f32_e32 v138, 1.0, v138
	v_add_f32_e32 v160, 1.0, v160
	v_add_f32_e32 v161, 1.0, v161
	v_add_f32_e32 v162, 1.0, v162
	v_rcp_f32_e32 v138, v138
	v_rcp_f32_e32 v160, v160
	v_rcp_f32_e32 v161, v161
	v_rcp_f32_e32 v162, v162
	v_pk_mul_f32 v[158:159], v[16:17], v[8:9]
	v_pk_mul_f32 v[156:157], v[14:15], v[6:7]
	v_mul_f32_e32 v138, v2, v138
	v_mul_f32_e32 v160, v3, v160
	v_mul_f32_e32 v161, v4, v161
	v_mul_f32_e32 v162, v5, v162
	v_mul_f32_e32 v138, v18, v138
	v_mul_f32_e32 v160, v19, v160
	v_mul_f32_e32 v161, v20, v161
	v_mul_f32_e32 v162, v21, v162
	v_cvt_pk_bf16_f32 v156, v156, v157
	v_cvt_pk_bf16_f32 v157, v158, v159
	v_cvt_pk_bf16_f32 v158, v138, v160
	v_cvt_pk_bf16_f32 v159, v161, v162
	v_add_co_u32_e32 v154, vcc, 0x2c000, v154
	v_permlane16_swap_b32_e32 v156, v158
	v_permlane16_swap_b32_e32 v157, v159
	v_addc_co_u32_e32 v155, vcc, 0, v155, vcc
	global_store_dwordx4 v[154:155], v[156:159], off

; __device__ __forceinline__ unsigned cvt_pk_bf16(float lo, float hi) { unsigned r; asm volatile("v_cvt_pk_bf16_f32 %0, %1, %2" : "=v"(r) : "v"(lo), "v"(hi)); return r; }
;     __device__ __forceinline__ void operator()(const f32x4 (&acc)[2][2][4][2], const Unit& u, int wr, int wc, int fr, int fq) const {
;     ...
;         if (pn < 4) {
;             const bool isq = pn < 2; const float* g = isq ? qg : kg; bf16_t* dst = (bf16_t*)(ws + (isq ? OFF_Q : OFF_K)); const float sc = isq ? qscale : 1.0f;
;             const int colb = (pn & 1) * 256 + 64 * wc + 8 * fq;
;             f32x4 gv[2][2];
; #pragma unroll
;             for (int bj = 0; bj < 2; ++bj)
; #pragma unroll
;                 for (int n = 0; n < 2; ++n) gv[bj][n] = *(const f32x4*)(g + 32 * bj + 8 * fq + 4 * n) * sc;
; #pragma unroll
;             for (int ai = 0; ai < 2; ++ai)
; #pragma unroll
;                 for (int m = 0; m < 4; ++m) {
;                     float ss = 0.f;
; #pragma unroll
;                     for (int bj = 0; bj < 2; ++bj)
; #pragma unroll
;                         for (int n = 0; n < 2; ++n) { const f32x4 x = acc[ai][bj][m][n]; ss += (x[0] * x[0] + x[1] * x[1]) + (x[2] * x[2] + x[3] * x[3]); }
;                     ss += __shfl_xor(ss, 16); ss += __shfl_xor(ss, 32);
;                     const float rstd = __builtin_amdgcn_rsqf(ss * (1.0f / 64.0f) + eps);
;                     bf16_t* rowp = dst + (row0 + ai * HALF + m * 16) * 512 + colb;
; #pragma unroll
;                     for (int bj = 0; bj < 2; ++bj) { const f32x4 v0 = acc[ai][bj][m][0] * rstd * gv[bj][0], v1 = acc[ai][bj][m][1] * rstd * gv[bj][1];
;                         u32x4 w; w.x = cvt_pk_bf16(v0[0], v0[1]); w.y = cvt_pk_bf16(v0[2], v0[3]); w.z = cvt_pk_bf16(v1[0], v1[1]); w.w = cvt_pk_bf16(v1[2], v1[3]);
;                         *(u32x4*)(rowp + 32 * bj) = w; }
.LBB0_281:
	s_mov_b32 s89, 2
	s_lshl_b32 s31, s40, 8
	s_cmp_lt_i32 s40, 2
	s_cselect_b64 vcc, -1, 0
	s_and_b64 s[6:7], vcc, exec
	s_cselect_b32 s7, s9, s11
	s_cselect_b32 s6, s8, s10
	global_load_dwordx4 v[156:159], v179, s[6:7]
	global_load_dwordx4 v[160:163], v179, s[6:7] offset:16
	global_load_dwordx4 v[182:185], v179, s[6:7] offset:128
	global_load_dwordx4 v[186:189], v179, s[6:7] offset:144
	v_pk_mul_f32 v[154:155], v[128:129], v[128:129]
	v_pk_mul_f32 v[192:193], v[126:127], v[126:127]
	v_pk_mul_f32 v[194:195], v[124:125], v[124:125]
	v_pk_mul_f32 v[196:197], v[122:123], v[122:123]
	v_pk_mov_b32 v[208:209], v[192:193], v[154:155] op_sel:[1,0]
	v_mov_b32_e32 v193, v155
	v_pk_mov_b32 v[154:155], v[196:197], v[194:195] op_sel:[1,0]
	v_mov_b32_e32 v197, v195
	v_mul_f32_e32 v138, v119, v119
	v_mul_f32_e32 v198, v121, v121
	v_pk_add_f32 v[192:193], v[208:209], v[192:193]
	v_pk_add_f32 v[154:155], v[154:155], v[196:197]
	v_mul_f32_e32 v191, v106, v106
	v_mul_f32_e32 v212, v107, v107
	v_mul_f32_e32 v213, v108, v108
	v_mul_f32_e32 v214, v109, v109
	v_pk_fma_f32 v[194:195], v[118:119], v[118:119], v[138:139] op_sel_hi:[1,1,0]
	v_pk_fma_f32 v[198:199], v[120:121], v[120:121], v[198:199] op_sel_hi:[1,1,0]
	v_pk_add_f32 v[192:193], v[192:193], v[192:193] op_sel:[0,1] op_sel_hi:[1,0]
	v_pk_add_f32 v[154:155], v[154:155], v[154:155] op_sel:[0,1] op_sel_hi:[1,0]
	v_mov_b32_e32 v195, v213
	v_mov_b32_e32 v199, v214
	v_mov_b32_e32 v193, v191
	v_mov_b32_e32 v155, v212
	v_pk_add_f32 v[194:195], v[194:195], v[198:199]
	v_pk_add_f32 v[154:155], v[192:193], v[154:155]
	s_cselect_b32 s6, s76, 0x8000000
	v_pk_add_f32 v[154:155], v[154:155], v[194:195]
	s_add_u32 s6, s12, s6
	v_add_f32_e32 v138, v154, v155
	ds_bpermute_b32 v154, v166, v138
	s_addc_u32 s7, s13, 0
	s_and_b32 s31, s31, 0x100
	v_or_b32_e32 v155, s31, v175
	v_pk_mul_f32 v[200:201], v[116:117], v[116:117]
	s_waitcnt lgkmcnt(0)
	v_add_f32_e32 v138, v138, v154
	ds_bpermute_b32 v154, v164, v138
	v_pk_mul_f32 v[202:203], v[114:115], v[114:115]
	v_pk_mul_f32 v[204:205], v[112:113], v[112:113]
	v_pk_mul_f32 v[206:207], v[110:111], v[110:111]
	v_cndmask_b32_e32 v190, 1.0, v181, vcc
	s_waitcnt lgkmcnt(0)
	v_add_f32_e32 v138, v138, v154
	v_fmamk_f32 v138, v138, 0x3c800000, v180
	v_rsq_f32_e32 v196, v138
	v_lshlrev_b32_e32 v138, 1, v155
	v_lshlrev_b64 v[152:153], 10, v[152:153]
	v_pk_mov_b32 v[210:211], v[202:203], v[200:201] op_sel:[1,0]
	v_mov_b32_e32 v203, v201
	v_pk_mov_b32 v[200:201], v[206:207], v[204:205] op_sel:[1,0]
	v_mov_b32_e32 v207, v205
	v_lshl_add_u64 v[154:155], s[6:7], 0, v[138:139]
	v_pk_add_f32 v[194:195], v[200:201], v[206:207]
	v_lshl_add_u64 v[152:153], v[154:155], 0, v[152:153]
	v_pk_mul_f32 v[198:199], v[126:127], v[196:197] op_sel_hi:[1,0]
	v_pk_mul_f32 v[200:201], v[128:129], v[196:197] op_sel_hi:[1,0]
	v_pk_add_f32 v[192:193], v[210:211], v[202:203]
	v_pk_mul_f32 v[202:203], v[122:123], v[196:197] op_sel_hi:[1,0]
	v_pk_mul_f32 v[204:205], v[124:125], v[196:197] op_sel_hi:[1,0]
	v_mul_f32_e32 v215, v90, v90
	v_mul_f32_e32 v216, v91, v91
	v_mul_f32_e32 v138, v103, v103
	v_pk_mul_f32 v[206:207], v[118:119], v[196:197] op_sel_hi:[1,0]
	v_pk_mul_f32 v[208:209], v[120:121], v[196:197] op_sel_hi:[1,0]
	v_pk_mul_f32 v[106:107], v[106:107], v[196:197] op_sel_hi:[1,0]
	v_pk_mul_f32 v[108:109], v[108:109], v[196:197] op_sel_hi:[1,0]
	s_waitcnt vmcnt(0)
	v_pk_mul_f32 v[154:155], v[190:191], v[158:159] op_sel_hi:[0,1]
	v_pk_mul_f32 v[156:157], v[190:191], v[156:157] op_sel_hi:[0,1]
	v_pk_mul_f32 v[126:127], v[190:191], v[162:163] op_sel_hi:[0,1]
	v_pk_mul_f32 v[128:129], v[190:191], v[160:161] op_sel_hi:[0,1]
	v_pk_mul_f32 v[160:161], v[154:155], v[200:201]
	v_pk_mul_f32 v[158:159], v[156:157], v[198:199]
	v_pk_mul_f32 v[124:125], v[190:191], v[182:183] op_sel_hi:[0,1]
	v_pk_mul_f32 v[162:163], v[126:127], v[204:205]
	v_pk_mul_f32 v[182:183], v[128:129], v[202:203]
	v_cvt_pk_bf16_f32 v158, v158, v159
	v_cvt_pk_bf16_f32 v159, v160, v161
	v_pk_mul_f32 v[118:119], v[190:191], v[188:189] op_sel_hi:[0,1]
	v_cvt_pk_bf16_f32 v160, v182, v183
	v_cvt_pk_bf16_f32 v161, v162, v163
	global_store_dwordx4 v[152:153], v[158:161], off
	v_mul_f32_e32 v162, v92, v92
	v_mul_f32_e32 v182, v93, v93
	v_pk_add_f32 v[158:159], v[192:193], v[192:193] op_sel:[0,1] op_sel_hi:[1,0]
	v_pk_add_f32 v[160:161], v[194:195], v[194:195] op_sel:[0,1] op_sel_hi:[1,0]
	v_mov_b32_e32 v159, v215
	v_mov_b32_e32 v161, v216
	v_pk_add_f32 v[158:159], v[158:159], v[160:161]
	v_pk_fma_f32 v[160:161], v[102:103], v[102:103], v[138:139] op_sel_hi:[1,1,0]
	v_mul_f32_e32 v138, v105, v105
	v_mov_b32_e32 v161, v162
	v_pk_fma_f32 v[162:163], v[104:105], v[104:105], v[138:139] op_sel_hi:[1,1,0]
	v_pk_mul_f32 v[120:121], v[190:191], v[186:187] op_sel_hi:[0,1]
	v_mov_b32_e32 v163, v182
	v_pk_add_f32 v[160:161], v[160:161], v[162:163]
	v_pk_mul_f32 v[122:123], v[190:191], v[184:185] op_sel_hi:[0,1]
	v_pk_add_f32 v[158:159], v[158:159], v[160:161]
	v_pk_mul_f32 v[160:161], v[124:125], v[206:207]
	v_add_f32_e32 v138, v158, v159
	ds_bpermute_b32 v162, v166, v138
	v_pk_mul_f32 v[158:159], v[122:123], v[208:209]
	s_waitcnt lgkmcnt(0)
	v_add_f32_e32 v138, v138, v162
	ds_bpermute_b32 v182, v164, v138
	v_pk_mul_f32 v[162:163], v[118:119], v[108:109]
	v_pk_mul_f32 v[108:109], v[120:121], v[106:107]
	v_cvt_pk_bf16_f32 v106, v160, v161
	v_cvt_pk_bf16_f32 v107, v158, v159
	s_waitcnt lgkmcnt(0)
; __device__ __forceinline__ unsigned cvt_pk_bf16(float lo, float hi) { unsigned r; asm volatile("v_cvt_pk_bf16_f32 %0, %1, %2" : "=v"(r) : "v"(lo), "v"(hi)); return r; }
;     __device__ __forceinline__ void operator()(const f32x4 (&acc)[2][2][4][2], const Unit& u, int wr, int wc, int fr, int fq) const {
;     ...
;                     float ss = 0.f;
; #pragma unroll
;                     for (int bj = 0; bj < 2; ++bj)
; #pragma unroll
;                         for (int n = 0; n < 2; ++n) { const f32x4 x = acc[ai][bj][m][n]; ss += (x[0] * x[0] + x[1] * x[1]) + (x[2] * x[2] + x[3] * x[3]); }
;                     ss += __shfl_xor(ss, 16); ss += __shfl_xor(ss, 32);
;                     const float rstd = __builtin_amdgcn_rsqf(ss * (1.0f / 64.0f) + eps);
;                     bf16_t* rowp = dst + (row0 + ai * HALF + m * 16) * 512 + colb;
; #pragma unroll
;                     for (int bj = 0; bj < 2; ++bj) { const f32x4 v0 = acc[ai][bj][m][0] * rstd * gv[bj][0], v1 = acc[ai][bj][m][1] * rstd * gv[bj][1];
;                         u32x4 w; w.x = cvt_pk_bf16(v0[0], v0[1]); w.y = cvt_pk_bf16(v0[2], v0[3]); w.z = cvt_pk_bf16(v1[0], v1[1]); w.w = cvt_pk_bf16(v1[2], v1[3]);
;                         *(u32x4*)(rowp + 32 * bj) = w; }
	v_add_f32_e32 v138, v138, v182
	v_fmamk_f32 v138, v138, 0x3c800000, v180
	v_rsq_f32_e32 v138, v138
	v_cvt_pk_bf16_f32 v108, v108, v109
	v_cvt_pk_bf16_f32 v109, v162, v163
	global_store_dwordx4 v[152:153], v[106:109], off offset:64
	v_pk_mul_f32 v[110:111], v[110:111], v[138:139] op_sel_hi:[1,0]
	v_pk_mul_f32 v[112:113], v[112:113], v[138:139] op_sel_hi:[1,0]
	v_pk_mul_f32 v[106:107], v[114:115], v[138:139] op_sel_hi:[1,0]
	v_pk_mul_f32 v[108:109], v[116:117], v[138:139] op_sel_hi:[1,0]
	v_pk_mul_f32 v[106:107], v[156:157], v[106:107]
	v_pk_mul_f32 v[108:109], v[154:155], v[108:109]
	v_pk_mul_f32 v[110:111], v[128:129], v[110:111]
	v_cvt_pk_bf16_f32 v106, v106, v107
	v_cvt_pk_bf16_f32 v107, v108, v109
	v_pk_mul_f32 v[112:113], v[126:127], v[112:113]
	v_cvt_pk_bf16_f32 v108, v110, v111
	v_add_co_u32_e32 v110, vcc, s56, v152
	v_cvt_pk_bf16_f32 v109, v112, v113
	v_pk_mul_f32 v[102:103], v[102:103], v[138:139] op_sel_hi:[1,0]
	s_nop 0
	v_addc_co_u32_e32 v111, vcc, 0, v153, vcc
	global_store_dwordx4 v[110:111], v[106:109], off
	v_pk_mul_f32 v[102:103], v[124:125], v[102:103]
	v_pk_mul_f32 v[90:91], v[90:91], v[138:139] op_sel_hi:[1,0]
	v_pk_mul_f32 v[106:107], v[100:101], v[100:101]
	v_pk_mul_f32 v[108:109], v[98:99], v[98:99]
	v_pk_mul_f32 v[92:93], v[92:93], v[138:139] op_sel_hi:[1,0]
	v_pk_mov_b32 v[112:113], v[108:109], v[106:107] op_sel:[1,0]
	v_mov_b32_e32 v109, v107
	v_pk_add_f32 v[106:107], v[112:113], v[108:109]
	v_pk_mul_f32 v[108:109], v[96:97], v[96:97]
	v_pk_mul_f32 v[112:113], v[94:95], v[94:95]
	v_pk_add_f32 v[106:107], v[106:107], v[106:107] op_sel:[0,1] op_sel_hi:[1,0]
	v_pk_mov_b32 v[114:115], v[112:113], v[108:109] op_sel:[1,0]
	v_mov_b32_e32 v113, v109
	v_pk_add_f32 v[108:109], v[114:115], v[112:113]
	v_mul_f32_e32 v112, v74, v74
	v_mul_f32_e32 v113, v75, v75
	v_pk_add_f32 v[108:109], v[108:109], v[108:109] op_sel:[0,1] op_sel_hi:[1,0]
	v_mov_b32_e32 v107, v112
	v_mov_b32_e32 v109, v113
	v_pk_add_f32 v[106:107], v[106:107], v[108:109]
	v_mul_f32_e32 v108, v87, v87
	v_mul_f32_e32 v112, v89, v89
	v_mul_f32_e32 v114, v76, v76
	v_mul_f32_e32 v115, v77, v77
	v_pk_fma_f32 v[108:109], v[86:87], v[86:87], v[108:109] op_sel_hi:[1,1,0]
	v_pk_fma_f32 v[112:113], v[88:89], v[88:89], v[112:113] op_sel_hi:[1,1,0]
	v_mov_b32_e32 v109, v114
	v_mov_b32_e32 v113, v115
	v_pk_add_f32 v[108:109], v[108:109], v[112:113]
	v_pk_mul_f32 v[104:105], v[104:105], v[138:139] op_sel_hi:[1,0]
	v_pk_add_f32 v[106:107], v[106:107], v[108:109]
	v_pk_mul_f32 v[104:105], v[122:123], v[104:105]
	v_add_f32_e32 v106, v106, v107
	ds_bpermute_b32 v107, v166, v106
	s_waitcnt lgkmcnt(0)
	v_add_f32_e32 v108, v106, v107
	ds_bpermute_b32 v109, v164, v108
	v_pk_mul_f32 v[106:107], v[118:119], v[92:93]
	v_pk_mul_f32 v[92:93], v[120:121], v[90:91]
	v_cvt_pk_bf16_f32 v90, v102, v103
	v_cvt_pk_bf16_f32 v91, v104, v105
	s_waitcnt lgkmcnt(0)
	v_add_f32_e32 v102, v108, v109
	v_fmamk_f32 v102, v102, 0x3c800000, v180
	v_rsq_f32_e32 v102, v102
	v_cvt_pk_bf16_f32 v92, v92, v93
	v_cvt_pk_bf16_f32 v93, v106, v107
	global_store_dwordx4 v[110:111], v[90:93], off offset:64
	v_pk_mul_f32 v[94:95], v[94:95], v[102:103] op_sel_hi:[1,0]
	v_pk_mul_f32 v[96:97], v[96:97], v[102:103] op_sel_hi:[1,0]
	v_pk_mul_f32 v[90:91], v[98:99], v[102:103] op_sel_hi:[1,0]
	v_pk_mul_f32 v[92:93], v[100:101], v[102:103] op_sel_hi:[1,0]
	v_pk_mul_f32 v[90:91], v[156:157], v[90:91]
	v_pk_mul_f32 v[92:93], v[154:155], v[92:93]
	v_pk_mul_f32 v[94:95], v[128:129], v[94:95]
	v_cvt_pk_bf16_f32 v90, v90, v91
	v_cvt_pk_bf16_f32 v91, v92, v93
	v_pk_mul_f32 v[96:97], v[126:127], v[96:97]
	v_cvt_pk_bf16_f32 v92, v94, v95
	v_add_co_u32_e32 v94, vcc, s60, v152
	v_cvt_pk_bf16_f32 v93, v96, v97
	v_pk_mul_f32 v[86:87], v[86:87], v[102:103] op_sel_hi:[1,0]
	s_nop 0
	v_addc_co_u32_e32 v95, vcc, 0, v153, vcc
	global_store_dwordx4 v[94:95], v[90:93], off
	v_pk_mul_f32 v[86:87], v[124:125], v[86:87]
	v_pk_mul_f32 v[74:75], v[74:75], v[102:103] op_sel_hi:[1,0]
	v_pk_mul_f32 v[90:91], v[84:85], v[84:85]
	v_pk_mul_f32 v[92:93], v[82:83], v[82:83]
	v_pk_mul_f32 v[76:77], v[76:77], v[102:103] op_sel_hi:[1,0]
	v_pk_mov_b32 v[96:97], v[92:93], v[90:91] op_sel:[1,0]
	v_mov_b32_e32 v93, v91
	v_pk_add_f32 v[90:91], v[96:97], v[92:93]
	v_pk_mul_f32 v[92:93], v[80:81], v[80:81]
	v_pk_mul_f32 v[96:97], v[78:79], v[78:79]
	v_pk_add_f32 v[90:91], v[90:91], v[90:91] op_sel:[0,1] op_sel_hi:[1,0]
	v_pk_mov_b32 v[98:99], v[96:97], v[92:93] op_sel:[1,0]
	v_mov_b32_e32 v97, v93
	v_pk_add_f32 v[92:93], v[98:99], v[96:97]
	v_mul_f32_e32 v96, v66, v66
	v_mul_f32_e32 v97, v67, v67
	v_pk_add_f32 v[92:93], v[92:93], v[92:93] op_sel:[0,1] op_sel_hi:[1,0]
	v_mov_b32_e32 v91, v96
	v_mov_b32_e32 v93, v97
	v_pk_add_f32 v[90:91], v[90:91], v[92:93]
	v_mul_f32_e32 v92, v71, v71
	v_mul_f32_e32 v96, v73, v73
	v_mul_f32_e32 v98, v68, v68
	v_mul_f32_e32 v99, v69, v69
	v_pk_fma_f32 v[92:93], v[70:71], v[70:71], v[92:93] op_sel_hi:[1,1,0]
	v_pk_fma_f32 v[96:97], v[72:73], v[72:73], v[96:97] op_sel_hi:[1,1,0]
	v_mov_b32_e32 v93, v98
	v_mov_b32_e32 v97, v99
	v_pk_add_f32 v[92:93], v[92:93], v[96:97]
	v_pk_mul_f32 v[88:89], v[88:89], v[102:103] op_sel_hi:[1,0]
	v_pk_add_f32 v[90:91], v[90:91], v[92:93]
	v_pk_mul_f32 v[88:89], v[122:123], v[88:89]
	v_add_f32_e32 v90, v90, v91
	ds_bpermute_b32 v91, v166, v90
	s_waitcnt lgkmcnt(0)
	v_add_f32_e32 v92, v90, v91
	ds_bpermute_b32 v93, v164, v92
	v_pk_mul_f32 v[90:91], v[118:119], v[76:77]
	v_pk_mul_f32 v[76:77], v[120:121], v[74:75]
	v_cvt_pk_bf16_f32 v74, v86, v87
	v_cvt_pk_bf16_f32 v75, v88, v89
	s_waitcnt lgkmcnt(0)
; __device__ __forceinline__ unsigned cvt_pk_bf16(float lo, float hi) { unsigned r; asm volatile("v_cvt_pk_bf16_f32 %0, %1, %2" : "=v"(r) : "v"(lo), "v"(hi)); return r; }
;     __device__ __forceinline__ void operator()(const f32x4 (&acc)[2][2][4][2], const Unit& u, int wr, int wc, int fr, int fq) const {
;     ...
;                     float ss = 0.f;
; #pragma unroll
;                     for (int bj = 0; bj < 2; ++bj)
; #pragma unroll
;                         for (int n = 0; n < 2; ++n) { const f32x4 x = acc[ai][bj][m][n]; ss += (x[0] * x[0] + x[1] * x[1]) + (x[2] * x[2] + x[3] * x[3]); }
;                     ss += __shfl_xor(ss, 16); ss += __shfl_xor(ss, 32);
;                     const float rstd = __builtin_amdgcn_rsqf(ss * (1.0f / 64.0f) + eps);
;                     bf16_t* rowp = dst + (row0 + ai * HALF + m * 16) * 512 + colb;
; #pragma unroll
;                     for (int bj = 0; bj < 2; ++bj) { const f32x4 v0 = acc[ai][bj][m][0] * rstd * gv[bj][0], v1 = acc[ai][bj][m][1] * rstd * gv[bj][1];
;                         u32x4 w; w.x = cvt_pk_bf16(v0[0], v0[1]); w.y = cvt_pk_bf16(v0[2], v0[3]); w.z = cvt_pk_bf16(v1[0], v1[1]); w.w = cvt_pk_bf16(v1[2], v1[3]);
;                         *(u32x4*)(rowp + 32 * bj) = w; }
	v_add_f32_e32 v86, v92, v93
	v_fmamk_f32 v86, v86, 0x3c800000, v180
	v_rsq_f32_e32 v86, v86
	v_cvt_pk_bf16_f32 v76, v76, v77
	v_cvt_pk_bf16_f32 v77, v90, v91
	global_store_dwordx4 v[94:95], v[74:77], off offset:64
	v_pk_mul_f32 v[78:79], v[78:79], v[86:87] op_sel_hi:[1,0]
	v_pk_mul_f32 v[80:81], v[80:81], v[86:87] op_sel_hi:[1,0]
	v_pk_mul_f32 v[74:75], v[82:83], v[86:87] op_sel_hi:[1,0]
	v_pk_mul_f32 v[76:77], v[84:85], v[86:87] op_sel_hi:[1,0]
	v_pk_mul_f32 v[74:75], v[156:157], v[74:75]
	v_pk_mul_f32 v[76:77], v[154:155], v[76:77]
	v_pk_mul_f32 v[78:79], v[128:129], v[78:79]
	v_cvt_pk_bf16_f32 v74, v74, v75
	v_cvt_pk_bf16_f32 v75, v76, v77
	v_pk_mul_f32 v[80:81], v[126:127], v[80:81]
	v_cvt_pk_bf16_f32 v76, v78, v79
	v_add_co_u32_e32 v78, vcc, s66, v152
	v_cvt_pk_bf16_f32 v77, v80, v81
	v_pk_mul_f32 v[70:71], v[70:71], v[86:87] op_sel_hi:[1,0]
	s_nop 0
	v_addc_co_u32_e32 v79, vcc, 0, v153, vcc
	global_store_dwordx4 v[78:79], v[74:77], off
	v_pk_mul_f32 v[70:71], v[124:125], v[70:71]
	v_pk_mul_f32 v[66:67], v[66:67], v[86:87] op_sel_hi:[1,0]
	v_pk_mul_f32 v[74:75], v[64:65], v[64:65]
	v_pk_mul_f32 v[76:77], v[62:63], v[62:63]
	v_pk_mul_f32 v[68:69], v[68:69], v[86:87] op_sel_hi:[1,0]
	v_pk_mov_b32 v[80:81], v[76:77], v[74:75] op_sel:[1,0]
	v_mov_b32_e32 v77, v75
	v_pk_add_f32 v[74:75], v[80:81], v[76:77]
	v_pk_mul_f32 v[76:77], v[60:61], v[60:61]
	v_pk_mul_f32 v[80:81], v[58:59], v[58:59]
	v_pk_add_f32 v[74:75], v[74:75], v[74:75] op_sel:[0,1] op_sel_hi:[1,0]
	v_pk_mov_b32 v[82:83], v[80:81], v[76:77] op_sel:[1,0]
	v_mov_b32_e32 v81, v77
	v_pk_add_f32 v[76:77], v[82:83], v[80:81]
	v_mul_f32_e32 v80, v42, v42
	v_mul_f32_e32 v81, v43, v43
	v_pk_add_f32 v[76:77], v[76:77], v[76:77] op_sel:[0,1] op_sel_hi:[1,0]
	v_mov_b32_e32 v75, v80
	v_mov_b32_e32 v77, v81
	v_pk_add_f32 v[74:75], v[74:75], v[76:77]
	v_mul_f32_e32 v76, v55, v55
	v_mul_f32_e32 v80, v57, v57
	v_mul_f32_e32 v82, v44, v44
	v_mul_f32_e32 v83, v45, v45
	v_pk_fma_f32 v[76:77], v[54:55], v[54:55], v[76:77] op_sel_hi:[1,1,0]
	v_pk_fma_f32 v[80:81], v[56:57], v[56:57], v[80:81] op_sel_hi:[1,1,0]
	v_mov_b32_e32 v77, v82
	v_mov_b32_e32 v81, v83
	v_pk_add_f32 v[76:77], v[76:77], v[80:81]
	v_pk_mul_f32 v[72:73], v[72:73], v[86:87] op_sel_hi:[1,0]
	v_pk_add_f32 v[74:75], v[74:75], v[76:77]
	v_pk_mul_f32 v[72:73], v[122:123], v[72:73]
	v_add_f32_e32 v74, v74, v75
	ds_bpermute_b32 v75, v166, v74
	s_waitcnt lgkmcnt(0)
	v_add_f32_e32 v76, v74, v75
	ds_bpermute_b32 v77, v164, v76
	v_pk_mul_f32 v[74:75], v[118:119], v[68:69]
	v_pk_mul_f32 v[68:69], v[120:121], v[66:67]
	v_cvt_pk_bf16_f32 v66, v70, v71
	v_cvt_pk_bf16_f32 v67, v72, v73
	s_waitcnt lgkmcnt(0)
	v_add_f32_e32 v70, v76, v77
	v_fmamk_f32 v70, v70, 0x3c800000, v180
	v_rsq_f32_e32 v70, v70
	v_cvt_pk_bf16_f32 v68, v68, v69
	v_cvt_pk_bf16_f32 v69, v74, v75
	global_store_dwordx4 v[78:79], v[66:69], off offset:64
	v_pk_mul_f32 v[62:63], v[62:63], v[70:71] op_sel_hi:[1,0]
	v_pk_mul_f32 v[58:59], v[58:59], v[70:71] op_sel_hi:[1,0]
	v_pk_mul_f32 v[62:63], v[156:157], v[62:63]
	v_pk_mul_f32 v[60:61], v[60:61], v[70:71] op_sel_hi:[1,0]
	v_pk_mul_f32 v[64:65], v[64:65], v[70:71] op_sel_hi:[1,0]
	v_pk_mul_f32 v[66:67], v[126:127], v[60:61]
	v_pk_mul_f32 v[60:61], v[128:129], v[58:59]
	v_cvt_pk_bf16_f32 v58, v62, v63
	v_add_co_u32_e32 v62, vcc, s69, v152
	v_pk_mul_f32 v[64:65], v[154:155], v[64:65]
	s_nop 0
	v_addc_co_u32_e32 v63, vcc, 0, v153, vcc
	v_cvt_pk_bf16_f32 v59, v64, v65
	v_cvt_pk_bf16_f32 v60, v60, v61
	v_cvt_pk_bf16_f32 v61, v66, v67
	global_store_dwordx4 v[62:63], v[58:61], off
	v_pk_mul_f32 v[54:55], v[54:55], v[70:71] op_sel_hi:[1,0]
	v_pk_mul_f32 v[42:43], v[42:43], v[70:71] op_sel_hi:[1,0]
	v_pk_mul_f32 v[58:59], v[52:53], v[52:53]
	v_pk_mul_f32 v[60:61], v[50:51], v[50:51]
	v_pk_mul_f32 v[54:55], v[124:125], v[54:55]
	v_pk_mov_b32 v[64:65], v[60:61], v[58:59] op_sel:[1,0]
	v_mov_b32_e32 v61, v59
	v_pk_add_f32 v[58:59], v[64:65], v[60:61]
	v_pk_mul_f32 v[60:61], v[48:49], v[48:49]
	v_pk_mul_f32 v[64:65], v[46:47], v[46:47]
	v_pk_add_f32 v[58:59], v[58:59], v[58:59] op_sel:[0,1] op_sel_hi:[1,0]
	v_pk_mov_b32 v[66:67], v[64:65], v[60:61] op_sel:[1,0]
	v_mov_b32_e32 v65, v61
	v_pk_add_f32 v[60:61], v[66:67], v[64:65]
	v_mul_f32_e32 v64, v26, v26
	v_mul_f32_e32 v65, v27, v27
	v_pk_add_f32 v[60:61], v[60:61], v[60:61] op_sel:[0,1] op_sel_hi:[1,0]
	v_mov_b32_e32 v59, v64
	v_mov_b32_e32 v61, v65
	v_pk_add_f32 v[58:59], v[58:59], v[60:61]
	v_mul_f32_e32 v60, v39, v39
	v_mul_f32_e32 v64, v41, v41
	v_mul_f32_e32 v66, v28, v28
	v_mul_f32_e32 v67, v29, v29
	v_pk_fma_f32 v[60:61], v[38:39], v[38:39], v[60:61] op_sel_hi:[1,1,0]
	v_pk_fma_f32 v[64:65], v[40:41], v[40:41], v[64:65] op_sel_hi:[1,1,0]
	v_mov_b32_e32 v61, v66
	v_mov_b32_e32 v65, v67
	v_pk_add_f32 v[60:61], v[60:61], v[64:65]
	v_pk_mul_f32 v[44:45], v[44:45], v[70:71] op_sel_hi:[1,0]
	v_pk_add_f32 v[58:59], v[58:59], v[60:61]
	v_pk_mul_f32 v[56:57], v[56:57], v[70:71] op_sel_hi:[1,0]
	v_add_f32_e32 v58, v58, v59
	ds_bpermute_b32 v59, v166, v58
	v_pk_mul_f32 v[56:57], v[122:123], v[56:57]
	s_waitcnt lgkmcnt(0)
	v_add_f32_e32 v60, v58, v59
	ds_bpermute_b32 v61, v164, v60
	v_pk_mul_f32 v[58:59], v[118:119], v[44:45]
	v_pk_mul_f32 v[44:45], v[120:121], v[42:43]
	v_cvt_pk_bf16_f32 v42, v54, v55
	v_cvt_pk_bf16_f32 v43, v56, v57
	s_waitcnt lgkmcnt(0)
; __device__ __forceinline__ unsigned cvt_pk_bf16(float lo, float hi) { unsigned r; asm volatile("v_cvt_pk_bf16_f32 %0, %1, %2" : "=v"(r) : "v"(lo), "v"(hi)); return r; }
;     __device__ __forceinline__ void operator()(const f32x4 (&acc)[2][2][4][2], const Unit& u, int wr, int wc, int fr, int fq) const {
;     ...
;                     float ss = 0.f;
; #pragma unroll
;                     for (int bj = 0; bj < 2; ++bj)
; #pragma unroll
;                         for (int n = 0; n < 2; ++n) { const f32x4 x = acc[ai][bj][m][n]; ss += (x[0] * x[0] + x[1] * x[1]) + (x[2] * x[2] + x[3] * x[3]); }
;                     ss += __shfl_xor(ss, 16); ss += __shfl_xor(ss, 32);
;                     const float rstd = __builtin_amdgcn_rsqf(ss * (1.0f / 64.0f) + eps);
;                     bf16_t* rowp = dst + (row0 + ai * HALF + m * 16) * 512 + colb;
; #pragma unroll
;                     for (int bj = 0; bj < 2; ++bj) { const f32x4 v0 = acc[ai][bj][m][0] * rstd * gv[bj][0], v1 = acc[ai][bj][m][1] * rstd * gv[bj][1];
;                         u32x4 w; w.x = cvt_pk_bf16(v0[0], v0[1]); w.y = cvt_pk_bf16(v0[2], v0[3]); w.z = cvt_pk_bf16(v1[0], v1[1]); w.w = cvt_pk_bf16(v1[2], v1[3]);
;                         *(u32x4*)(rowp + 32 * bj) = w; }
	v_add_f32_e32 v54, v60, v61
	v_fmamk_f32 v54, v54, 0x3c800000, v180
	v_rsq_f32_e32 v54, v54
	v_cvt_pk_bf16_f32 v44, v44, v45
	v_cvt_pk_bf16_f32 v45, v58, v59
	global_store_dwordx4 v[62:63], v[42:45], off offset:64
	v_pk_mul_f32 v[46:47], v[46:47], v[54:55] op_sel_hi:[1,0]
	v_pk_mul_f32 v[48:49], v[48:49], v[54:55] op_sel_hi:[1,0]
	v_pk_mul_f32 v[42:43], v[50:51], v[54:55] op_sel_hi:[1,0]
	v_pk_mul_f32 v[44:45], v[52:53], v[54:55] op_sel_hi:[1,0]
	v_pk_mul_f32 v[42:43], v[156:157], v[42:43]
	v_pk_mul_f32 v[44:45], v[154:155], v[44:45]
	v_pk_mul_f32 v[46:47], v[128:129], v[46:47]
	v_cvt_pk_bf16_f32 v42, v42, v43
	v_cvt_pk_bf16_f32 v43, v44, v45
	v_pk_mul_f32 v[48:49], v[126:127], v[48:49]
	v_cvt_pk_bf16_f32 v44, v46, v47
	v_add_co_u32_e32 v46, vcc, s70, v152
	v_cvt_pk_bf16_f32 v45, v48, v49
	v_pk_mul_f32 v[38:39], v[38:39], v[54:55] op_sel_hi:[1,0]
	s_nop 0
	v_addc_co_u32_e32 v47, vcc, 0, v153, vcc
	global_store_dwordx4 v[46:47], v[42:45], off
	v_pk_mul_f32 v[38:39], v[124:125], v[38:39]
	v_pk_mul_f32 v[26:27], v[26:27], v[54:55] op_sel_hi:[1,0]
	v_pk_mul_f32 v[42:43], v[36:37], v[36:37]
	v_pk_mul_f32 v[44:45], v[34:35], v[34:35]
	v_pk_mul_f32 v[28:29], v[28:29], v[54:55] op_sel_hi:[1,0]
	v_pk_mov_b32 v[48:49], v[44:45], v[42:43] op_sel:[1,0]
	v_mov_b32_e32 v45, v43
	v_pk_add_f32 v[42:43], v[48:49], v[44:45]
	v_pk_mul_f32 v[44:45], v[32:33], v[32:33]
	v_pk_mul_f32 v[48:49], v[30:31], v[30:31]
	v_pk_add_f32 v[42:43], v[42:43], v[42:43] op_sel:[0,1] op_sel_hi:[1,0]
	v_pk_mov_b32 v[50:51], v[48:49], v[44:45] op_sel:[1,0]
	v_mov_b32_e32 v49, v45
	v_pk_add_f32 v[44:45], v[50:51], v[48:49]
	v_mul_f32_e32 v48, v10, v10
	v_mul_f32_e32 v49, v11, v11
	v_pk_add_f32 v[44:45], v[44:45], v[44:45] op_sel:[0,1] op_sel_hi:[1,0]
	v_mov_b32_e32 v43, v48
	v_mov_b32_e32 v45, v49
	v_pk_add_f32 v[42:43], v[42:43], v[44:45]
	v_mul_f32_e32 v44, v23, v23
	v_mul_f32_e32 v48, v25, v25
	v_mul_f32_e32 v50, v12, v12
	v_mul_f32_e32 v51, v13, v13
	v_pk_fma_f32 v[44:45], v[22:23], v[22:23], v[44:45] op_sel_hi:[1,1,0]
	v_pk_fma_f32 v[48:49], v[24:25], v[24:25], v[48:49] op_sel_hi:[1,1,0]
	v_mov_b32_e32 v45, v50
	v_mov_b32_e32 v49, v51
	v_pk_add_f32 v[44:45], v[44:45], v[48:49]
	v_pk_mul_f32 v[40:41], v[40:41], v[54:55] op_sel_hi:[1,0]
	v_pk_add_f32 v[42:43], v[42:43], v[44:45]
	v_pk_mul_f32 v[40:41], v[122:123], v[40:41]
	v_add_f32_e32 v42, v42, v43
	ds_bpermute_b32 v43, v166, v42
	s_waitcnt lgkmcnt(0)
	v_add_f32_e32 v44, v42, v43
	ds_bpermute_b32 v45, v164, v44
	v_pk_mul_f32 v[42:43], v[118:119], v[28:29]
	v_pk_mul_f32 v[28:29], v[120:121], v[26:27]
	v_cvt_pk_bf16_f32 v26, v38, v39
	v_cvt_pk_bf16_f32 v27, v40, v41
	s_waitcnt lgkmcnt(0)
	v_add_f32_e32 v38, v44, v45
	v_fmamk_f32 v38, v38, 0x3c800000, v180
	v_rsq_f32_e32 v38, v38
	v_cvt_pk_bf16_f32 v28, v28, v29
	v_cvt_pk_bf16_f32 v29, v42, v43
	global_store_dwordx4 v[46:47], v[26:29], off offset:64
	v_pk_mul_f32 v[30:31], v[30:31], v[38:39] op_sel_hi:[1,0]
	v_pk_mul_f32 v[32:33], v[32:33], v[38:39] op_sel_hi:[1,0]
	v_pk_mul_f32 v[26:27], v[34:35], v[38:39] op_sel_hi:[1,0]
	v_pk_mul_f32 v[28:29], v[36:37], v[38:39] op_sel_hi:[1,0]
	v_pk_mul_f32 v[26:27], v[156:157], v[26:27]
	v_pk_mul_f32 v[28:29], v[154:155], v[28:29]
	v_pk_mul_f32 v[30:31], v[128:129], v[30:31]
	v_cvt_pk_bf16_f32 v26, v26, v27
	v_cvt_pk_bf16_f32 v27, v28, v29
	v_pk_mul_f32 v[32:33], v[126:127], v[32:33]
	v_cvt_pk_bf16_f32 v28, v30, v31
	v_add_co_u32_e32 v30, vcc, s71, v152
	v_cvt_pk_bf16_f32 v29, v32, v33
	v_pk_mul_f32 v[22:23], v[22:23], v[38:39] op_sel_hi:[1,0]
	s_nop 0
	v_addc_co_u32_e32 v31, vcc, 0, v153, vcc
	global_store_dwordx4 v[30:31], v[26:29], off
	v_pk_mul_f32 v[22:23], v[124:125], v[22:23]
	v_pk_mul_f32 v[10:11], v[10:11], v[38:39] op_sel_hi:[1,0]
	v_pk_mul_f32 v[26:27], v[20:21], v[20:21]
	v_pk_mul_f32 v[28:29], v[18:19], v[18:19]
	v_pk_mul_f32 v[12:13], v[12:13], v[38:39] op_sel_hi:[1,0]
	v_pk_mov_b32 v[32:33], v[28:29], v[26:27] op_sel:[1,0]
	v_mov_b32_e32 v29, v27
	v_pk_add_f32 v[26:27], v[32:33], v[28:29]
	v_pk_mul_f32 v[28:29], v[16:17], v[16:17]
	v_pk_mul_f32 v[32:33], v[14:15], v[14:15]
	v_pk_add_f32 v[26:27], v[26:27], v[26:27] op_sel:[0,1] op_sel_hi:[1,0]
	v_pk_mov_b32 v[34:35], v[32:33], v[28:29] op_sel:[1,0]
	v_mov_b32_e32 v33, v29
	v_pk_add_f32 v[28:29], v[34:35], v[32:33]
	v_mul_f32_e32 v32, v2, v2
	v_mul_f32_e32 v33, v3, v3
	v_pk_add_f32 v[28:29], v[28:29], v[28:29] op_sel:[0,1] op_sel_hi:[1,0]
	v_mov_b32_e32 v27, v32
	v_mov_b32_e32 v29, v33
	v_pk_add_f32 v[26:27], v[26:27], v[28:29]
	v_mul_f32_e32 v28, v7, v7
	v_mul_f32_e32 v32, v9, v9
	v_mul_f32_e32 v34, v4, v4
	v_mul_f32_e32 v35, v5, v5
	v_pk_fma_f32 v[28:29], v[6:7], v[6:7], v[28:29] op_sel_hi:[1,1,0]
	v_pk_fma_f32 v[32:33], v[8:9], v[8:9], v[32:33] op_sel_hi:[1,1,0]
	v_mov_b32_e32 v29, v34
	v_mov_b32_e32 v33, v35
	v_pk_add_f32 v[28:29], v[28:29], v[32:33]
	v_pk_mul_f32 v[24:25], v[24:25], v[38:39] op_sel_hi:[1,0]
	v_pk_add_f32 v[26:27], v[26:27], v[28:29]
	v_pk_mul_f32 v[24:25], v[122:123], v[24:25]
	v_add_f32_e32 v26, v26, v27
	ds_bpermute_b32 v27, v166, v26
	s_waitcnt lgkmcnt(0)
	v_add_f32_e32 v28, v26, v27
	ds_bpermute_b32 v29, v164, v28
	v_pk_mul_f32 v[26:27], v[118:119], v[12:13]
	v_pk_mul_f32 v[12:13], v[120:121], v[10:11]
	v_cvt_pk_bf16_f32 v10, v22, v23
	v_cvt_pk_bf16_f32 v11, v24, v25
	s_waitcnt lgkmcnt(0)
	v_add_f32_e32 v22, v28, v29
	v_fmamk_f32 v22, v22, 0x3c800000, v180
	v_rsq_f32_e32 v22, v22
	v_cvt_pk_bf16_f32 v12, v12, v13
	v_cvt_pk_bf16_f32 v13, v26, v27
	global_store_dwordx4 v[30:31], v[10:13], off offset:64
	v_pk_mul_f32 v[14:15], v[14:15], v[22:23] op_sel_hi:[1,0]
	v_pk_mul_f32 v[16:17], v[16:17], v[22:23] op_sel_hi:[1,0]
	v_pk_mul_f32 v[10:11], v[18:19], v[22:23] op_sel_hi:[1,0]
	v_pk_mul_f32 v[12:13], v[20:21], v[22:23] op_sel_hi:[1,0]
	v_pk_mul_f32 v[10:11], v[156:157], v[10:11]
	v_pk_mul_f32 v[12:13], v[154:155], v[12:13]
	v_pk_mul_f32 v[14:15], v[128:129], v[14:15]
	v_cvt_pk_bf16_f32 v10, v10, v11
	v_cvt_pk_bf16_f32 v11, v12, v13
	v_pk_mul_f32 v[2:3], v[2:3], v[22:23] op_sel_hi:[1,0]
	v_cvt_pk_bf16_f32 v12, v14, v15
	v_add_co_u32_e32 v14, vcc, s72, v152
	v_pk_mul_f32 v[4:5], v[4:5], v[22:23] op_sel_hi:[1,0]
	s_nop 0
	v_addc_co_u32_e32 v15, vcc, 0, v153, vcc
	v_pk_mul_f32 v[16:17], v[126:127], v[16:17]
	v_pk_mul_f32 v[6:7], v[6:7], v[22:23] op_sel_hi:[1,0]
	v_cvt_pk_bf16_f32 v13, v16, v17
	global_store_dwordx4 v[14:15], v[10:13], off
	v_pk_mul_f32 v[8:9], v[8:9], v[22:23] op_sel_hi:[1,0]
	v_pk_mul_f32 v[6:7], v[124:125], v[6:7]
	v_pk_mul_f32 v[10:11], v[118:119], v[4:5]
	v_pk_mul_f32 v[4:5], v[120:121], v[2:3]
	v_pk_mul_f32 v[8:9], v[122:123], v[8:9]
	v_cvt_pk_bf16_f32 v2, v6, v7
	s_nop 0
	v_cvt_pk_bf16_f32 v3, v8, v9
	v_cvt_pk_bf16_f32 v4, v4, v5
	v_cvt_pk_bf16_f32 v5, v10, v11
	global_store_dwordx4 v[14:15], v[2:5], off offset:64
	s_andn2_b64 vcc, exec, s[4:5]
	s_mov_b64 s[4:5], -1
	s_cbranch_vccnz .LBB0_230

; #define PG8_STAGE(bufoff, gbase, voff) do { _Pragma("unroll") for (int _i = 0; _i < 2; ++_i) \
;         __builtin_amdgcn_global_load_lds((const unsigned*)((const char*)(gbase) + (voff)[_i]), (PG8_LAS unsigned*)(lds + (bufoff) + ldsw + _i * 8192), 16, 0, 0); } while (0)
; #define PG8_WAIT_V(n) asm volatile("s_waitcnt vmcnt(" #n ")" ::: "memory")
; #define PG8_BAR __builtin_amdgcn_s_barrier()
; template <class Epi, class Sched, bool ALIGN_EPI = false, bool SP2 = false>
; __device__ __forceinline__ void gemm_phase(PG8_LAS unsigned char* lds, const Gemm g, const Sched& S, const Epi& E) {
;     ...
;     const int tid = tid_, wid = __builtin_amdgcn_readfirstlane(tid >> 6), lane = tid & 63, wr = wid >> 2, wc = wid & 3, fr = lane & 15, fq = lane >> 4;
;     const int K = g.K, nt = K / BK;
;     unsigned voffA[2], voffB[2];
; #pragma unroll
;     for (int i = 0; i < 2; ++i) { int R, C; stage_rc(tid * 16 + i * 8192, R, C); const int Rb = Epi::PERM ? ((R & ~31) + perm32(R & 31)) : R;
;         voffA[i] = (unsigned)(R * K + C) * 2u; voffB[i] = (unsigned)(Rb * K + C) * 2u; }
;     const size_t kstep = (size_t)(BK * 2);
;     const size_t hstep = (size_t)HALF * K * 2;
;     const size_t tstep = 2 * hstep;
;     const unsigned ldsw = (unsigned)wid * 1024u;
;     const int aoff = lds_byte(wr * 64 + fr, fq * 8), boff = lds_byte(wc * 32 + fr, fq * 8);
;     ...
;         PG8_STAGE(PG8_SB(1, 0), cB + kstep, voffB); PG8_STAGE(PG8_SA(1, 0), cA + kstep, voffA); PG8_STAGE(PG8_SB(1, 1), cB + hstep + kstep, voffB);
;         PG8_WAIT_V(6); PG8_BAR;
.LBB0_497:
	s_add_u32 s8, s4, 0x8000000
	s_addc_u32 s9, s5, 0
	s_add_u32 s10, s4, 0x14000000
	s_addc_u32 s11, s5, 0
	s_lshl_b32 s4, s12, 5
	s_mov_b64 s[12:13], 0x80
	s_and_b32 s21, s4, 0x60
	s_add_i32 m0, s46, 0x18000
	v_lshl_add_u64 v[10:11], v[10:11], 0, s[12:13]
	s_lshl_b32 s20, s16, 13
	s_lshl_b32 s22, s21, 7
	s_waitcnt vmcnt(2)
	s_barrier
	global_load_lds_dwordx4 v[10:11], off
	v_lshl_add_u64 v[8:9], v[8:9], 0, s[12:13]
	s_add_i32 m0, s46, 0x1a000
	s_add_i32 s51, s46, 0x8000
	s_add_i32 s52, s46, 0xa000
	global_load_lds_dwordx4 v[8:9], off
	v_lshl_add_u64 v[4:5], v[4:5], 0, s[12:13]
	s_mov_b32 m0, s51
	s_add_u32 s4, s36, 0x40080
	global_load_lds_dwordx4 v[4:5], off
	v_lshl_add_u64 v[4:5], v[6:7], 0, s[12:13]
	s_mov_b32 m0, s52
	s_addc_u32 s5, s37, 0
	global_load_lds_dwordx4 v[4:5], off
	s_add_i32 m0, s46, 0x1c000
	v_lshl_add_u64 v[4:5], s[4:5], 0, v[154:155]
	global_load_lds_dwordx4 v[4:5], off
	v_lshl_add_u64 v[4:5], s[4:5], 0, v[158:159]
	s_add_i32 m0, s46, 0x1e000
	s_mov_b64 s[4:5], 0x40080
	global_load_lds_dwordx4 v[4:5], off
	v_lshrrev_b32_e32 v5, 1, v1
	v_and_b32_e32 v5, 24, v5
	v_and_b32_e32 v4, 15, v1
	v_lshlrev_b32_e32 v6, 1, v5
	v_lshl_or_b32 v6, v4, 6, v6
	v_lshlrev_b32_e32 v4, 10, v4
	v_lshl_or_b32 v4, s16, 16, v4
	v_or3_b32 v174, v5, v4, s21
	v_lshlrev_b32_e32 v4, 14, v2
	v_and_b32_e32 v4, 0xffff8000, v4
	v_lshl_add_u32 v4, v12, 11, v4
	v_and_b32_e32 v2, 1, v2
	v_lshl_or_b32 v2, v2, 6, v4
	v_lshl_add_u32 v2, v13, 1, v2
	v_lshl_add_u64 v[160:161], v[2:3], 0, s[4:5]
	v_lshlrev_b32_e32 v2, 14, v14
	v_and_b32_e32 v2, 0xffff8000, v2
	v_lshlrev_b32_e32 v1, 2, v1
	v_lshl_add_u32 v2, v15, 11, v2
	v_and_b32_e32 v4, 1, v14
	v_and_b32_e32 v1, 32, v1
	s_waitcnt vmcnt(6)
	v_lshl_or_b32 v2, v4, 6, v2
	v_bitop3_b32 v7, v6, s20, v1 bitop3:0xde
	s_cmpk_lt_u32 s15, 0x100
	v_lshl_add_u32 v2, v16, 1, v2
	s_sext_i32_i8 s35, s14
	v_bitop3_b32 v1, v6, s22, v1 bitop3:0xde
	s_cselect_b64 s[14:15], -1, 0
	s_ashr_i32 s53, s33, 31
	v_lshl_add_u64 v[162:163], v[2:3], 0, s[4:5]
	v_mov_b64_e32 v[164:165], 0x200
	v_mov_b64_e32 v[166:167], 0x1ff
	s_add_i32 s54, 0, 0x10000
	s_add_i32 s55, 0, 0x14000
	v_add_u32_e32 v175, 0, v7
	s_mov_b32 s16, 0x3b808081
	s_barrier
	s_mov_b32 s89, 0
	s_branch .LBB0_500

; #define PG8_STAGE(bufoff, gbase, voff) do { _Pragma("unroll") for (int _i = 0; _i < 2; ++_i) \
;         __builtin_amdgcn_global_load_lds((const unsigned*)((const char*)(gbase) + (voff)[_i]), (PG8_LAS unsigned*)(lds + (bufoff) + ldsw + _i * 8192), 16, 0, 0); } while (0)
; #define PG8_LDA(dst, b, h) do { _Pragma("unroll") for (int m = 0; m < 4; ++m) _Pragma("unroll") for (int k = 0; k < 2; ++k) dst[m][k] = *(const PG8_LAS bf16x8*)(lds + PG8_SA(b, h) + aoff + m * 2048 + k * 1024); } while (0)
; #define PG8_LDB(dst, b, h) do { _Pragma("unroll") for (int n = 0; n < 2; ++n) _Pragma("unroll") for (int k = 0; k < 2; ++k) dst[n][k] = *(const PG8_LAS bf16x8*)(lds + PG8_SB(b, h) + boff + n * 2048 + k * 1024); } while (0)
; #define PG8_MMA(ai, bj, At, Bt) do { __builtin_amdgcn_s_setprio(1); _Pragma("unroll") for (int m = 0; m < 4; ++m) _Pragma("unroll") for (int n = 0; n < 2; ++n) _Pragma("unroll") for (int k = 0; k < 2; ++k) \
;         acc[ai][bj][m][n] = __builtin_amdgcn_mfma_f32_16x16x32_bf16(Bt[n][k], At[m][k], acc[ai][bj][m][n], 0, 0, 0); __builtin_amdgcn_s_setprio(0); } while (0)
; #define PG8_WAIT_V(n) asm volatile("s_waitcnt vmcnt(" #n ")" ::: "memory")
; template <class Epi, class Sched, bool ALIGN_EPI = false, bool SP2 = false>
; __device__ __forceinline__ void gemm_phase(PG8_LAS unsigned char* lds, const Gemm g, const Sched& S, const Epi& E) {
;     ...
;         const bool has_next = S.next(ui + 1, nxt);
;         const char* nA = has_next ? (const char*)g.A + (size_t)nxt.pm * tstep : cA; const char* nB = has_next ? (const char*)g.Bt + (size_t)nxt.pn * tstep : cB;
;         for (int t = 0; t < nt; t += 2) {
;             if constexpr (Epi::MID) { if (t == nt / 2) E.mid(acc, cur, wr, wc, fr, fq); }
;             const bool last = (t == nt - 2);
;             const char* a1 = cA + (size_t)(t + 1) * kstep;
;             const char* a2 = last ? nA : cA + (size_t)(t + 2) * kstep; const char* b2 = last ? nB : cB + (size_t)(t + 2) * kstep;
;             const char* a3 = a2 + kstep; const char* b3 = b2 + kstep;
;             if (last && has_next) S.a_ready(nxt);
;             if constexpr (SP2) {
;             PG8_LDB(B0, 0, 0); PG8_LDB(B1, 0, 1); PG8_SCHED; PG8_LDA(At, 0, 0); PG8_STAGE(PG8_SA(1, 1), a1 + hstep, voffA);
;             PG8_WAIT_V(8); PG8_WAIT_L(0); PG8_BAR; PG8_MMA(0, 0, At, B0); PG8_MMA(0, 1, At, B1); PG8_BAR; PG8_SCHED;
.LBB0_506:
	s_ashr_i32 s23, s22, 31
	s_lshl_b64 s[26:27], s[22:23], 19
	s_add_u32 s26, s43, s26
	s_addc_u32 s27, s44, s27
	s_and_b64 s[28:29], s[4:5], exec
	s_cselect_b32 s23, s27, s31
	s_cselect_b32 s56, s26, s30
	s_ashr_i32 s21, s20, 31
	s_lshl_b64 s[28:29], s[20:21], 19
	s_add_u32 s28, s41, s28
	s_addc_u32 s29, s42, s29
	s_and_b64 s[38:39], s[4:5], exec
	s_cselect_b32 s21, s29, s37
	s_cselect_b32 s57, s28, s36
	s_lshl_b32 s34, s34, 18
	s_lshl_b32 s35, s35, 8
	s_add_i32 s34, s34, s35
	s_add_u32 s58, s36, 0x100
	v_add_u32_e32 v168, s34, v174
	v_lshl_add_u64 v[170:171], s[30:31], 0, v[160:161]
	v_lshl_add_u64 v[172:173], s[30:31], 0, v[162:163]
	s_addc_u32 s59, s37, 0
	s_mov_b32 s60, -2
	s_mov_b64 s[34:35], 0
	v_add_u32_e32 v2, s54, v1
	ds_read_b128 v[134:137], v2
	ds_read_b128 v[138:141], v2 offset:1024
	ds_read_b128 v[142:145], v2 offset:2048
	ds_read_b128 v[146:149], v2 offset:3072
	v_add_u32_e32 v2, s55, v1
	s_add_u32 s36, s30, s34
	ds_read_b128 v[176:179], v2
	ds_read_b128 v[180:183], v2 offset:1024
	ds_read_b128 v[184:187], v2 offset:2048
	ds_read_b128 v[188:191], v2 offset:3072
	s_addc_u32 s37, s31, s35
	s_add_u32 s36, s36, 0x100
	s_addc_u32 s37, s37, 0
	s_add_u32 s61, s58, s34
	s_addc_u32 s62, s59, s35
	s_cmpk_eq_i32 s34, 0x700
	s_cselect_b32 s39, s23, s37
	s_cselect_b32 s38, s56, s36
	s_cselect_b32 s37, s21, s62
	s_cselect_b32 s36, s57, s61
	v_lshl_add_u64 v[4:5], v[170:171], 0, s[34:35]
	s_add_i32 m0, s46, 0xc000
	ds_read_b128 v[192:195], v175
	ds_read_b128 v[196:199], v175 offset:1024
	ds_read_b128 v[200:203], v175 offset:2048
	ds_read_b128 v[204:207], v175 offset:3072
	ds_read_b128 v[208:211], v175 offset:4096
	ds_read_b128 v[212:215], v175 offset:5120
	ds_read_b128 v[216:219], v175 offset:6144
	ds_read_b128 v[220:223], v175 offset:7168
	global_load_lds_dwordx4 v[4:5], off
	v_lshl_add_u64 v[4:5], v[172:173], 0, s[34:35]
	s_add_i32 m0, s46, 0xe000
	s_nop 0
	global_load_lds_dwordx4 v[4:5], off
	s_cmp_eq_u32 s89, 0
	s_cbranch_scc1 .Lrw_p4_0_a
	s_waitcnt vmcnt(40)
	s_branch .Lrw_p4_0_z

; #define PG8_STAGE(bufoff, gbase, voff) do { _Pragma("unroll") for (int _i = 0; _i < 2; ++_i) \
;         __builtin_amdgcn_global_load_lds((const unsigned*)((const char*)(gbase) + (voff)[_i]), (PG8_LAS unsigned*)(lds + (bufoff) + ldsw + _i * 8192), 16, 0, 0); } while (0)
; #define PG8_LDA(dst, b, h) do { _Pragma("unroll") for (int m = 0; m < 4; ++m) _Pragma("unroll") for (int k = 0; k < 2; ++k) dst[m][k] = *(const PG8_LAS bf16x8*)(lds + PG8_SA(b, h) + aoff + m * 2048 + k * 1024); } while (0)
; #define PG8_MMA(ai, bj, At, Bt) do { __builtin_amdgcn_s_setprio(1); _Pragma("unroll") for (int m = 0; m < 4; ++m) _Pragma("unroll") for (int n = 0; n < 2; ++n) _Pragma("unroll") for (int k = 0; k < 2; ++k) \
;         acc[ai][bj][m][n] = __builtin_amdgcn_mfma_f32_16x16x32_bf16(Bt[n][k], At[m][k], acc[ai][bj][m][n], 0, 0, 0); __builtin_amdgcn_s_setprio(0); } while (0)
; #define PG8_WAIT_V(n) asm volatile("s_waitcnt vmcnt(" #n ")" ::: "memory")
; #define PG8_WAIT_L(n) asm volatile("s_waitcnt lgkmcnt(" #n ")" ::: "memory")
; #define PG8_BAR __builtin_amdgcn_s_barrier()
; #define PG8_SCHED __builtin_amdgcn_sched_barrier(0)
; template <class Epi, class Sched, bool ALIGN_EPI = false, bool SP2 = false>
; __device__ __forceinline__ void gemm_phase(PG8_LAS unsigned char* lds, const Gemm g, const Sched& S, const Epi& E) {
;     ...
;             PG8_WAIT_V(8); PG8_WAIT_L(0); PG8_BAR; PG8_MMA(0, 0, At, B0); PG8_MMA(0, 1, At, B1); PG8_BAR; PG8_SCHED;
;             PG8_LDA(At, 0, 1); PG8_STAGE(PG8_SB(0, 0), b2, voffB); PG8_STAGE(PG8_SB(0, 1), b2 + hstep, voffB); PG8_STAGE(PG8_SA(0, 0), a2, voffA);
.Lrw_p4_0_z:
	s_waitcnt lgkmcnt(0)
	s_barrier
	s_setprio 1
	s_waitcnt lgkmcnt(0)
	v_mfma_f32_16x16x32_bf16 v[130:133], v[134:137], v[192:195], 0
	v_mfma_f32_16x16x32_bf16 v[126:129], v[142:145], v[192:195], 0
	v_mfma_f32_16x16x32_bf16 v[114:117], v[134:137], v[200:203], 0
	v_mfma_f32_16x16x32_bf16 v[110:113], v[142:145], v[200:203], 0
	v_mfma_f32_16x16x32_bf16 v[98:101], v[134:137], v[208:211], 0
	v_mfma_f32_16x16x32_bf16 v[94:97], v[142:145], v[208:211], 0
	v_mfma_f32_16x16x32_bf16 v[82:85], v[134:137], v[216:219], 0
	v_mfma_f32_16x16x32_bf16 v[78:81], v[142:145], v[216:219], 0
	v_mfma_f32_16x16x32_bf16 v[130:133], v[138:141], v[196:199], v[130:133]
	v_mfma_f32_16x16x32_bf16 v[126:129], v[146:149], v[196:199], v[126:129]
	v_mfma_f32_16x16x32_bf16 v[114:117], v[138:141], v[204:207], v[114:117]
	v_mfma_f32_16x16x32_bf16 v[110:113], v[146:149], v[204:207], v[110:113]
	v_mfma_f32_16x16x32_bf16 v[98:101], v[138:141], v[212:215], v[98:101]
	v_mfma_f32_16x16x32_bf16 v[94:97], v[146:149], v[212:215], v[94:97]
	v_mfma_f32_16x16x32_bf16 v[82:85], v[138:141], v[220:223], v[82:85]
	v_mfma_f32_16x16x32_bf16 v[78:81], v[146:149], v[220:223], v[78:81]
	s_setprio 0
	s_setprio 1
	v_mfma_f32_16x16x32_bf16 v[122:125], v[176:179], v[192:195], 0
	v_mfma_f32_16x16x32_bf16 v[118:121], v[184:187], v[192:195], 0
	v_mfma_f32_16x16x32_bf16 v[106:109], v[176:179], v[200:203], 0
	v_mfma_f32_16x16x32_bf16 v[102:105], v[184:187], v[200:203], 0
	v_mfma_f32_16x16x32_bf16 v[90:93], v[176:179], v[208:211], 0
	v_mfma_f32_16x16x32_bf16 v[86:89], v[184:187], v[208:211], 0
	v_mfma_f32_16x16x32_bf16 v[74:77], v[176:179], v[216:219], 0
	v_mfma_f32_16x16x32_bf16 v[70:73], v[184:187], v[216:219], 0
	v_mfma_f32_16x16x32_bf16 v[122:125], v[180:183], v[196:199], v[122:125]
	v_mfma_f32_16x16x32_bf16 v[118:121], v[188:191], v[196:199], v[118:121]
	v_mfma_f32_16x16x32_bf16 v[106:109], v[180:183], v[204:207], v[106:109]
	v_mfma_f32_16x16x32_bf16 v[102:105], v[188:191], v[204:207], v[102:105]
	v_mfma_f32_16x16x32_bf16 v[90:93], v[180:183], v[212:215], v[90:93]
	v_mfma_f32_16x16x32_bf16 v[86:89], v[188:191], v[212:215], v[86:89]
	v_mfma_f32_16x16x32_bf16 v[74:77], v[180:183], v[220:223], v[74:77]
	v_mfma_f32_16x16x32_bf16 v[70:73], v[188:191], v[220:223], v[70:73]
	s_setprio 0
	s_barrier
	s_add_i32 s61, s54, s45
	v_lshl_add_u64 v[150:151], s[36:37], 0, v[154:155]
	s_mov_b32 m0, s61
	ds_read_b128 v[192:195], v175 offset:16384
	ds_read_b128 v[196:199], v175 offset:17408
	ds_read_b128 v[200:203], v175 offset:18432
	ds_read_b128 v[204:207], v175 offset:19456
	ds_read_b128 v[208:211], v175 offset:20480
	ds_read_b128 v[212:215], v175 offset:21504
	ds_read_b128 v[216:219], v175 offset:22528
	ds_read_b128 v[220:223], v175 offset:23552
	global_load_lds_dwordx4 v[150:151], off
	s_add_i32 m0, s61, 0x2000
	s_add_u32 s62, s36, 0x40000
	v_lshl_add_u64 v[224:225], s[36:37], 0, v[158:159]
	s_addc_u32 s63, s37, 0
	s_add_i32 s61, s55, s45
	global_load_lds_dwordx4 v[224:225], off
	v_lshl_add_u64 v[4:5], s[62:63], 0, v[154:155]
	s_mov_b32 m0, s61
	v_lshl_add_u64 v[226:227], s[38:39], 0, v[152:153]
	global_load_lds_dwordx4 v[4:5], off
	v_lshl_add_u64 v[4:5], s[62:63], 0, v[158:159]
	s_add_i32 m0, s61, 0x2000
	v_lshl_add_u64 v[228:229], s[38:39], 0, v[156:157]
	global_load_lds_dwordx4 v[4:5], off
	s_mov_b32 m0, s46
	s_nop 0
	global_load_lds_dwordx4 v[226:227], off
	s_mov_b32 m0, s47
	s_nop 0
	global_load_lds_dwordx4 v[228:229], off
	s_cmp_eq_u32 s89, 0
	s_cbranch_scc1 .Lrw_p4_1_a
	s_waitcnt vmcnt(40)
	s_branch .Lrw_p4_1_z

; #define PG8_STAGE(bufoff, gbase, voff) do { _Pragma("unroll") for (int _i = 0; _i < 2; ++_i) \
;         __builtin_amdgcn_global_load_lds((const unsigned*)((const char*)(gbase) + (voff)[_i]), (PG8_LAS unsigned*)(lds + (bufoff) + ldsw + _i * 8192), 16, 0, 0); } while (0)
; #define PG8_LDA(dst, b, h) do { _Pragma("unroll") for (int m = 0; m < 4; ++m) _Pragma("unroll") for (int k = 0; k < 2; ++k) dst[m][k] = *(const PG8_LAS bf16x8*)(lds + PG8_SA(b, h) + aoff + m * 2048 + k * 1024); } while (0)
; #define PG8_LDB(dst, b, h) do { _Pragma("unroll") for (int n = 0; n < 2; ++n) _Pragma("unroll") for (int k = 0; k < 2; ++k) dst[n][k] = *(const PG8_LAS bf16x8*)(lds + PG8_SB(b, h) + boff + n * 2048 + k * 1024); } while (0)
; #define PG8_MMA(ai, bj, At, Bt) do { __builtin_amdgcn_s_setprio(1); _Pragma("unroll") for (int m = 0; m < 4; ++m) _Pragma("unroll") for (int n = 0; n < 2; ++n) _Pragma("unroll") for (int k = 0; k < 2; ++k) \
;         acc[ai][bj][m][n] = __builtin_amdgcn_mfma_f32_16x16x32_bf16(Bt[n][k], At[m][k], acc[ai][bj][m][n], 0, 0, 0); __builtin_amdgcn_s_setprio(0); } while (0)
; #define PG8_WAIT_V(n) asm volatile("s_waitcnt vmcnt(" #n ")" ::: "memory")
; #define PG8_WAIT_L(n) asm volatile("s_waitcnt lgkmcnt(" #n ")" ::: "memory")
; #define PG8_BAR __builtin_amdgcn_s_barrier()
; #define PG8_SCHED __builtin_amdgcn_sched_barrier(0)
; template <class Epi, class Sched, bool ALIGN_EPI = false, bool SP2 = false>
; __device__ __forceinline__ void gemm_phase(PG8_LAS unsigned char* lds, const Gemm g, const Sched& S, const Epi& E) {
;     ...
;             PG8_WAIT_V(8); PG8_WAIT_L(0); PG8_BAR; PG8_MMA(1, 0, At, B0); PG8_MMA(1, 1, At, B1); PG8_BAR; PG8_SCHED;
;             PG8_LDB(B0, 1, 0); PG8_LDB(B1, 1, 1); PG8_SCHED; PG8_LDA(At, 1, 0); PG8_STAGE(PG8_SA(0, 1), a2 + hstep, voffA);
;             PG8_WAIT_V(8); PG8_WAIT_L(0); PG8_BAR; PG8_MMA(0, 0, At, B0); PG8_MMA(0, 1, At, B1); PG8_BAR; PG8_SCHED;
.Lrw_p4_1_z:
	s_waitcnt lgkmcnt(0)
	s_barrier
	s_setprio 1
	s_waitcnt lgkmcnt(0)
	v_mfma_f32_16x16x32_bf16 v[66:69], v[134:137], v[192:195], 0
	v_mfma_f32_16x16x32_bf16 v[62:65], v[142:145], v[192:195], 0
	v_mfma_f32_16x16x32_bf16 v[50:53], v[134:137], v[200:203], 0
	v_mfma_f32_16x16x32_bf16 v[46:49], v[142:145], v[200:203], 0
	v_mfma_f32_16x16x32_bf16 v[34:37], v[134:137], v[208:211], 0
	v_mfma_f32_16x16x32_bf16 v[30:33], v[142:145], v[208:211], 0
	v_mfma_f32_16x16x32_bf16 v[18:21], v[134:137], v[216:219], 0
	v_mfma_f32_16x16x32_bf16 v[14:17], v[142:145], v[216:219], 0
	v_mfma_f32_16x16x32_bf16 v[66:69], v[138:141], v[196:199], v[66:69]
	v_mfma_f32_16x16x32_bf16 v[62:65], v[146:149], v[196:199], v[62:65]
	v_mfma_f32_16x16x32_bf16 v[50:53], v[138:141], v[204:207], v[50:53]
	v_mfma_f32_16x16x32_bf16 v[46:49], v[146:149], v[204:207], v[46:49]
	v_mfma_f32_16x16x32_bf16 v[34:37], v[138:141], v[212:215], v[34:37]
	v_mfma_f32_16x16x32_bf16 v[30:33], v[146:149], v[212:215], v[30:33]
	v_mfma_f32_16x16x32_bf16 v[18:21], v[138:141], v[220:223], v[18:21]
	v_mfma_f32_16x16x32_bf16 v[14:17], v[146:149], v[220:223], v[14:17]
	s_setprio 0
	s_setprio 1
	v_mfma_f32_16x16x32_bf16 v[58:61], v[176:179], v[192:195], 0
	v_mfma_f32_16x16x32_bf16 v[54:57], v[184:187], v[192:195], 0
	v_mfma_f32_16x16x32_bf16 v[42:45], v[176:179], v[200:203], 0
	v_mfma_f32_16x16x32_bf16 v[38:41], v[184:187], v[200:203], 0
	v_mfma_f32_16x16x32_bf16 v[26:29], v[176:179], v[208:211], 0
	v_mfma_f32_16x16x32_bf16 v[22:25], v[184:187], v[208:211], 0
	v_mfma_f32_16x16x32_bf16 v[10:13], v[176:179], v[216:219], 0
	v_mfma_f32_16x16x32_bf16 v[4:7], v[184:187], v[216:219], 0
	v_mfma_f32_16x16x32_bf16 v[58:61], v[180:183], v[196:199], v[58:61]
	v_mfma_f32_16x16x32_bf16 v[54:57], v[188:191], v[196:199], v[54:57]
	v_mfma_f32_16x16x32_bf16 v[42:45], v[180:183], v[204:207], v[42:45]
	v_mfma_f32_16x16x32_bf16 v[38:41], v[188:191], v[204:207], v[38:41]
	v_mfma_f32_16x16x32_bf16 v[26:29], v[180:183], v[212:215], v[26:29]
	v_mfma_f32_16x16x32_bf16 v[22:25], v[188:191], v[212:215], v[22:25]
	v_mfma_f32_16x16x32_bf16 v[10:13], v[180:183], v[220:223], v[10:13]
	v_mfma_f32_16x16x32_bf16 v[4:7], v[188:191], v[220:223], v[4:7]
	s_setprio 0
	s_barrier
	s_add_i32 s61, 0, 0x18000
	v_add_u32_e32 v2, s61, v1
	s_add_i32 s62, 0, 0x1c000
	ds_read_b128 v[134:137], v2
	ds_read_b128 v[138:141], v2 offset:1024
	ds_read_b128 v[142:145], v2 offset:2048
	ds_read_b128 v[146:149], v2 offset:3072
	v_add_u32_e32 v2, s62, v1
	ds_read_b128 v[176:179], v2
	ds_read_b128 v[180:183], v2 offset:1024
	ds_read_b128 v[184:187], v2 offset:2048
	ds_read_b128 v[188:191], v2 offset:3072
	s_add_u32 s38, s38, 0x40000
	s_addc_u32 s39, s39, 0
	s_mov_b32 m0, s48
	v_lshl_add_u64 v[8:9], s[38:39], 0, v[152:153]
	ds_read_b128 v[192:195], v175 offset:32768
	ds_read_b128 v[196:199], v175 offset:33792
	ds_read_b128 v[200:203], v175 offset:34816
	ds_read_b128 v[204:207], v175 offset:35840
	ds_read_b128 v[208:211], v175 offset:36864
	ds_read_b128 v[212:215], v175 offset:37888
	ds_read_b128 v[216:219], v175 offset:38912
	ds_read_b128 v[220:223], v175 offset:39936
	global_load_lds_dwordx4 v[8:9], off
	v_lshl_add_u64 v[8:9], s[38:39], 0, v[156:157]
	s_mov_b32 m0, s49
	s_nop 0
	global_load_lds_dwordx4 v[8:9], off
	s_waitcnt vmcnt(8)
	s_waitcnt lgkmcnt(0)
	s_barrier
	s_setprio 1
	s_waitcnt lgkmcnt(0)
	v_mfma_f32_16x16x32_bf16 v[130:133], v[134:137], v[192:195], v[130:133]
	v_mfma_f32_16x16x32_bf16 v[126:129], v[142:145], v[192:195], v[126:129]
	v_mfma_f32_16x16x32_bf16 v[114:117], v[134:137], v[200:203], v[114:117]
	v_mfma_f32_16x16x32_bf16 v[110:113], v[142:145], v[200:203], v[110:113]
	v_mfma_f32_16x16x32_bf16 v[98:101], v[134:137], v[208:211], v[98:101]
	v_mfma_f32_16x16x32_bf16 v[94:97], v[142:145], v[208:211], v[94:97]
	v_mfma_f32_16x16x32_bf16 v[82:85], v[134:137], v[216:219], v[82:85]
	v_mfma_f32_16x16x32_bf16 v[78:81], v[142:145], v[216:219], v[78:81]
	v_mfma_f32_16x16x32_bf16 v[130:133], v[138:141], v[196:199], v[130:133]
	v_mfma_f32_16x16x32_bf16 v[126:129], v[146:149], v[196:199], v[126:129]
	v_mfma_f32_16x16x32_bf16 v[114:117], v[138:141], v[204:207], v[114:117]
	v_mfma_f32_16x16x32_bf16 v[110:113], v[146:149], v[204:207], v[110:113]
	v_mfma_f32_16x16x32_bf16 v[98:101], v[138:141], v[212:215], v[98:101]
	v_mfma_f32_16x16x32_bf16 v[94:97], v[146:149], v[212:215], v[94:97]
	v_mfma_f32_16x16x32_bf16 v[82:85], v[138:141], v[220:223], v[82:85]
	v_mfma_f32_16x16x32_bf16 v[78:81], v[146:149], v[220:223], v[78:81]
	s_setprio 0
	s_setprio 1
	v_mfma_f32_16x16x32_bf16 v[122:125], v[176:179], v[192:195], v[122:125]
	v_mfma_f32_16x16x32_bf16 v[118:121], v[184:187], v[192:195], v[118:121]
	v_mfma_f32_16x16x32_bf16 v[106:109], v[176:179], v[200:203], v[106:109]
	v_mfma_f32_16x16x32_bf16 v[102:105], v[184:187], v[200:203], v[102:105]
	v_mfma_f32_16x16x32_bf16 v[90:93], v[176:179], v[208:211], v[90:93]
	v_mfma_f32_16x16x32_bf16 v[86:89], v[184:187], v[208:211], v[86:89]
	v_mfma_f32_16x16x32_bf16 v[74:77], v[176:179], v[216:219], v[74:77]
	v_mfma_f32_16x16x32_bf16 v[70:73], v[184:187], v[216:219], v[70:73]
	v_mfma_f32_16x16x32_bf16 v[122:125], v[180:183], v[196:199], v[122:125]
	v_mfma_f32_16x16x32_bf16 v[118:121], v[188:191], v[196:199], v[118:121]
	v_mfma_f32_16x16x32_bf16 v[106:109], v[180:183], v[204:207], v[106:109]
	v_mfma_f32_16x16x32_bf16 v[102:105], v[188:191], v[204:207], v[102:105]
	v_mfma_f32_16x16x32_bf16 v[90:93], v[180:183], v[212:215], v[90:93]
	v_mfma_f32_16x16x32_bf16 v[86:89], v[188:191], v[212:215], v[86:89]
	v_mfma_f32_16x16x32_bf16 v[74:77], v[180:183], v[220:223], v[74:77]
	v_mfma_f32_16x16x32_bf16 v[70:73], v[188:191], v[220:223], v[70:73]
	s_setprio 0
	s_barrier
; #define PG8_STAGE(bufoff, gbase, voff) do { _Pragma("unroll") for (int _i = 0; _i < 2; ++_i) \
;         __builtin_amdgcn_global_load_lds((const unsigned*)((const char*)(gbase) + (voff)[_i]), (PG8_LAS unsigned*)(lds + (bufoff) + ldsw + _i * 8192), 16, 0, 0); } while (0)
; #define PG8_LDA(dst, b, h) do { _Pragma("unroll") for (int m = 0; m < 4; ++m) _Pragma("unroll") for (int k = 0; k < 2; ++k) dst[m][k] = *(const PG8_LAS bf16x8*)(lds + PG8_SA(b, h) + aoff + m * 2048 + k * 1024); } while (0)
; #define PG8_MMA(ai, bj, At, Bt) do { __builtin_amdgcn_s_setprio(1); _Pragma("unroll") for (int m = 0; m < 4; ++m) _Pragma("unroll") for (int n = 0; n < 2; ++n) _Pragma("unroll") for (int k = 0; k < 2; ++k) \
;         acc[ai][bj][m][n] = __builtin_amdgcn_mfma_f32_16x16x32_bf16(Bt[n][k], At[m][k], acc[ai][bj][m][n], 0, 0, 0); __builtin_amdgcn_s_setprio(0); } while (0)
; #define PG8_WAIT_V(n) asm volatile("s_waitcnt vmcnt(" #n ")" ::: "memory")
; #define PG8_WAIT_L(n) asm volatile("s_waitcnt lgkmcnt(" #n ")" ::: "memory")
; #define PG8_BAR __builtin_amdgcn_s_barrier()
; #define PG8_SCHED __builtin_amdgcn_sched_barrier(0)
; template <class Epi, class Sched, bool ALIGN_EPI = false, bool SP2 = false>
; __device__ __forceinline__ void gemm_phase(PG8_LAS unsigned char* lds, const Gemm g, const Sched& S, const Epi& E) {
;     ...
;             PG8_LDA(At, 1, 1); PG8_STAGE(PG8_SB(1, 0), b3, voffB); PG8_STAGE(PG8_SB(1, 1), b3 + hstep, voffB); PG8_STAGE(PG8_SA(1, 0), a3, voffA);
;             PG8_WAIT_V(8); PG8_WAIT_L(0); PG8_BAR; PG8_MMA(1, 0, At, B0); PG8_MMA(1, 1, At, B1); PG8_BAR; PG8_SCHED;
	s_add_i32 s38, s61, s45
	v_lshl_add_u64 v[8:9], v[150:151], 0, s[12:13]
	s_mov_b32 m0, s38
	ds_read_b128 v[192:195], v175 offset:49152
	ds_read_b128 v[196:199], v175 offset:50176
	ds_read_b128 v[200:203], v175 offset:51200
	ds_read_b128 v[204:207], v175 offset:52224
	ds_read_b128 v[208:211], v175 offset:53248
	ds_read_b128 v[212:215], v175 offset:54272
	ds_read_b128 v[216:219], v175 offset:55296
	ds_read_b128 v[220:223], v175 offset:56320
	global_load_lds_dwordx4 v[8:9], off
	s_add_i32 m0, s38, 0x2000
	s_add_u32 s36, s36, 0x40080
	v_lshl_add_u64 v[8:9], v[224:225], 0, s[12:13]
	s_addc_u32 s37, s37, 0
	s_add_i32 s38, s62, s45
	global_load_lds_dwordx4 v[8:9], off
	v_lshl_add_u64 v[8:9], s[36:37], 0, v[154:155]
	s_mov_b32 m0, s38
	s_nop 0
	global_load_lds_dwordx4 v[8:9], off
	v_lshl_add_u64 v[8:9], s[36:37], 0, v[158:159]
	s_add_i32 m0, s38, 0x2000
	s_nop 0
	global_load_lds_dwordx4 v[8:9], off
	v_lshl_add_u64 v[8:9], v[226:227], 0, s[12:13]
	s_mov_b32 m0, s51
	s_nop 0
	global_load_lds_dwordx4 v[8:9], off
	v_lshl_add_u64 v[8:9], v[228:229], 0, s[12:13]
	s_mov_b32 m0, s52
	s_nop 0
	global_load_lds_dwordx4 v[8:9], off
	s_waitcnt vmcnt(8)
	s_waitcnt lgkmcnt(0)
	s_barrier
	s_setprio 1
	s_waitcnt lgkmcnt(0)
	v_mfma_f32_16x16x32_bf16 v[66:69], v[134:137], v[192:195], v[66:69]
	v_mfma_f32_16x16x32_bf16 v[62:65], v[142:145], v[192:195], v[62:65]
	v_mfma_f32_16x16x32_bf16 v[50:53], v[134:137], v[200:203], v[50:53]
	v_mfma_f32_16x16x32_bf16 v[46:49], v[142:145], v[200:203], v[46:49]
	v_mfma_f32_16x16x32_bf16 v[34:37], v[134:137], v[208:211], v[34:37]
	v_mfma_f32_16x16x32_bf16 v[30:33], v[142:145], v[208:211], v[30:33]
	v_mfma_f32_16x16x32_bf16 v[18:21], v[134:137], v[216:219], v[18:21]
	v_mfma_f32_16x16x32_bf16 v[14:17], v[142:145], v[216:219], v[14:17]
	v_mfma_f32_16x16x32_bf16 v[66:69], v[138:141], v[196:199], v[66:69]
	v_mfma_f32_16x16x32_bf16 v[62:65], v[146:149], v[196:199], v[62:65]
	v_mfma_f32_16x16x32_bf16 v[50:53], v[138:141], v[204:207], v[50:53]
	v_mfma_f32_16x16x32_bf16 v[46:49], v[146:149], v[204:207], v[46:49]
	v_mfma_f32_16x16x32_bf16 v[34:37], v[138:141], v[212:215], v[34:37]
	v_mfma_f32_16x16x32_bf16 v[30:33], v[146:149], v[212:215], v[30:33]
	v_mfma_f32_16x16x32_bf16 v[18:21], v[138:141], v[220:223], v[18:21]
	v_mfma_f32_16x16x32_bf16 v[14:17], v[146:149], v[220:223], v[14:17]
	s_setprio 0
	s_setprio 1
	v_mfma_f32_16x16x32_bf16 v[58:61], v[176:179], v[192:195], v[58:61]
	v_mfma_f32_16x16x32_bf16 v[54:57], v[184:187], v[192:195], v[54:57]
	v_mfma_f32_16x16x32_bf16 v[42:45], v[176:179], v[200:203], v[42:45]
	v_mfma_f32_16x16x32_bf16 v[38:41], v[184:187], v[200:203], v[38:41]
	v_mfma_f32_16x16x32_bf16 v[26:29], v[176:179], v[208:211], v[26:29]
	v_mfma_f32_16x16x32_bf16 v[22:25], v[184:187], v[208:211], v[22:25]
	v_mfma_f32_16x16x32_bf16 v[8:11], v[176:179], v[216:219], v[10:13]
	v_mfma_f32_16x16x32_bf16 v[4:7], v[184:187], v[216:219], v[4:7]
	v_mfma_f32_16x16x32_bf16 v[58:61], v[180:183], v[196:199], v[58:61]
	v_mfma_f32_16x16x32_bf16 v[54:57], v[188:191], v[196:199], v[54:57]
	v_mfma_f32_16x16x32_bf16 v[42:45], v[180:183], v[204:207], v[42:45]
	v_mfma_f32_16x16x32_bf16 v[38:41], v[188:191], v[204:207], v[38:41]
	v_mfma_f32_16x16x32_bf16 v[26:29], v[180:183], v[212:215], v[26:29]
	v_mfma_f32_16x16x32_bf16 v[22:25], v[188:191], v[212:215], v[22:25]
	v_mfma_f32_16x16x32_bf16 v[10:13], v[180:183], v[220:223], v[8:11]
	v_mfma_f32_16x16x32_bf16 v[6:9], v[188:191], v[220:223], v[4:7]
	s_setprio 0
	s_barrier
	s_add_i32 s60, s60, 2
	s_add_u32 s34, s34, 0x100
	s_addc_u32 s35, s35, 0
	s_cmp_gt_u32 s60, 13
	s_cbranch_scc1 .LBB0_510
	s_branch .LBB0_508

; __device__ __forceinline__ unsigned cvt_pk_bf16(float lo, float hi) { unsigned r; asm volatile("v_cvt_pk_bf16_f32 %0, %1, %2" : "=v"(r) : "v"(lo), "v"(hi)); return r; }
;     static __device__ __forceinline__ float ub(unsigned w, int k) { return (float)((w >> (8 * k)) & 0xffu); }
;     __device__ __forceinline__ void operator()(const f32x4 (&acc)[2][2][4][2], const Unit& u, int wr, int wc, int fr, int fq) const {
;         unsigned off0 = (unsigned)((u.pm * BM + wr * 64 + fr) * 1024 + u.pn * BM + wc * 32 + 8 * fq); const float s = 1.0f / 255.0f;
;         asm volatile("" : "+v"(off0));
; #pragma unroll
;         for (int ai = 0; ai < 2; ++ai)
; #pragma unroll
;             for (int m = 0; m < 4; ++m) { const unsigned off = off0 + (unsigned)((ai * HALF + m * 16) * 1024);
; #pragma unroll
;                 for (int bj = 0; bj < 2; ++bj) { const u32x4 g = *(const u32x4*)(AB + (off + bj * HALF)); const f32x4 v0 = acc[ai][bj][m][0] * s, v1 = acc[ai][bj][m][1] * s;
;                     u32x4 w; w.x = cvt_pk_bf16(v0[0] * ub(g.x, 1), v0[1] * ub(g.x, 3)); w.y = cvt_pk_bf16(v0[2] * ub(g.y, 1), v0[3] * ub(g.y, 3));
;                     w.z = cvt_pk_bf16(v1[0] * ub(g.z, 1), v1[1] * ub(g.z, 3)); w.w = cvt_pk_bf16(v1[2] * ub(g.w, 1), v1[3] * ub(g.w, 3));
;                     *(u32x4*)((unsigned char*)MG + 2u * (off + bj * HALF)) = w; } }
.LBB0_512:
	s_mov_b32 s89, 1
	v_lshlrev_b32_e32 v2, 1, v168
	v_add_u32_e32 v240, 0x8000, v2
	v_add_u32_e32 v241, 0x10000, v2
	v_add_u32_e32 v242, 0x18000, v2
	v_add_u32_e32 v243, 0x40000, v2
	v_add_u32_e32 v244, 0x48000, v2
	v_add_u32_e32 v245, 0x50000, v2
	v_add_u32_e32 v246, 0x58000, v2
	global_load_dwordx4 v[176:179], v2, s[10:11] offset:0
	global_load_dwordx4 v[180:183], v2, s[10:11] offset:256
	global_load_dwordx4 v[184:187], v240, s[10:11] offset:0
	global_load_dwordx4 v[188:191], v240, s[10:11] offset:256
	global_load_dwordx4 v[192:195], v241, s[10:11] offset:0
	global_load_dwordx4 v[196:199], v241, s[10:11] offset:256
	global_load_dwordx4 v[200:203], v242, s[10:11] offset:0
	global_load_dwordx4 v[204:207], v242, s[10:11] offset:256
	global_load_dwordx4 v[208:211], v243, s[10:11] offset:0
	global_load_dwordx4 v[212:215], v243, s[10:11] offset:256
	global_load_dwordx4 v[216:219], v244, s[10:11] offset:0
	global_load_dwordx4 v[220:223], v244, s[10:11] offset:256
	global_load_dwordx4 v[224:227], v245, s[10:11] offset:0
	global_load_dwordx4 v[228:231], v245, s[10:11] offset:256
	global_load_dwordx4 v[232:235], v246, s[10:11] offset:0
	global_load_dwordx4 v[236:239], v246, s[10:11] offset:256
	s_waitcnt vmcnt(15)
	v_pk_mul_f32 v[130:131], v[130:131], s[16:17] op_sel_hi:[1,0]
	v_pk_mul_f32 v[132:133], v[132:133], s[16:17] op_sel_hi:[1,0]
	v_pk_mul_f32 v[126:127], v[126:127], s[16:17] op_sel_hi:[1,0]
	v_pk_mul_f32 v[128:129], v[128:129], s[16:17] op_sel_hi:[1,0]
	v_cvt_f32_ubyte1_e32 v134, v176
	v_cvt_f32_ubyte3_e32 v135, v176
	v_cvt_f32_ubyte1_e32 v136, v177
	v_cvt_f32_ubyte3_e32 v137, v177
	v_cvt_f32_ubyte1_e32 v138, v178
	v_cvt_f32_ubyte3_e32 v139, v178
	v_cvt_f32_ubyte1_e32 v140, v179
	v_cvt_f32_ubyte3_e32 v141, v179
	v_mul_f32_e32 v130, v130, v134
	v_mul_f32_e32 v131, v131, v135
	v_mul_f32_e32 v132, v132, v136
	v_mul_f32_e32 v133, v133, v137
	v_mul_f32_e32 v126, v126, v138
	v_mul_f32_e32 v127, v127, v139
	v_mul_f32_e32 v128, v128, v140
	v_mul_f32_e32 v129, v129, v141
	v_cvt_pk_bf16_f32 v176, v130, v131
	v_cvt_pk_bf16_f32 v177, v132, v133
	v_cvt_pk_bf16_f32 v178, v126, v127
	v_cvt_pk_bf16_f32 v179, v128, v129
	global_store_dwordx4 v2, v[176:179], s[8:9] offset:0
	s_waitcnt vmcnt(15)
	v_pk_mul_f32 v[122:123], v[122:123], s[16:17] op_sel_hi:[1,0]
	v_pk_mul_f32 v[124:125], v[124:125], s[16:17] op_sel_hi:[1,0]
	v_pk_mul_f32 v[118:119], v[118:119], s[16:17] op_sel_hi:[1,0]
	v_pk_mul_f32 v[120:121], v[120:121], s[16:17] op_sel_hi:[1,0]
	v_cvt_f32_ubyte1_e32 v134, v180
	v_cvt_f32_ubyte3_e32 v135, v180
	v_cvt_f32_ubyte1_e32 v136, v181
	v_cvt_f32_ubyte3_e32 v137, v181
	v_cvt_f32_ubyte1_e32 v138, v182
	v_cvt_f32_ubyte3_e32 v139, v182
	v_cvt_f32_ubyte1_e32 v140, v183
	v_cvt_f32_ubyte3_e32 v141, v183
	v_mul_f32_e32 v122, v122, v134
	v_mul_f32_e32 v123, v123, v135
	v_mul_f32_e32 v124, v124, v136
	v_mul_f32_e32 v125, v125, v137
	v_mul_f32_e32 v118, v118, v138
	v_mul_f32_e32 v119, v119, v139
	v_mul_f32_e32 v120, v120, v140
	v_mul_f32_e32 v121, v121, v141
	v_cvt_pk_bf16_f32 v180, v122, v123
	v_cvt_pk_bf16_f32 v181, v124, v125
	v_cvt_pk_bf16_f32 v182, v118, v119
	v_cvt_pk_bf16_f32 v183, v120, v121
	global_store_dwordx4 v2, v[180:183], s[8:9] offset:256
	s_waitcnt vmcnt(15)
	v_pk_mul_f32 v[114:115], v[114:115], s[16:17] op_sel_hi:[1,0]
	v_pk_mul_f32 v[116:117], v[116:117], s[16:17] op_sel_hi:[1,0]
	v_pk_mul_f32 v[110:111], v[110:111], s[16:17] op_sel_hi:[1,0]
	v_pk_mul_f32 v[112:113], v[112:113], s[16:17] op_sel_hi:[1,0]
	v_cvt_f32_ubyte1_e32 v134, v184
	v_cvt_f32_ubyte3_e32 v135, v184
	v_cvt_f32_ubyte1_e32 v136, v185
	v_cvt_f32_ubyte3_e32 v137, v185
	v_cvt_f32_ubyte1_e32 v138, v186
	v_cvt_f32_ubyte3_e32 v139, v186
	v_cvt_f32_ubyte1_e32 v140, v187
	v_cvt_f32_ubyte3_e32 v141, v187
	v_mul_f32_e32 v114, v114, v134
	v_mul_f32_e32 v115, v115, v135
	v_mul_f32_e32 v116, v116, v136
	v_mul_f32_e32 v117, v117, v137
	v_mul_f32_e32 v110, v110, v138
	v_mul_f32_e32 v111, v111, v139
	v_mul_f32_e32 v112, v112, v140
	v_mul_f32_e32 v113, v113, v141
	v_cvt_pk_bf16_f32 v184, v114, v115
	v_cvt_pk_bf16_f32 v185, v116, v117
	v_cvt_pk_bf16_f32 v186, v110, v111
	v_cvt_pk_bf16_f32 v187, v112, v113
	global_store_dwordx4 v240, v[184:187], s[8:9] offset:0
	s_waitcnt vmcnt(15)
	v_pk_mul_f32 v[106:107], v[106:107], s[16:17] op_sel_hi:[1,0]
	v_pk_mul_f32 v[108:109], v[108:109], s[16:17] op_sel_hi:[1,0]
	v_pk_mul_f32 v[102:103], v[102:103], s[16:17] op_sel_hi:[1,0]
	v_pk_mul_f32 v[104:105], v[104:105], s[16:17] op_sel_hi:[1,0]
	v_cvt_f32_ubyte1_e32 v134, v188
	v_cvt_f32_ubyte3_e32 v135, v188
	v_cvt_f32_ubyte1_e32 v136, v189
	v_cvt_f32_ubyte3_e32 v137, v189
	v_cvt_f32_ubyte1_e32 v138, v190
	v_cvt_f32_ubyte3_e32 v139, v190
	v_cvt_f32_ubyte1_e32 v140, v191
	v_cvt_f32_ubyte3_e32 v141, v191
	v_mul_f32_e32 v106, v106, v134
	v_mul_f32_e32 v107, v107, v135
	v_mul_f32_e32 v108, v108, v136
	v_mul_f32_e32 v109, v109, v137
	v_mul_f32_e32 v102, v102, v138
	v_mul_f32_e32 v103, v103, v139
	v_mul_f32_e32 v104, v104, v140
	v_mul_f32_e32 v105, v105, v141
	v_cvt_pk_bf16_f32 v188, v106, v107
	v_cvt_pk_bf16_f32 v189, v108, v109
	v_cvt_pk_bf16_f32 v190, v102, v103
	v_cvt_pk_bf16_f32 v191, v104, v105
	global_store_dwordx4 v240, v[188:191], s[8:9] offset:256
	s_waitcnt vmcnt(15)
; __device__ __forceinline__ unsigned cvt_pk_bf16(float lo, float hi) { unsigned r; asm volatile("v_cvt_pk_bf16_f32 %0, %1, %2" : "=v"(r) : "v"(lo), "v"(hi)); return r; }
;     static __device__ __forceinline__ float ub(unsigned w, int k) { return (float)((w >> (8 * k)) & 0xffu); }
;     __device__ __forceinline__ void operator()(const f32x4 (&acc)[2][2][4][2], const Unit& u, int wr, int wc, int fr, int fq) const {
;     ...
;                 for (int bj = 0; bj < 2; ++bj) { const u32x4 g = *(const u32x4*)(AB + (off + bj * HALF)); const f32x4 v0 = acc[ai][bj][m][0] * s, v1 = acc[ai][bj][m][1] * s;
;                     u32x4 w; w.x = cvt_pk_bf16(v0[0] * ub(g.x, 1), v0[1] * ub(g.x, 3)); w.y = cvt_pk_bf16(v0[2] * ub(g.y, 1), v0[3] * ub(g.y, 3));
;                     w.z = cvt_pk_bf16(v1[0] * ub(g.z, 1), v1[1] * ub(g.z, 3)); w.w = cvt_pk_bf16(v1[2] * ub(g.w, 1), v1[3] * ub(g.w, 3));
;                     *(u32x4*)((unsigned char*)MG + 2u * (off + bj * HALF)) = w; } }
	v_pk_mul_f32 v[98:99], v[98:99], s[16:17] op_sel_hi:[1,0]
	v_pk_mul_f32 v[100:101], v[100:101], s[16:17] op_sel_hi:[1,0]
	v_pk_mul_f32 v[94:95], v[94:95], s[16:17] op_sel_hi:[1,0]
	v_pk_mul_f32 v[96:97], v[96:97], s[16:17] op_sel_hi:[1,0]
	v_cvt_f32_ubyte1_e32 v134, v192
	v_cvt_f32_ubyte3_e32 v135, v192
	v_cvt_f32_ubyte1_e32 v136, v193
	v_cvt_f32_ubyte3_e32 v137, v193
	v_cvt_f32_ubyte1_e32 v138, v194
	v_cvt_f32_ubyte3_e32 v139, v194
	v_cvt_f32_ubyte1_e32 v140, v195
	v_cvt_f32_ubyte3_e32 v141, v195
	v_mul_f32_e32 v98, v98, v134
	v_mul_f32_e32 v99, v99, v135
	v_mul_f32_e32 v100, v100, v136
	v_mul_f32_e32 v101, v101, v137
	v_mul_f32_e32 v94, v94, v138
	v_mul_f32_e32 v95, v95, v139
	v_mul_f32_e32 v96, v96, v140
	v_mul_f32_e32 v97, v97, v141
	v_cvt_pk_bf16_f32 v192, v98, v99
	v_cvt_pk_bf16_f32 v193, v100, v101
	v_cvt_pk_bf16_f32 v194, v94, v95
	v_cvt_pk_bf16_f32 v195, v96, v97
	global_store_dwordx4 v241, v[192:195], s[8:9] offset:0
	s_waitcnt vmcnt(15)
	v_pk_mul_f32 v[90:91], v[90:91], s[16:17] op_sel_hi:[1,0]
	v_pk_mul_f32 v[92:93], v[92:93], s[16:17] op_sel_hi:[1,0]
	v_pk_mul_f32 v[86:87], v[86:87], s[16:17] op_sel_hi:[1,0]
	v_pk_mul_f32 v[88:89], v[88:89], s[16:17] op_sel_hi:[1,0]
	v_cvt_f32_ubyte1_e32 v134, v196
	v_cvt_f32_ubyte3_e32 v135, v196
	v_cvt_f32_ubyte1_e32 v136, v197
	v_cvt_f32_ubyte3_e32 v137, v197
	v_cvt_f32_ubyte1_e32 v138, v198
	v_cvt_f32_ubyte3_e32 v139, v198
	v_cvt_f32_ubyte1_e32 v140, v199
	v_cvt_f32_ubyte3_e32 v141, v199
	v_mul_f32_e32 v90, v90, v134
	v_mul_f32_e32 v91, v91, v135
	v_mul_f32_e32 v92, v92, v136
	v_mul_f32_e32 v93, v93, v137
	v_mul_f32_e32 v86, v86, v138
	v_mul_f32_e32 v87, v87, v139
	v_mul_f32_e32 v88, v88, v140
	v_mul_f32_e32 v89, v89, v141
	v_cvt_pk_bf16_f32 v196, v90, v91
	v_cvt_pk_bf16_f32 v197, v92, v93
	v_cvt_pk_bf16_f32 v198, v86, v87
	v_cvt_pk_bf16_f32 v199, v88, v89
	global_store_dwordx4 v241, v[196:199], s[8:9] offset:256
	s_waitcnt vmcnt(15)
	v_pk_mul_f32 v[82:83], v[82:83], s[16:17] op_sel_hi:[1,0]
	v_pk_mul_f32 v[84:85], v[84:85], s[16:17] op_sel_hi:[1,0]
	v_pk_mul_f32 v[78:79], v[78:79], s[16:17] op_sel_hi:[1,0]
	v_pk_mul_f32 v[80:81], v[80:81], s[16:17] op_sel_hi:[1,0]
	v_cvt_f32_ubyte1_e32 v134, v200
	v_cvt_f32_ubyte3_e32 v135, v200
	v_cvt_f32_ubyte1_e32 v136, v201
	v_cvt_f32_ubyte3_e32 v137, v201
	v_cvt_f32_ubyte1_e32 v138, v202
	v_cvt_f32_ubyte3_e32 v139, v202
	v_cvt_f32_ubyte1_e32 v140, v203
	v_cvt_f32_ubyte3_e32 v141, v203
	v_mul_f32_e32 v82, v82, v134
	v_mul_f32_e32 v83, v83, v135
	v_mul_f32_e32 v84, v84, v136
	v_mul_f32_e32 v85, v85, v137
	v_mul_f32_e32 v78, v78, v138
	v_mul_f32_e32 v79, v79, v139
	v_mul_f32_e32 v80, v80, v140
	v_mul_f32_e32 v81, v81, v141
	v_cvt_pk_bf16_f32 v200, v82, v83
	v_cvt_pk_bf16_f32 v201, v84, v85
	v_cvt_pk_bf16_f32 v202, v78, v79
	v_cvt_pk_bf16_f32 v203, v80, v81
	global_store_dwordx4 v242, v[200:203], s[8:9] offset:0
	s_waitcnt vmcnt(15)
	v_pk_mul_f32 v[74:75], v[74:75], s[16:17] op_sel_hi:[1,0]
	v_pk_mul_f32 v[76:77], v[76:77], s[16:17] op_sel_hi:[1,0]
	v_pk_mul_f32 v[70:71], v[70:71], s[16:17] op_sel_hi:[1,0]
	v_pk_mul_f32 v[72:73], v[72:73], s[16:17] op_sel_hi:[1,0]
	v_cvt_f32_ubyte1_e32 v134, v204
	v_cvt_f32_ubyte3_e32 v135, v204
	v_cvt_f32_ubyte1_e32 v136, v205
	v_cvt_f32_ubyte3_e32 v137, v205
	v_cvt_f32_ubyte1_e32 v138, v206
	v_cvt_f32_ubyte3_e32 v139, v206
	v_cvt_f32_ubyte1_e32 v140, v207
	v_cvt_f32_ubyte3_e32 v141, v207
	v_mul_f32_e32 v74, v74, v134
	v_mul_f32_e32 v75, v75, v135
	v_mul_f32_e32 v76, v76, v136
	v_mul_f32_e32 v77, v77, v137
	v_mul_f32_e32 v70, v70, v138
	v_mul_f32_e32 v71, v71, v139
	v_mul_f32_e32 v72, v72, v140
	v_mul_f32_e32 v73, v73, v141
	v_cvt_pk_bf16_f32 v204, v74, v75
	v_cvt_pk_bf16_f32 v205, v76, v77
	v_cvt_pk_bf16_f32 v206, v70, v71
	v_cvt_pk_bf16_f32 v207, v72, v73
	global_store_dwordx4 v242, v[204:207], s[8:9] offset:256
	s_waitcnt vmcnt(15)
	v_pk_mul_f32 v[66:67], v[66:67], s[16:17] op_sel_hi:[1,0]
	v_pk_mul_f32 v[68:69], v[68:69], s[16:17] op_sel_hi:[1,0]
	v_pk_mul_f32 v[62:63], v[62:63], s[16:17] op_sel_hi:[1,0]
	v_pk_mul_f32 v[64:65], v[64:65], s[16:17] op_sel_hi:[1,0]
	v_cvt_f32_ubyte1_e32 v134, v208
	v_cvt_f32_ubyte3_e32 v135, v208
	v_cvt_f32_ubyte1_e32 v136, v209
	v_cvt_f32_ubyte3_e32 v137, v209
	v_cvt_f32_ubyte1_e32 v138, v210
	v_cvt_f32_ubyte3_e32 v139, v210
	v_cvt_f32_ubyte1_e32 v140, v211
	v_cvt_f32_ubyte3_e32 v141, v211
	v_mul_f32_e32 v66, v66, v134
	v_mul_f32_e32 v67, v67, v135
	v_mul_f32_e32 v68, v68, v136
	v_mul_f32_e32 v69, v69, v137
	v_mul_f32_e32 v62, v62, v138
	v_mul_f32_e32 v63, v63, v139
	v_mul_f32_e32 v64, v64, v140
	v_mul_f32_e32 v65, v65, v141
	v_cvt_pk_bf16_f32 v208, v66, v67
	v_cvt_pk_bf16_f32 v209, v68, v69
	v_cvt_pk_bf16_f32 v210, v62, v63
	v_cvt_pk_bf16_f32 v211, v64, v65
	global_store_dwordx4 v243, v[208:211], s[8:9] offset:0
	s_waitcnt vmcnt(15)
	v_pk_mul_f32 v[58:59], v[58:59], s[16:17] op_sel_hi:[1,0]
	v_pk_mul_f32 v[60:61], v[60:61], s[16:17] op_sel_hi:[1,0]
	v_pk_mul_f32 v[54:55], v[54:55], s[16:17] op_sel_hi:[1,0]
	v_pk_mul_f32 v[56:57], v[56:57], s[16:17] op_sel_hi:[1,0]
	v_cvt_f32_ubyte1_e32 v134, v212
	v_cvt_f32_ubyte3_e32 v135, v212
	v_cvt_f32_ubyte1_e32 v136, v213
	v_cvt_f32_ubyte3_e32 v137, v213
	v_cvt_f32_ubyte1_e32 v138, v214
	v_cvt_f32_ubyte3_e32 v139, v214
	v_cvt_f32_ubyte1_e32 v140, v215
	v_cvt_f32_ubyte3_e32 v141, v215
	v_mul_f32_e32 v58, v58, v134
	v_mul_f32_e32 v59, v59, v135
	v_mul_f32_e32 v60, v60, v136
	v_mul_f32_e32 v61, v61, v137
	v_mul_f32_e32 v54, v54, v138
	v_mul_f32_e32 v55, v55, v139
	v_mul_f32_e32 v56, v56, v140
	v_mul_f32_e32 v57, v57, v141
	v_cvt_pk_bf16_f32 v212, v58, v59
	v_cvt_pk_bf16_f32 v213, v60, v61
	v_cvt_pk_bf16_f32 v214, v54, v55
	v_cvt_pk_bf16_f32 v215, v56, v57
	global_store_dwordx4 v243, v[212:215], s[8:9] offset:256
	s_waitcnt vmcnt(15)
; __device__ __forceinline__ unsigned cvt_pk_bf16(float lo, float hi) { unsigned r; asm volatile("v_cvt_pk_bf16_f32 %0, %1, %2" : "=v"(r) : "v"(lo), "v"(hi)); return r; }
;     static __device__ __forceinline__ float ub(unsigned w, int k) { return (float)((w >> (8 * k)) & 0xffu); }
; #define PG8_BAR __builtin_amdgcn_s_barrier()
;     __device__ __forceinline__ void operator()(const f32x4 (&acc)[2][2][4][2], const Unit& u, int wr, int wc, int fr, int fq) const {
;     ...
;                 for (int bj = 0; bj < 2; ++bj) { const u32x4 g = *(const u32x4*)(AB + (off + bj * HALF)); const f32x4 v0 = acc[ai][bj][m][0] * s, v1 = acc[ai][bj][m][1] * s;
;                     u32x4 w; w.x = cvt_pk_bf16(v0[0] * ub(g.x, 1), v0[1] * ub(g.x, 3)); w.y = cvt_pk_bf16(v0[2] * ub(g.y, 1), v0[3] * ub(g.y, 3));
;                     w.z = cvt_pk_bf16(v1[0] * ub(g.z, 1), v1[1] * ub(g.z, 3)); w.w = cvt_pk_bf16(v1[2] * ub(g.w, 1), v1[3] * ub(g.w, 3));
;                     *(u32x4*)((unsigned char*)MG + 2u * (off + bj * HALF)) = w; } }
; template <class Epi, class Sched, bool ALIGN_EPI = false, bool SP2 = false>
; __device__ __forceinline__ void gemm_phase(PG8_LAS unsigned char* lds, const Gemm g, const Sched& S, const Epi& E) {
;     ...
;         if (!has_next) break;
; #pragma unroll
;         for (int a = 0; a < 2; ++a)
; #pragma unroll
;             for (int b = 0; b < 2; ++b)
; #pragma unroll
;                 for (int m = 0; m < 4; ++m)
; #pragma unroll
;                     for (int n = 0; n < 2; ++n) acc[a][b][m][n] = (f32x4){0.f, 0.f, 0.f, 0.f};
;         cur = nxt; cA = nA; cB = nB; ++ui;
;         if constexpr (ALIGN_EPI) { if (wr == 1) PG8_BAR; }
	v_pk_mul_f32 v[50:51], v[50:51], s[16:17] op_sel_hi:[1,0]
	v_pk_mul_f32 v[52:53], v[52:53], s[16:17] op_sel_hi:[1,0]
	v_pk_mul_f32 v[46:47], v[46:47], s[16:17] op_sel_hi:[1,0]
	v_pk_mul_f32 v[48:49], v[48:49], s[16:17] op_sel_hi:[1,0]
	v_cvt_f32_ubyte1_e32 v134, v216
	v_cvt_f32_ubyte3_e32 v135, v216
	v_cvt_f32_ubyte1_e32 v136, v217
	v_cvt_f32_ubyte3_e32 v137, v217
	v_cvt_f32_ubyte1_e32 v138, v218
	v_cvt_f32_ubyte3_e32 v139, v218
	v_cvt_f32_ubyte1_e32 v140, v219
	v_cvt_f32_ubyte3_e32 v141, v219
	v_mul_f32_e32 v50, v50, v134
	v_mul_f32_e32 v51, v51, v135
	v_mul_f32_e32 v52, v52, v136
	v_mul_f32_e32 v53, v53, v137
	v_mul_f32_e32 v46, v46, v138
	v_mul_f32_e32 v47, v47, v139
	v_mul_f32_e32 v48, v48, v140
	v_mul_f32_e32 v49, v49, v141
	v_cvt_pk_bf16_f32 v216, v50, v51
	v_cvt_pk_bf16_f32 v217, v52, v53
	v_cvt_pk_bf16_f32 v218, v46, v47
	v_cvt_pk_bf16_f32 v219, v48, v49
	global_store_dwordx4 v244, v[216:219], s[8:9] offset:0
	s_waitcnt vmcnt(15)
	v_pk_mul_f32 v[42:43], v[42:43], s[16:17] op_sel_hi:[1,0]
	v_pk_mul_f32 v[44:45], v[44:45], s[16:17] op_sel_hi:[1,0]
	v_pk_mul_f32 v[38:39], v[38:39], s[16:17] op_sel_hi:[1,0]
	v_pk_mul_f32 v[40:41], v[40:41], s[16:17] op_sel_hi:[1,0]
	v_cvt_f32_ubyte1_e32 v134, v220
	v_cvt_f32_ubyte3_e32 v135, v220
	v_cvt_f32_ubyte1_e32 v136, v221
	v_cvt_f32_ubyte3_e32 v137, v221
	v_cvt_f32_ubyte1_e32 v138, v222
	v_cvt_f32_ubyte3_e32 v139, v222
	v_cvt_f32_ubyte1_e32 v140, v223
	v_cvt_f32_ubyte3_e32 v141, v223
	v_mul_f32_e32 v42, v42, v134
	v_mul_f32_e32 v43, v43, v135
	v_mul_f32_e32 v44, v44, v136
	v_mul_f32_e32 v45, v45, v137
	v_mul_f32_e32 v38, v38, v138
	v_mul_f32_e32 v39, v39, v139
	v_mul_f32_e32 v40, v40, v140
	v_mul_f32_e32 v41, v41, v141
	v_cvt_pk_bf16_f32 v220, v42, v43
	v_cvt_pk_bf16_f32 v221, v44, v45
	v_cvt_pk_bf16_f32 v222, v38, v39
	v_cvt_pk_bf16_f32 v223, v40, v41
	global_store_dwordx4 v244, v[220:223], s[8:9] offset:256
	s_waitcnt vmcnt(15)
	v_pk_mul_f32 v[34:35], v[34:35], s[16:17] op_sel_hi:[1,0]
	v_pk_mul_f32 v[36:37], v[36:37], s[16:17] op_sel_hi:[1,0]
	v_pk_mul_f32 v[30:31], v[30:31], s[16:17] op_sel_hi:[1,0]
	v_pk_mul_f32 v[32:33], v[32:33], s[16:17] op_sel_hi:[1,0]
	v_cvt_f32_ubyte1_e32 v134, v224
	v_cvt_f32_ubyte3_e32 v135, v224
	v_cvt_f32_ubyte1_e32 v136, v225
	v_cvt_f32_ubyte3_e32 v137, v225
	v_cvt_f32_ubyte1_e32 v138, v226
	v_cvt_f32_ubyte3_e32 v139, v226
	v_cvt_f32_ubyte1_e32 v140, v227
	v_cvt_f32_ubyte3_e32 v141, v227
	v_mul_f32_e32 v34, v34, v134
	v_mul_f32_e32 v35, v35, v135
	v_mul_f32_e32 v36, v36, v136
	v_mul_f32_e32 v37, v37, v137
	v_mul_f32_e32 v30, v30, v138
	v_mul_f32_e32 v31, v31, v139
	v_mul_f32_e32 v32, v32, v140
	v_mul_f32_e32 v33, v33, v141
	v_cvt_pk_bf16_f32 v224, v34, v35
	v_cvt_pk_bf16_f32 v225, v36, v37
	v_cvt_pk_bf16_f32 v226, v30, v31
	v_cvt_pk_bf16_f32 v227, v32, v33
	global_store_dwordx4 v245, v[224:227], s[8:9] offset:0
	s_waitcnt vmcnt(15)
	v_pk_mul_f32 v[26:27], v[26:27], s[16:17] op_sel_hi:[1,0]
	v_pk_mul_f32 v[28:29], v[28:29], s[16:17] op_sel_hi:[1,0]
	v_pk_mul_f32 v[22:23], v[22:23], s[16:17] op_sel_hi:[1,0]
	v_pk_mul_f32 v[24:25], v[24:25], s[16:17] op_sel_hi:[1,0]
	v_cvt_f32_ubyte1_e32 v134, v228
	v_cvt_f32_ubyte3_e32 v135, v228
	v_cvt_f32_ubyte1_e32 v136, v229
	v_cvt_f32_ubyte3_e32 v137, v229
	v_cvt_f32_ubyte1_e32 v138, v230
	v_cvt_f32_ubyte3_e32 v139, v230
	v_cvt_f32_ubyte1_e32 v140, v231
	v_cvt_f32_ubyte3_e32 v141, v231
	v_mul_f32_e32 v26, v26, v134
	v_mul_f32_e32 v27, v27, v135
	v_mul_f32_e32 v28, v28, v136
	v_mul_f32_e32 v29, v29, v137
	v_mul_f32_e32 v22, v22, v138
	v_mul_f32_e32 v23, v23, v139
	v_mul_f32_e32 v24, v24, v140
	v_mul_f32_e32 v25, v25, v141
	v_cvt_pk_bf16_f32 v228, v26, v27
	v_cvt_pk_bf16_f32 v229, v28, v29
	v_cvt_pk_bf16_f32 v230, v22, v23
	v_cvt_pk_bf16_f32 v231, v24, v25
	global_store_dwordx4 v245, v[228:231], s[8:9] offset:256
	s_waitcnt vmcnt(15)
	v_pk_mul_f32 v[18:19], v[18:19], s[16:17] op_sel_hi:[1,0]
	v_pk_mul_f32 v[20:21], v[20:21], s[16:17] op_sel_hi:[1,0]
	v_pk_mul_f32 v[14:15], v[14:15], s[16:17] op_sel_hi:[1,0]
	v_pk_mul_f32 v[16:17], v[16:17], s[16:17] op_sel_hi:[1,0]
	v_cvt_f32_ubyte1_e32 v134, v232
	v_cvt_f32_ubyte3_e32 v135, v232
	v_cvt_f32_ubyte1_e32 v136, v233
	v_cvt_f32_ubyte3_e32 v137, v233
	v_cvt_f32_ubyte1_e32 v138, v234
	v_cvt_f32_ubyte3_e32 v139, v234
	v_cvt_f32_ubyte1_e32 v140, v235
	v_cvt_f32_ubyte3_e32 v141, v235
	v_mul_f32_e32 v18, v18, v134
	v_mul_f32_e32 v19, v19, v135
	v_mul_f32_e32 v20, v20, v136
	v_mul_f32_e32 v21, v21, v137
	v_mul_f32_e32 v14, v14, v138
	v_mul_f32_e32 v15, v15, v139
	v_mul_f32_e32 v16, v16, v140
	v_mul_f32_e32 v17, v17, v141
	v_cvt_pk_bf16_f32 v232, v18, v19
	v_cvt_pk_bf16_f32 v233, v20, v21
	v_cvt_pk_bf16_f32 v234, v14, v15
	v_cvt_pk_bf16_f32 v235, v16, v17
	global_store_dwordx4 v246, v[232:235], s[8:9] offset:0
	s_waitcnt vmcnt(15)
	v_pk_mul_f32 v[10:11], v[10:11], s[16:17] op_sel_hi:[1,0]
	v_pk_mul_f32 v[12:13], v[12:13], s[16:17] op_sel_hi:[1,0]
	v_pk_mul_f32 v[6:7], v[6:7], s[16:17] op_sel_hi:[1,0]
	v_pk_mul_f32 v[8:9], v[8:9], s[16:17] op_sel_hi:[1,0]
	v_cvt_f32_ubyte1_e32 v134, v236
	v_cvt_f32_ubyte3_e32 v135, v236
	v_cvt_f32_ubyte1_e32 v136, v237
	v_cvt_f32_ubyte3_e32 v137, v237
	v_cvt_f32_ubyte1_e32 v138, v238
	v_cvt_f32_ubyte3_e32 v139, v238
	v_cvt_f32_ubyte1_e32 v140, v239
	v_cvt_f32_ubyte3_e32 v141, v239
	v_mul_f32_e32 v10, v10, v134
	v_mul_f32_e32 v11, v11, v135
	v_mul_f32_e32 v12, v12, v136
	v_mul_f32_e32 v13, v13, v137
	v_mul_f32_e32 v6, v6, v138
	v_mul_f32_e32 v7, v7, v139
	v_mul_f32_e32 v8, v8, v140
	v_mul_f32_e32 v9, v9, v141
	v_cvt_pk_bf16_f32 v236, v10, v11
	v_cvt_pk_bf16_f32 v237, v12, v13
	v_cvt_pk_bf16_f32 v238, v6, v7
	v_cvt_pk_bf16_f32 v239, v8, v9
	global_store_dwordx4 v246, v[236:239], s[8:9] offset:256
	s_andn2_b64 vcc, exec, s[4:5]
	s_mov_b64 s[4:5], -1
	s_cbranch_vccnz .LBB0_499
	s_andn2_b64 vcc, exec, s[6:7]
	s_cbranch_vccnz .LBB0_498
	s_barrier
	s_branch .LBB0_498

; #define PG8_STAGE(bufoff, gbase, voff) do { _Pragma("unroll") for (int _i = 0; _i < 2; ++_i) \
;         __builtin_amdgcn_global_load_lds((const unsigned*)((const char*)(gbase) + (voff)[_i]), (PG8_LAS unsigned*)(lds + (bufoff) + ldsw + _i * 8192), 16, 0, 0); } while (0)
; #define PG8_WAIT_V(n) asm volatile("s_waitcnt vmcnt(" #n ")" ::: "memory")
; #define PG8_BAR __builtin_amdgcn_s_barrier()
; template <class Epi, class Sched, bool ALIGN_EPI = false, bool SP2 = false>
; __device__ __forceinline__ void gemm_phase(PG8_LAS unsigned char* lds, const Gemm g, const Sched& S, const Epi& E) {
;     ...
;     for (int i = 0; i < 2; ++i) { int R, C; stage_rc(tid * 16 + i * 8192, R, C); const int Rb = Epi::PERM ? ((R & ~31) + perm32(R & 31)) : R;
;         voffA[i] = (unsigned)(R * K + C) * 2u; voffB[i] = (unsigned)(Rb * K + C) * 2u; }
;     const size_t kstep = (size_t)(BK * 2);
;     const size_t hstep = (size_t)HALF * K * 2;
;     const size_t tstep = 2 * hstep;
;     const unsigned ldsw = (unsigned)wid * 1024u;
;     const int aoff = lds_byte(wr * 64 + fr, fq * 8), boff = lds_byte(wc * 32 + fr, fq * 8);
;     ...
;         PG8_STAGE(PG8_SB(0, 0), cB, voffB); PG8_STAGE(PG8_SB(0, 1), cB + hstep, voffB); PG8_STAGE(PG8_SA(0, 0), cA, voffA); PG8_STAGE(PG8_SA(0, 1), cA + hstep, voffA);
;         if (wr == 1) PG8_BAR;
;         PG8_WAIT_V(2); PG8_BAR;
;         PG8_STAGE(PG8_SB(1, 0), cB + kstep, voffB); PG8_STAGE(PG8_SA(1, 0), cA + kstep, voffA); PG8_STAGE(PG8_SB(1, 1), cB + hstep + kstep, voffB);
;         PG8_WAIT_V(6); PG8_BAR;
.LBB0_575:
	s_add_u32 s50, s10, 0x2000
	s_addc_u32 s51, s11, 0
	s_lshl_b32 s0, s15, 5
	s_mov_b64 s[10:11], 0x80
	s_and_b32 s15, s0, 0x60
	s_add_i32 m0, s45, 0x18000
	v_lshl_add_u64 v[8:9], v[8:9], 0, s[10:11]
	s_lshl_b32 s16, s14, 6
	s_lshl_b32 s14, s14, 13
	s_lshl_b32 s17, s15, 7
	s_waitcnt vmcnt(2)
	s_barrier
	global_load_lds_dwordx4 v[8:9], off
	v_lshl_add_u64 v[6:7], v[6:7], 0, s[10:11]
	s_add_i32 m0, s45, 0x1a000
	s_add_i32 s52, s45, 0x8000
	s_add_i32 s53, s45, 0xa000
	global_load_lds_dwordx4 v[6:7], off
	v_lshl_add_u64 v[2:3], v[2:3], 0, s[10:11]
	s_mov_b32 m0, s52
	s_add_u32 s0, s36, 0x40080
	global_load_lds_dwordx4 v[2:3], off
	v_lshl_add_u64 v[2:3], v[4:5], 0, s[10:11]
	s_mov_b32 m0, s53
	s_addc_u32 s1, s37, 0
	global_load_lds_dwordx4 v[2:3], off
	s_add_i32 m0, s45, 0x1c000
	v_lshl_add_u64 v[2:3], s[0:1], 0, v[144:145]
	global_load_lds_dwordx4 v[2:3], off
	v_lshl_add_u64 v[2:3], s[0:1], 0, v[146:147]
	s_add_i32 m0, s45, 0x1e000
	v_bfe_u32 v4, v0, 4, 2
	global_load_lds_dwordx4 v[2:3], off
	v_and_b32_e32 v2, 15, v0
	v_lshlrev_b32_e32 v3, 4, v4
	v_lshlrev_b32_e32 v0, 2, v0
	v_lshl_or_b32 v3, v2, 6, v3
	v_and_b32_e32 v0, 32, v0
	v_bitop3_b32 v5, v3, s14, v0 bitop3:0xde
	v_bitop3_b32 v162, v3, s17, v0 bitop3:0xde
	v_lshlrev_b32_e32 v0, 14, v1
	v_and_b32_e32 v0, 0xffff8000, v0
	v_lshl_add_u32 v0, v10, 11, v0
	v_and_b32_e32 v1, 1, v1
	v_lshl_or_b32 v0, v1, 6, v0
	v_lshl_add_u32 v150, v11, 1, v0
	v_lshlrev_b32_e32 v0, 14, v12
	s_cmpk_lt_u32 s13, 0x100
	v_and_b32_e32 v0, 0xffff8000, v0
	s_sext_i32_i8 s61, s12
	s_waitcnt vmcnt(6)
	s_cselect_b64 s[12:13], -1, 0
	s_ashr_i32 s0, s16, 31
	v_lshl_add_u32 v0, v13, 11, v0
	v_and_b32_e32 v1, 1, v12
	v_or_b32_e32 v2, s16, v2
	v_mov_b32_e32 v3, s0
	v_lshl_or_b32 v0, v1, 6, v0
	s_add_i32 s55, 0, 0x10000
	s_add_i32 s56, 0, 0x14000
	v_lshlrev_b64 v[148:149], 12, v[2:3]
	s_ashr_i32 s54, s3, 31
	v_lshl_or_b32 v163, v4, 2, s15
	v_mov_b32_e32 v151, v145
	v_lshl_add_u32 v152, v14, 1, v0
	v_mov_b32_e32 v153, v145
	v_mov_b64_e32 v[154:155], 0x200
	v_mov_b64_e32 v[156:157], 0x1ff
	v_add_u32_e32 v164, s55, v162
	v_add_u32_e32 v165, s56, v162
	v_add_u32_e32 v166, 0, v5
	s_mov_b64 s[14:15], 0x80000
	s_mov_b32 s57, 0x80000
	s_mov_b64 s[16:17], 0x90000
	s_mov_b32 s58, 0x90000
	s_mov_b64 s[18:19], 0xa0000
	s_mov_b32 s59, 0xa0000
	s_mov_b64 s[20:21], 0xb0000
	s_mov_b32 s60, 0xb0000
	s_barrier
	s_mov_b32 s89, 0
	s_branch .LBB0_578

; #define PG8_STAGE(bufoff, gbase, voff) do { _Pragma("unroll") for (int _i = 0; _i < 2; ++_i) \
;         __builtin_amdgcn_global_load_lds((const unsigned*)((const char*)(gbase) + (voff)[_i]), (PG8_LAS unsigned*)(lds + (bufoff) + ldsw + _i * 8192), 16, 0, 0); } while (0)
; #define PG8_LDA(dst, b, h) do { _Pragma("unroll") for (int m = 0; m < 4; ++m) _Pragma("unroll") for (int k = 0; k < 2; ++k) dst[m][k] = *(const PG8_LAS bf16x8*)(lds + PG8_SA(b, h) + aoff + m * 2048 + k * 1024); } while (0)
; #define PG8_LDB(dst, b, h) do { _Pragma("unroll") for (int n = 0; n < 2; ++n) _Pragma("unroll") for (int k = 0; k < 2; ++k) dst[n][k] = *(const PG8_LAS bf16x8*)(lds + PG8_SB(b, h) + boff + n * 2048 + k * 1024); } while (0)
; #define PG8_MMA(ai, bj, At, Bt) do { __builtin_amdgcn_s_setprio(1); _Pragma("unroll") for (int m = 0; m < 4; ++m) _Pragma("unroll") for (int n = 0; n < 2; ++n) _Pragma("unroll") for (int k = 0; k < 2; ++k) \
;         acc[ai][bj][m][n] = __builtin_amdgcn_mfma_f32_16x16x32_bf16(Bt[n][k], At[m][k], acc[ai][bj][m][n], 0, 0, 0); __builtin_amdgcn_s_setprio(0); } while (0)
; #define PG8_WAIT_V(n) asm volatile("s_waitcnt vmcnt(" #n ")" ::: "memory")
; #define PG8_WAIT_L(n) asm volatile("s_waitcnt lgkmcnt(" #n ")" ::: "memory")
; template <class Epi, class Sched, bool ALIGN_EPI = false, bool SP2 = false>
; __device__ __forceinline__ void gemm_phase(PG8_LAS unsigned char* lds, const Gemm g, const Sched& S, const Epi& E) {
;     ...
;         const char* nA = has_next ? (const char*)g.A + (size_t)nxt.pm * tstep : cA; const char* nB = has_next ? (const char*)g.Bt + (size_t)nxt.pn * tstep : cB;
;         for (int t = 0; t < nt; t += 2) {
;             if constexpr (Epi::MID) { if (t == nt / 2) E.mid(acc, cur, wr, wc, fr, fq); }
;             const bool last = (t == nt - 2);
;             const char* a1 = cA + (size_t)(t + 1) * kstep;
;             const char* a2 = last ? nA : cA + (size_t)(t + 2) * kstep; const char* b2 = last ? nB : cB + (size_t)(t + 2) * kstep;
;             const char* a3 = a2 + kstep; const char* b3 = b2 + kstep;
;             if (last && has_next) S.a_ready(nxt);
;             if constexpr (SP2) {
;             PG8_LDB(B0, 0, 0); PG8_LDB(B1, 0, 1); PG8_SCHED; PG8_LDA(At, 0, 0); PG8_STAGE(PG8_SA(1, 1), a1 + hstep, voffA);
;             PG8_WAIT_V(8); PG8_WAIT_L(0); PG8_BAR; PG8_MMA(0, 0, At, B0); PG8_MMA(0, 1, At, B1); PG8_BAR; PG8_SCHED;
.LBB0_584:
	s_ashr_i32 s25, s24, 31
	s_lshl_b64 s[26:27], s[24:25], 19
	s_add_u32 s26, s42, s26
	s_addc_u32 s27, s43, s27
	s_and_b64 s[28:29], s[0:1], exec
	s_cselect_b32 s25, s27, s35
	s_cselect_b32 s31, s26, s34
	s_ashr_i32 s23, s22, 31
	s_lshl_b64 s[28:29], s[22:23], 19
	s_add_u32 s28, s40, s28
	s_addc_u32 s29, s41, s29
	s_and_b64 s[38:39], s[0:1], exec
	s_cselect_b32 s23, s29, s37
	s_cselect_b32 s62, s28, s36
	s_add_u32 s34, s34, 0x40080
	s_addc_u32 s35, s35, 0
	s_add_u32 s63, s36, 0x100
	s_addc_u32 s64, s37, 0
	s_mov_b32 s65, -2
	ds_read_b128 v[128:131], v164
	ds_read_b128 v[132:135], v164 offset:1024
	ds_read_b128 v[136:139], v164 offset:2048
	ds_read_b128 v[140:143], v164 offset:3072
	ds_read_b128 v[158:161], v165
	ds_read_b128 v[168:171], v165 offset:1024
	ds_read_b128 v[172:175], v165 offset:2048
	ds_read_b128 v[176:179], v165 offset:3072
	s_add_u32 s36, s34, 0xfffc0080
	s_addc_u32 s37, s35, -1
	s_cmp_eq_u32 s65, 12
	s_cselect_b32 s39, s25, s37
	s_cselect_b32 s38, s31, s36
	s_cselect_b32 s37, s23, s64
	s_cselect_b32 s36, s62, s63
	v_lshl_add_u64 v[212:213], s[34:35], 0, v[150:151]
	s_add_i32 m0, s45, 0xc000
	ds_read_b128 v[180:183], v166
	ds_read_b128 v[184:187], v166 offset:1024
	ds_read_b128 v[188:191], v166 offset:2048
	ds_read_b128 v[192:195], v166 offset:3072
	ds_read_b128 v[196:199], v166 offset:4096
	ds_read_b128 v[200:203], v166 offset:5120
	ds_read_b128 v[204:207], v166 offset:6144
	ds_read_b128 v[208:211], v166 offset:7168
	global_load_lds_dwordx4 v[212:213], off
	v_lshl_add_u64 v[212:213], s[34:35], 0, v[152:153]
	s_add_i32 m0, s45, 0xe000
	s_nop 0
	global_load_lds_dwordx4 v[212:213], off
	s_cmp_eq_u32 s89, 0
	s_cbranch_scc1 .Lrw_p5_0_a
	s_waitcnt vmcnt(63)
	s_branch .Lrw_p5_0_z

; #define PG8_STAGE(bufoff, gbase, voff) do { _Pragma("unroll") for (int _i = 0; _i < 2; ++_i) \
;         __builtin_amdgcn_global_load_lds((const unsigned*)((const char*)(gbase) + (voff)[_i]), (PG8_LAS unsigned*)(lds + (bufoff) + ldsw + _i * 8192), 16, 0, 0); } while (0)
; #define PG8_LDA(dst, b, h) do { _Pragma("unroll") for (int m = 0; m < 4; ++m) _Pragma("unroll") for (int k = 0; k < 2; ++k) dst[m][k] = *(const PG8_LAS bf16x8*)(lds + PG8_SA(b, h) + aoff + m * 2048 + k * 1024); } while (0)
; #define PG8_MMA(ai, bj, At, Bt) do { __builtin_amdgcn_s_setprio(1); _Pragma("unroll") for (int m = 0; m < 4; ++m) _Pragma("unroll") for (int n = 0; n < 2; ++n) _Pragma("unroll") for (int k = 0; k < 2; ++k) \
;         acc[ai][bj][m][n] = __builtin_amdgcn_mfma_f32_16x16x32_bf16(Bt[n][k], At[m][k], acc[ai][bj][m][n], 0, 0, 0); __builtin_amdgcn_s_setprio(0); } while (0)
; #define PG8_WAIT_V(n) asm volatile("s_waitcnt vmcnt(" #n ")" ::: "memory")
; #define PG8_WAIT_L(n) asm volatile("s_waitcnt lgkmcnt(" #n ")" ::: "memory")
; #define PG8_BAR __builtin_amdgcn_s_barrier()
; #define PG8_SCHED __builtin_amdgcn_sched_barrier(0)
; template <class Epi, class Sched, bool ALIGN_EPI = false, bool SP2 = false>
; __device__ __forceinline__ void gemm_phase(PG8_LAS unsigned char* lds, const Gemm g, const Sched& S, const Epi& E) {
;     ...
;             PG8_WAIT_V(8); PG8_WAIT_L(0); PG8_BAR; PG8_MMA(0, 0, At, B0); PG8_MMA(0, 1, At, B1); PG8_BAR; PG8_SCHED;
;             PG8_LDA(At, 0, 1); PG8_STAGE(PG8_SB(0, 0), b2, voffB); PG8_STAGE(PG8_SB(0, 1), b2 + hstep, voffB); PG8_STAGE(PG8_SA(0, 0), a2, voffA);
;             PG8_WAIT_V(8); PG8_WAIT_L(0); PG8_BAR; PG8_MMA(1, 0, At, B0); PG8_MMA(1, 1, At, B1); PG8_BAR; PG8_SCHED;
.Lrw_p5_0_z:
	s_waitcnt lgkmcnt(0)
	s_barrier
	s_setprio 1
	s_waitcnt lgkmcnt(0)
	v_mfma_f32_16x16x32_bf16 v[124:127], v[128:131], v[180:183], 0
	v_mfma_f32_16x16x32_bf16 v[120:123], v[136:139], v[180:183], 0
	v_mfma_f32_16x16x32_bf16 v[116:119], v[128:131], v[188:191], 0
	v_mfma_f32_16x16x32_bf16 v[112:115], v[136:139], v[188:191], 0
	v_mfma_f32_16x16x32_bf16 v[108:111], v[128:131], v[196:199], 0
	v_mfma_f32_16x16x32_bf16 v[100:103], v[136:139], v[196:199], 0
	v_mfma_f32_16x16x32_bf16 v[92:95], v[128:131], v[204:207], 0
	v_mfma_f32_16x16x32_bf16 v[76:79], v[136:139], v[204:207], 0
	v_mfma_f32_16x16x32_bf16 v[124:127], v[132:135], v[184:187], v[124:127]
	v_mfma_f32_16x16x32_bf16 v[120:123], v[140:143], v[184:187], v[120:123]
	v_mfma_f32_16x16x32_bf16 v[116:119], v[132:135], v[192:195], v[116:119]
	v_mfma_f32_16x16x32_bf16 v[112:115], v[140:143], v[192:195], v[112:115]
	v_mfma_f32_16x16x32_bf16 v[108:111], v[132:135], v[200:203], v[108:111]
	v_mfma_f32_16x16x32_bf16 v[100:103], v[140:143], v[200:203], v[100:103]
	v_mfma_f32_16x16x32_bf16 v[92:95], v[132:135], v[208:211], v[92:95]
	v_mfma_f32_16x16x32_bf16 v[76:79], v[140:143], v[208:211], v[76:79]
	s_setprio 0
	s_setprio 1
	v_mfma_f32_16x16x32_bf16 v[104:107], v[158:161], v[180:183], 0
	v_mfma_f32_16x16x32_bf16 v[96:99], v[172:175], v[180:183], 0
	v_mfma_f32_16x16x32_bf16 v[88:91], v[158:161], v[188:191], 0
	v_mfma_f32_16x16x32_bf16 v[84:87], v[172:175], v[188:191], 0
	v_mfma_f32_16x16x32_bf16 v[80:83], v[158:161], v[196:199], 0
	v_mfma_f32_16x16x32_bf16 v[72:75], v[172:175], v[196:199], 0
	v_mfma_f32_16x16x32_bf16 v[68:71], v[158:161], v[204:207], 0
	v_mfma_f32_16x16x32_bf16 v[64:67], v[172:175], v[204:207], 0
	v_mfma_f32_16x16x32_bf16 v[104:107], v[168:171], v[184:187], v[104:107]
	v_mfma_f32_16x16x32_bf16 v[96:99], v[176:179], v[184:187], v[96:99]
	v_mfma_f32_16x16x32_bf16 v[88:91], v[168:171], v[192:195], v[88:91]
	v_mfma_f32_16x16x32_bf16 v[84:87], v[176:179], v[192:195], v[84:87]
	v_mfma_f32_16x16x32_bf16 v[80:83], v[168:171], v[200:203], v[80:83]
	v_mfma_f32_16x16x32_bf16 v[72:75], v[176:179], v[200:203], v[72:75]
	v_mfma_f32_16x16x32_bf16 v[68:71], v[168:171], v[208:211], v[68:71]
	v_mfma_f32_16x16x32_bf16 v[64:67], v[176:179], v[208:211], v[64:67]
	s_setprio 0
	s_barrier
	s_add_i32 s66, s55, s44
	v_lshl_add_u64 v[212:213], s[36:37], 0, v[144:145]
	s_mov_b32 m0, s66
	ds_read_b128 v[180:183], v166 offset:16384
	ds_read_b128 v[184:187], v166 offset:17408
	ds_read_b128 v[188:191], v166 offset:18432
	ds_read_b128 v[192:195], v166 offset:19456
	ds_read_b128 v[196:199], v166 offset:20480
	ds_read_b128 v[200:203], v166 offset:21504
	ds_read_b128 v[204:207], v166 offset:22528
	ds_read_b128 v[208:211], v166 offset:23552
	global_load_lds_dwordx4 v[212:213], off
	s_add_i32 m0, s66, 0x2000
	s_add_u32 s66, s36, 0x40000
	v_lshl_add_u64 v[214:215], s[36:37], 0, v[146:147]
	s_addc_u32 s67, s37, 0
	s_add_i32 s68, s56, s44
	global_load_lds_dwordx4 v[214:215], off
	v_lshl_add_u64 v[216:217], s[66:67], 0, v[144:145]
	s_mov_b32 m0, s68
	v_lshl_add_u64 v[218:219], s[38:39], 0, v[146:147]
	global_load_lds_dwordx4 v[216:217], off
	v_lshl_add_u64 v[216:217], s[66:67], 0, v[146:147]
	s_add_i32 m0, s68, 0x2000
	s_nop 0
	global_load_lds_dwordx4 v[216:217], off
	v_lshl_add_u64 v[216:217], s[38:39], 0, v[144:145]
	s_mov_b32 m0, s45
	s_nop 0
	global_load_lds_dwordx4 v[216:217], off
	s_mov_b32 m0, s46
	s_nop 0
	global_load_lds_dwordx4 v[218:219], off
	s_cmp_eq_u32 s89, 0
	s_cbranch_scc1 .Lrw_p5_1_a
	s_waitcnt vmcnt(63)
	s_branch .Lrw_p5_1_z

; #define PG8_STAGE(bufoff, gbase, voff) do { _Pragma("unroll") for (int _i = 0; _i < 2; ++_i) \
;         __builtin_amdgcn_global_load_lds((const unsigned*)((const char*)(gbase) + (voff)[_i]), (PG8_LAS unsigned*)(lds + (bufoff) + ldsw + _i * 8192), 16, 0, 0); } while (0)
; #define PG8_LDA(dst, b, h) do { _Pragma("unroll") for (int m = 0; m < 4; ++m) _Pragma("unroll") for (int k = 0; k < 2; ++k) dst[m][k] = *(const PG8_LAS bf16x8*)(lds + PG8_SA(b, h) + aoff + m * 2048 + k * 1024); } while (0)
; #define PG8_LDB(dst, b, h) do { _Pragma("unroll") for (int n = 0; n < 2; ++n) _Pragma("unroll") for (int k = 0; k < 2; ++k) dst[n][k] = *(const PG8_LAS bf16x8*)(lds + PG8_SB(b, h) + boff + n * 2048 + k * 1024); } while (0)
; #define PG8_MMA(ai, bj, At, Bt) do { __builtin_amdgcn_s_setprio(1); _Pragma("unroll") for (int m = 0; m < 4; ++m) _Pragma("unroll") for (int n = 0; n < 2; ++n) _Pragma("unroll") for (int k = 0; k < 2; ++k) \
;         acc[ai][bj][m][n] = __builtin_amdgcn_mfma_f32_16x16x32_bf16(Bt[n][k], At[m][k], acc[ai][bj][m][n], 0, 0, 0); __builtin_amdgcn_s_setprio(0); } while (0)
; #define PG8_WAIT_V(n) asm volatile("s_waitcnt vmcnt(" #n ")" ::: "memory")
; #define PG8_WAIT_L(n) asm volatile("s_waitcnt lgkmcnt(" #n ")" ::: "memory")
; #define PG8_BAR __builtin_amdgcn_s_barrier()
; #define PG8_SCHED __builtin_amdgcn_sched_barrier(0)
; template <class Epi, class Sched, bool ALIGN_EPI = false, bool SP2 = false>
; __device__ __forceinline__ void gemm_phase(PG8_LAS unsigned char* lds, const Gemm g, const Sched& S, const Epi& E) {
;     ...
;             PG8_WAIT_V(8); PG8_WAIT_L(0); PG8_BAR; PG8_MMA(1, 0, At, B0); PG8_MMA(1, 1, At, B1); PG8_BAR; PG8_SCHED;
;             PG8_LDB(B0, 1, 0); PG8_LDB(B1, 1, 1); PG8_SCHED; PG8_LDA(At, 1, 0); PG8_STAGE(PG8_SA(0, 1), a2 + hstep, voffA);
;             PG8_WAIT_V(8); PG8_WAIT_L(0); PG8_BAR; PG8_MMA(0, 0, At, B0); PG8_MMA(0, 1, At, B1); PG8_BAR; PG8_SCHED;
.Lrw_p5_1_z:
	s_waitcnt lgkmcnt(0)
	s_barrier
	s_setprio 1
	s_waitcnt lgkmcnt(0)
	v_mfma_f32_16x16x32_bf16 v[60:63], v[128:131], v[180:183], 0
	v_mfma_f32_16x16x32_bf16 v[56:59], v[136:139], v[180:183], 0
	v_mfma_f32_16x16x32_bf16 v[52:55], v[128:131], v[188:191], 0
	v_mfma_f32_16x16x32_bf16 v[48:51], v[136:139], v[188:191], 0
	v_mfma_f32_16x16x32_bf16 v[32:35], v[128:131], v[196:199], 0
	v_mfma_f32_16x16x32_bf16 v[24:27], v[136:139], v[196:199], 0
	v_mfma_f32_16x16x32_bf16 v[20:23], v[128:131], v[204:207], 0
	v_mfma_f32_16x16x32_bf16 v[8:11], v[136:139], v[204:207], 0
	v_mfma_f32_16x16x32_bf16 v[60:63], v[132:135], v[184:187], v[60:63]
	v_mfma_f32_16x16x32_bf16 v[56:59], v[140:143], v[184:187], v[56:59]
	v_mfma_f32_16x16x32_bf16 v[52:55], v[132:135], v[192:195], v[52:55]
	v_mfma_f32_16x16x32_bf16 v[48:51], v[140:143], v[192:195], v[48:51]
	v_mfma_f32_16x16x32_bf16 v[32:35], v[132:135], v[200:203], v[32:35]
	v_mfma_f32_16x16x32_bf16 v[24:27], v[140:143], v[200:203], v[24:27]
	v_mfma_f32_16x16x32_bf16 v[20:23], v[132:135], v[208:211], v[20:23]
	v_mfma_f32_16x16x32_bf16 v[8:11], v[140:143], v[208:211], v[8:11]
	s_setprio 0
	s_setprio 1
	v_mfma_f32_16x16x32_bf16 v[44:47], v[158:161], v[180:183], 0
	v_mfma_f32_16x16x32_bf16 v[40:43], v[172:175], v[180:183], 0
	v_mfma_f32_16x16x32_bf16 v[36:39], v[158:161], v[188:191], 0
	v_mfma_f32_16x16x32_bf16 v[28:31], v[172:175], v[188:191], 0
	v_mfma_f32_16x16x32_bf16 v[16:19], v[158:161], v[196:199], 0
	v_mfma_f32_16x16x32_bf16 v[12:15], v[172:175], v[196:199], 0
	v_mfma_f32_16x16x32_bf16 v[4:7], v[158:161], v[204:207], 0
	v_mfma_f32_16x16x32_bf16 v[0:3], v[172:175], v[204:207], 0
	v_mfma_f32_16x16x32_bf16 v[44:47], v[168:171], v[184:187], v[44:47]
	v_mfma_f32_16x16x32_bf16 v[40:43], v[176:179], v[184:187], v[40:43]
	v_mfma_f32_16x16x32_bf16 v[36:39], v[168:171], v[192:195], v[36:39]
	v_mfma_f32_16x16x32_bf16 v[28:31], v[176:179], v[192:195], v[28:31]
	v_mfma_f32_16x16x32_bf16 v[16:19], v[168:171], v[200:203], v[16:19]
	v_mfma_f32_16x16x32_bf16 v[12:15], v[176:179], v[200:203], v[12:15]
	v_mfma_f32_16x16x32_bf16 v[4:7], v[168:171], v[208:211], v[4:7]
	v_mfma_f32_16x16x32_bf16 v[0:3], v[176:179], v[208:211], v[0:3]
	s_setprio 0
	s_barrier
	s_add_i32 s66, 0, 0x18000
	s_add_i32 s67, 0, 0x1c000
	v_add_u32_e32 v140, s66, v162
	v_add_u32_e32 v167, s67, v162
	ds_read_b128 v[128:131], v140
	ds_read_b128 v[132:135], v140 offset:1024
	ds_read_b128 v[136:139], v140 offset:2048
	ds_read_b128 v[140:143], v140 offset:3072
	ds_read_b128 v[158:161], v167
	ds_read_b128 v[168:171], v167 offset:1024
	ds_read_b128 v[172:175], v167 offset:2048
	ds_read_b128 v[176:179], v167 offset:3072
	s_add_u32 s38, s38, 0x40000
	s_addc_u32 s39, s39, 0
	s_mov_b32 m0, s47
	v_lshl_add_u64 v[220:221], s[38:39], 0, v[144:145]
	ds_read_b128 v[180:183], v166 offset:32768
	ds_read_b128 v[184:187], v166 offset:33792
	ds_read_b128 v[188:191], v166 offset:34816
	ds_read_b128 v[192:195], v166 offset:35840
	ds_read_b128 v[196:199], v166 offset:36864
	ds_read_b128 v[200:203], v166 offset:37888
	ds_read_b128 v[204:207], v166 offset:38912
	ds_read_b128 v[208:211], v166 offset:39936
	global_load_lds_dwordx4 v[220:221], off
	v_lshl_add_u64 v[220:221], s[38:39], 0, v[146:147]
	s_mov_b32 m0, s48
	s_nop 0
	global_load_lds_dwordx4 v[220:221], off
	s_waitcnt vmcnt(8)
	s_waitcnt lgkmcnt(0)
	s_barrier
	s_setprio 1
	s_waitcnt lgkmcnt(0)
	v_mfma_f32_16x16x32_bf16 v[124:127], v[128:131], v[180:183], v[124:127]
	v_mfma_f32_16x16x32_bf16 v[120:123], v[136:139], v[180:183], v[120:123]
	v_mfma_f32_16x16x32_bf16 v[116:119], v[128:131], v[188:191], v[116:119]
	v_mfma_f32_16x16x32_bf16 v[112:115], v[136:139], v[188:191], v[112:115]
	v_mfma_f32_16x16x32_bf16 v[108:111], v[128:131], v[196:199], v[108:111]
	v_mfma_f32_16x16x32_bf16 v[100:103], v[136:139], v[196:199], v[100:103]
	v_mfma_f32_16x16x32_bf16 v[92:95], v[128:131], v[204:207], v[92:95]
	v_mfma_f32_16x16x32_bf16 v[76:79], v[136:139], v[204:207], v[76:79]
	v_mfma_f32_16x16x32_bf16 v[124:127], v[132:135], v[184:187], v[124:127]
	v_mfma_f32_16x16x32_bf16 v[120:123], v[140:143], v[184:187], v[120:123]
	v_mfma_f32_16x16x32_bf16 v[116:119], v[132:135], v[192:195], v[116:119]
	v_mfma_f32_16x16x32_bf16 v[112:115], v[140:143], v[192:195], v[112:115]
	v_mfma_f32_16x16x32_bf16 v[108:111], v[132:135], v[200:203], v[108:111]
	v_mfma_f32_16x16x32_bf16 v[100:103], v[140:143], v[200:203], v[100:103]
	v_mfma_f32_16x16x32_bf16 v[92:95], v[132:135], v[208:211], v[92:95]
	v_mfma_f32_16x16x32_bf16 v[76:79], v[140:143], v[208:211], v[76:79]
	s_setprio 0
	s_setprio 1
	v_mfma_f32_16x16x32_bf16 v[104:107], v[158:161], v[180:183], v[104:107]
	v_mfma_f32_16x16x32_bf16 v[96:99], v[172:175], v[180:183], v[96:99]
	v_mfma_f32_16x16x32_bf16 v[88:91], v[158:161], v[188:191], v[88:91]
	v_mfma_f32_16x16x32_bf16 v[84:87], v[172:175], v[188:191], v[84:87]
	v_mfma_f32_16x16x32_bf16 v[80:83], v[158:161], v[196:199], v[80:83]
	v_mfma_f32_16x16x32_bf16 v[72:75], v[172:175], v[196:199], v[72:75]
	v_mfma_f32_16x16x32_bf16 v[68:71], v[158:161], v[204:207], v[68:71]
	v_mfma_f32_16x16x32_bf16 v[64:67], v[172:175], v[204:207], v[64:67]
	v_mfma_f32_16x16x32_bf16 v[104:107], v[168:171], v[184:187], v[104:107]
	v_mfma_f32_16x16x32_bf16 v[96:99], v[176:179], v[184:187], v[96:99]
	v_mfma_f32_16x16x32_bf16 v[88:91], v[168:171], v[192:195], v[88:91]
	v_mfma_f32_16x16x32_bf16 v[84:87], v[176:179], v[192:195], v[84:87]
	v_mfma_f32_16x16x32_bf16 v[80:83], v[168:171], v[200:203], v[80:83]
	v_mfma_f32_16x16x32_bf16 v[72:75], v[176:179], v[200:203], v[72:75]
	v_mfma_f32_16x16x32_bf16 v[68:71], v[168:171], v[208:211], v[68:71]
	v_mfma_f32_16x16x32_bf16 v[64:67], v[176:179], v[208:211], v[64:67]
	s_setprio 0
	s_barrier
; #define PG8_STAGE(bufoff, gbase, voff) do { _Pragma("unroll") for (int _i = 0; _i < 2; ++_i) \
;         __builtin_amdgcn_global_load_lds((const unsigned*)((const char*)(gbase) + (voff)[_i]), (PG8_LAS unsigned*)(lds + (bufoff) + ldsw + _i * 8192), 16, 0, 0); } while (0)
; #define PG8_LDA(dst, b, h) do { _Pragma("unroll") for (int m = 0; m < 4; ++m) _Pragma("unroll") for (int k = 0; k < 2; ++k) dst[m][k] = *(const PG8_LAS bf16x8*)(lds + PG8_SA(b, h) + aoff + m * 2048 + k * 1024); } while (0)
; #define PG8_MMA(ai, bj, At, Bt) do { __builtin_amdgcn_s_setprio(1); _Pragma("unroll") for (int m = 0; m < 4; ++m) _Pragma("unroll") for (int n = 0; n < 2; ++n) _Pragma("unroll") for (int k = 0; k < 2; ++k) \
;         acc[ai][bj][m][n] = __builtin_amdgcn_mfma_f32_16x16x32_bf16(Bt[n][k], At[m][k], acc[ai][bj][m][n], 0, 0, 0); __builtin_amdgcn_s_setprio(0); } while (0)
; #define PG8_WAIT_V(n) asm volatile("s_waitcnt vmcnt(" #n ")" ::: "memory")
; #define PG8_WAIT_L(n) asm volatile("s_waitcnt lgkmcnt(" #n ")" ::: "memory")
; #define PG8_BAR __builtin_amdgcn_s_barrier()
; #define PG8_SCHED __builtin_amdgcn_sched_barrier(0)
; template <class Epi, class Sched, bool ALIGN_EPI = false, bool SP2 = false>
; __device__ __forceinline__ void gemm_phase(PG8_LAS unsigned char* lds, const Gemm g, const Sched& S, const Epi& E) {
;     ...
;             PG8_LDA(At, 1, 1); PG8_STAGE(PG8_SB(1, 0), b3, voffB); PG8_STAGE(PG8_SB(1, 1), b3 + hstep, voffB); PG8_STAGE(PG8_SA(1, 0), a3, voffA);
;             PG8_WAIT_V(8); PG8_WAIT_L(0); PG8_BAR; PG8_MMA(1, 0, At, B0); PG8_MMA(1, 1, At, B1); PG8_BAR; PG8_SCHED;
	s_add_i32 s38, s66, s44
	v_lshl_add_u64 v[212:213], v[212:213], 0, s[10:11]
	s_mov_b32 m0, s38
	ds_read_b128 v[180:183], v166 offset:49152
	ds_read_b128 v[184:187], v166 offset:50176
	ds_read_b128 v[188:191], v166 offset:51200
	ds_read_b128 v[192:195], v166 offset:52224
	ds_read_b128 v[196:199], v166 offset:53248
	ds_read_b128 v[200:203], v166 offset:54272
	ds_read_b128 v[204:207], v166 offset:55296
	ds_read_b128 v[208:211], v166 offset:56320
	global_load_lds_dwordx4 v[212:213], off
	s_add_i32 m0, s38, 0x2000
	s_add_u32 s36, s36, 0x40080
	v_lshl_add_u64 v[212:213], v[214:215], 0, s[10:11]
	s_addc_u32 s37, s37, 0
	s_add_i32 s38, s67, s44
	global_load_lds_dwordx4 v[212:213], off
	v_lshl_add_u64 v[212:213], s[36:37], 0, v[144:145]
	s_mov_b32 m0, s38
	s_nop 0
	global_load_lds_dwordx4 v[212:213], off
	v_lshl_add_u64 v[212:213], s[36:37], 0, v[146:147]
	s_add_i32 m0, s38, 0x2000
	s_nop 0
	global_load_lds_dwordx4 v[212:213], off
	v_lshl_add_u64 v[212:213], v[216:217], 0, s[10:11]
	s_mov_b32 m0, s52
	s_nop 0
	global_load_lds_dwordx4 v[212:213], off
	v_lshl_add_u64 v[212:213], v[218:219], 0, s[10:11]
	s_mov_b32 m0, s53
	s_nop 0
	global_load_lds_dwordx4 v[212:213], off
	s_waitcnt vmcnt(8)
	s_waitcnt lgkmcnt(0)
	s_barrier
	s_setprio 1
	s_waitcnt lgkmcnt(0)
	v_mfma_f32_16x16x32_bf16 v[60:63], v[128:131], v[180:183], v[60:63]
	v_mfma_f32_16x16x32_bf16 v[56:59], v[136:139], v[180:183], v[56:59]
	v_mfma_f32_16x16x32_bf16 v[52:55], v[128:131], v[188:191], v[52:55]
	v_mfma_f32_16x16x32_bf16 v[48:51], v[136:139], v[188:191], v[48:51]
	v_mfma_f32_16x16x32_bf16 v[32:35], v[128:131], v[196:199], v[32:35]
	v_mfma_f32_16x16x32_bf16 v[24:27], v[136:139], v[196:199], v[24:27]
	v_mfma_f32_16x16x32_bf16 v[20:23], v[128:131], v[204:207], v[20:23]
	v_mfma_f32_16x16x32_bf16 v[8:11], v[136:139], v[204:207], v[8:11]
	v_mfma_f32_16x16x32_bf16 v[60:63], v[132:135], v[184:187], v[60:63]
	v_mfma_f32_16x16x32_bf16 v[56:59], v[140:143], v[184:187], v[56:59]
	v_mfma_f32_16x16x32_bf16 v[52:55], v[132:135], v[192:195], v[52:55]
	v_mfma_f32_16x16x32_bf16 v[48:51], v[140:143], v[192:195], v[48:51]
	v_mfma_f32_16x16x32_bf16 v[32:35], v[132:135], v[200:203], v[32:35]
	v_mfma_f32_16x16x32_bf16 v[24:27], v[140:143], v[200:203], v[24:27]
	v_mfma_f32_16x16x32_bf16 v[20:23], v[132:135], v[208:211], v[20:23]
	v_mfma_f32_16x16x32_bf16 v[8:11], v[140:143], v[208:211], v[8:11]
	s_setprio 0
	s_setprio 1
	v_mfma_f32_16x16x32_bf16 v[44:47], v[158:161], v[180:183], v[44:47]
	v_mfma_f32_16x16x32_bf16 v[40:43], v[172:175], v[180:183], v[40:43]
	v_mfma_f32_16x16x32_bf16 v[36:39], v[158:161], v[188:191], v[36:39]
	v_mfma_f32_16x16x32_bf16 v[28:31], v[172:175], v[188:191], v[28:31]
	v_mfma_f32_16x16x32_bf16 v[16:19], v[158:161], v[196:199], v[16:19]
	v_mfma_f32_16x16x32_bf16 v[12:15], v[172:175], v[196:199], v[12:15]
	v_mfma_f32_16x16x32_bf16 v[4:7], v[158:161], v[204:207], v[4:7]
	v_mfma_f32_16x16x32_bf16 v[0:3], v[172:175], v[204:207], v[0:3]
	v_mfma_f32_16x16x32_bf16 v[44:47], v[168:171], v[184:187], v[44:47]
	v_mfma_f32_16x16x32_bf16 v[40:43], v[176:179], v[184:187], v[40:43]
	v_mfma_f32_16x16x32_bf16 v[36:39], v[168:171], v[192:195], v[36:39]
	v_mfma_f32_16x16x32_bf16 v[28:31], v[176:179], v[192:195], v[28:31]
	v_mfma_f32_16x16x32_bf16 v[16:19], v[168:171], v[200:203], v[16:19]
	v_mfma_f32_16x16x32_bf16 v[12:15], v[176:179], v[200:203], v[12:15]
	v_mfma_f32_16x16x32_bf16 v[4:7], v[168:171], v[208:211], v[4:7]
	v_mfma_f32_16x16x32_bf16 v[0:3], v[176:179], v[208:211], v[0:3]
	s_setprio 0
	s_barrier
	s_add_i32 s65, s65, 2
	s_add_u32 s34, s34, 0x100
	s_addc_u32 s35, s35, 0
	s_add_u32 s63, s63, 0x100
	s_addc_u32 s64, s64, 0
	s_cmp_gt_u32 s65, 13

;     __device__ __forceinline__ void operator()(const f32x4 (&acc)[2][2][4][2], const Unit& u, int wr, int wc, int fr, int fq) const {
;         const size_t row0 = (size_t)u.pm * BM + wr * 64 + fr; const int col0 = u.pn * BM + wc * 32 + 4 * fq; const float* gp = gate + (size_t)(u.pm >> 4) * 3072 + col0;
;         f32x4 gv[2][2];
; #pragma unroll
;         for (int bj = 0; bj < 2; ++bj)
; #pragma unroll
;             for (int n = 0; n < 2; ++n) gv[bj][n] = *(const f32x4*)(gp + bj * HALF + n * 16);
; #pragma unroll
;         for (int ai = 0; ai < 2; ++ai) {
;             f32x4 xv[4][2][2];
; #pragma unroll
;             for (int m = 0; m < 4; ++m) { const size_t off = (row0 + ai * HALF + m * 16) * 1024 + col0;
; #pragma unroll
;                 for (int bj = 0; bj < 2; ++bj)
; #pragma unroll
;                     for (int n = 0; n < 2; ++n) xv[m][bj][n] = *(const f32x4*)(x + off + bj * HALF + n * 16); }
;             asm volatile("" ::: "memory");
; #pragma unroll
;             for (int m = 0; m < 4; ++m) { const size_t off = (row0 + ai * HALF + m * 16) * 1024 + col0;
; #pragma unroll
;                 for (int bj = 0; bj < 2; ++bj)
; #pragma unroll
;                     for (int n = 0; n < 2; ++n) *(f32x4*)(out + off + bj * HALF + n * 16) = xv[m][bj][n] + gv[bj][n] * acc[ai][bj][m][n]; }
.LBB0_588:
	s_mov_b32 s89, 1
	s_ashr_i32 s23, s30, 4
	s_ashr_i32 s31, s30, 31
	v_lshl_or_b32 v128, s61, 8, v163
	s_mul_hi_i32 s25, s23, 0x3000
	s_mulk_i32 s23, 0x3000
	s_add_u32 s34, s50, s23
	v_ashrrev_i32_e32 v129, 31, v128
	s_addc_u32 s35, s51, s25
	v_lshlrev_b64 v[232:233], 2, v[128:129]
	v_mbcnt_lo_u32_b32 v246, -1, 0
	v_mbcnt_hi_u32_b32 v246, -1, v246
	v_bfe_u32 v246, v246, 3, 1
	v_mul_i32_i24_e32 v246, 0xffff8040, v246
	v_ashrrev_i32_e32 v247, 31, v246
	v_lshl_add_u64 v[246:247], v[232:233], 0, v[246:247]
	v_mov_b32_e32 v248, 0x8000
	v_mov_b32_e32 v249, 0
	s_lshl_b64 s[30:31], s[30:31], 20
	v_lshl_add_u64 v[158:159], s[4:5], 0, v[232:233]
	v_lshl_add_u64 v[234:235], s[30:31], 0, v[148:149]
	v_lshl_add_u64 v[128:129], s[34:35], 0, v[232:233]
	v_lshl_add_u64 v[160:161], v[158:159], 0, v[234:235]
	global_load_dwordx4 v[168:171], v[160:161], off
	global_load_dwordx4 v[140:143], v[128:129], off
	global_load_dwordx4 v[136:139], v[128:129], off offset:64
	global_load_dwordx4 v[172:175], v[160:161], off offset:64
	global_load_dwordx4 v[176:179], v[160:161], off offset:512
	global_load_dwordx4 v[132:135], v[128:129], off offset:512
	s_nop 0
	global_load_dwordx4 v[128:131], v[128:129], off offset:576
	s_nop 0
	global_load_dwordx4 v[180:183], v[160:161], off offset:576
	v_or_b32_e32 v236, 0x10000, v234
	v_mov_b32_e32 v237, v235
	v_or_b32_e32 v238, 0x20000, v234
	v_mov_b32_e32 v239, v235
	v_or_b32_e32 v240, 0x30000, v234
	v_mov_b32_e32 v241, v235
	v_lshl_add_u64 v[196:197], v[158:159], 0, v[236:237]
	v_lshl_add_u64 v[212:213], v[158:159], 0, v[238:239]
	v_lshl_add_u64 v[158:159], v[158:159], 0, v[240:241]
	global_load_dwordx4 v[184:187], v[196:197], off
	global_load_dwordx4 v[188:191], v[196:197], off offset:64
	global_load_dwordx4 v[192:195], v[196:197], off offset:512
	s_nop 0
	global_load_dwordx4 v[196:199], v[196:197], off offset:576
	s_nop 0
	global_load_dwordx4 v[200:203], v[212:213], off
	global_load_dwordx4 v[204:207], v[212:213], off offset:64
	global_load_dwordx4 v[208:211], v[212:213], off offset:512
	s_nop 0
	global_load_dwordx4 v[212:215], v[212:213], off offset:576
	s_nop 0
	global_load_dwordx4 v[216:219], v[158:159], off
	global_load_dwordx4 v[220:223], v[158:159], off offset:64
	global_load_dwordx4 v[224:227], v[158:159], off offset:512
	global_load_dwordx4 v[228:231], v[158:159], off offset:576
	v_lshl_add_u64 v[158:159], s[6:7], 0, v[234:235]
	v_lshl_add_u64 v[158:159], v[158:159], 0, v[246:247]
	v_lshl_add_u64 v[234:235], s[6:7], 0, v[236:237]
	v_lshl_add_u64 v[236:237], s[6:7], 0, v[238:239]
	v_lshl_add_u64 v[238:239], s[6:7], 0, v[240:241]
	v_lshl_add_u64 v[234:235], v[234:235], 0, v[246:247]
	v_lshl_add_u64 v[236:237], v[236:237], 0, v[246:247]
	s_waitcnt vmcnt(0)
	v_pk_fma_f32 v[126:127], v[126:127], v[142:143], v[170:171]
	v_pk_fma_f32 v[124:125], v[124:125], v[140:141], v[168:169]
	v_pk_fma_f32 v[122:123], v[122:123], v[138:139], v[174:175]
	v_pk_fma_f32 v[120:121], v[120:121], v[136:137], v[172:173]
	v_pk_fma_f32 v[106:107], v[106:107], v[134:135], v[178:179]
	v_pk_fma_f32 v[104:105], v[104:105], v[132:133], v[176:177]
	v_pk_fma_f32 v[98:99], v[98:99], v[130:131], v[182:183]
	v_pk_fma_f32 v[96:97], v[96:97], v[128:129], v[180:181]
	s_nop 1
	v_mov_b32_e32 v252, v124
	v_mov_b32_e32 v253, v125
	v_mov_b32_e32 v254, v126
	v_mov_b32_e32 v255, v127
	v_mov_b32_dpp v124, v120 row_shr:8 row_mask:0xf bank_mask:0xc
	v_mov_b32_dpp v125, v121 row_shr:8 row_mask:0xf bank_mask:0xc
	v_mov_b32_dpp v126, v122 row_shr:8 row_mask:0xf bank_mask:0xc
	v_mov_b32_dpp v127, v123 row_shr:8 row_mask:0xf bank_mask:0xc
	v_mov_b32_dpp v120, v252 row_shl:8 row_mask:0xf bank_mask:0x3
	v_mov_b32_dpp v121, v253 row_shl:8 row_mask:0xf bank_mask:0x3
	v_mov_b32_dpp v122, v254 row_shl:8 row_mask:0xf bank_mask:0x3
	v_mov_b32_dpp v123, v255 row_shl:8 row_mask:0xf bank_mask:0x3
	v_lshl_add_u64 v[250:251], v[158:159], 0, v[248:249]
	global_store_dwordx4 v[158:159], v[124:127], off
	global_store_dwordx4 v[250:251], v[120:123], off
	s_nop 1
	v_mov_b32_e32 v252, v104
	v_mov_b32_e32 v253, v105
	v_mov_b32_e32 v254, v106
	v_mov_b32_e32 v255, v107
	v_mov_b32_dpp v104, v96 row_shr:8 row_mask:0xf bank_mask:0xc
	v_mov_b32_dpp v105, v97 row_shr:8 row_mask:0xf bank_mask:0xc
	v_mov_b32_dpp v106, v98 row_shr:8 row_mask:0xf bank_mask:0xc
	v_mov_b32_dpp v107, v99 row_shr:8 row_mask:0xf bank_mask:0xc
	v_mov_b32_dpp v96, v252 row_shl:8 row_mask:0xf bank_mask:0x3
	v_mov_b32_dpp v97, v253 row_shl:8 row_mask:0xf bank_mask:0x3
	v_mov_b32_dpp v98, v254 row_shl:8 row_mask:0xf bank_mask:0x3
	v_mov_b32_dpp v99, v255 row_shl:8 row_mask:0xf bank_mask:0x3
	v_lshl_add_u64 v[250:251], v[158:159], 0, v[248:249]
	global_store_dwordx4 v[158:159], v[104:107], off offset:512
	global_store_dwordx4 v[250:251], v[96:99], off offset:512
	v_lshl_add_u64 v[124:125], v[160:161], 0, s[20:21]
	v_lshl_add_u64 v[170:171], v[158:159], 0, s[16:17]
	v_pk_fma_f32 v[98:99], v[118:119], v[142:143], v[186:187]
	v_pk_fma_f32 v[96:97], v[116:117], v[140:141], v[184:185]
	v_pk_fma_f32 v[106:107], v[114:115], v[138:139], v[190:191]
	v_pk_fma_f32 v[80:81], v[80:81], v[132:133], v[208:209]
	v_pk_fma_f32 v[104:105], v[112:113], v[136:137], v[188:189]
	v_pk_fma_f32 v[90:91], v[90:91], v[134:135], v[194:195]
	v_pk_fma_f32 v[88:89], v[88:89], v[132:133], v[192:193]
	v_pk_fma_f32 v[86:87], v[86:87], v[130:131], v[198:199]
	v_pk_fma_f32 v[84:85], v[84:85], v[128:129], v[196:197]
	v_pk_fma_f32 v[110:111], v[110:111], v[142:143], v[202:203]
	v_pk_fma_f32 v[108:109], v[108:109], v[140:141], v[200:201]
	v_pk_fma_f32 v[102:103], v[102:103], v[138:139], v[206:207]
	v_pk_fma_f32 v[100:101], v[100:101], v[136:137], v[204:205]
;     __device__ __forceinline__ void operator()(const f32x4 (&acc)[2][2][4][2], const Unit& u, int wr, int wc, int fr, int fq) const {
;     ...
;         for (int ai = 0; ai < 2; ++ai) {
;             f32x4 xv[4][2][2];
; #pragma unroll
;             for (int m = 0; m < 4; ++m) { const size_t off = (row0 + ai * HALF + m * 16) * 1024 + col0;
; #pragma unroll
;                 for (int bj = 0; bj < 2; ++bj)
; #pragma unroll
;                     for (int n = 0; n < 2; ++n) xv[m][bj][n] = *(const f32x4*)(x + off + bj * HALF + n * 16); }
;             asm volatile("" ::: "memory");
; #pragma unroll
;             for (int m = 0; m < 4; ++m) { const size_t off = (row0 + ai * HALF + m * 16) * 1024 + col0;
; #pragma unroll
;                 for (int bj = 0; bj < 2; ++bj)
; #pragma unroll
;                     for (int n = 0; n < 2; ++n) *(f32x4*)(out + off + bj * HALF + n * 16) = xv[m][bj][n] + gv[bj][n] * acc[ai][bj][m][n]; }
	v_pk_fma_f32 v[82:83], v[82:83], v[134:135], v[210:211]
	v_pk_fma_f32 v[74:75], v[74:75], v[130:131], v[214:215]
	v_pk_fma_f32 v[72:73], v[72:73], v[128:129], v[212:213]
	s_nop 1
	v_mov_b32_e32 v252, v96
	v_mov_b32_e32 v253, v97
	v_mov_b32_e32 v254, v98
	v_mov_b32_e32 v255, v99
	v_mov_b32_dpp v96, v104 row_shr:8 row_mask:0xf bank_mask:0xc
	v_mov_b32_dpp v97, v105 row_shr:8 row_mask:0xf bank_mask:0xc
	v_mov_b32_dpp v98, v106 row_shr:8 row_mask:0xf bank_mask:0xc
	v_mov_b32_dpp v99, v107 row_shr:8 row_mask:0xf bank_mask:0xc
	v_mov_b32_dpp v104, v252 row_shl:8 row_mask:0xf bank_mask:0x3
	v_mov_b32_dpp v105, v253 row_shl:8 row_mask:0xf bank_mask:0x3
	v_mov_b32_dpp v106, v254 row_shl:8 row_mask:0xf bank_mask:0x3
	v_mov_b32_dpp v107, v255 row_shl:8 row_mask:0xf bank_mask:0x3
	v_lshl_add_u64 v[250:251], v[234:235], 0, v[248:249]
	global_store_dwordx4 v[234:235], v[96:99], off
	global_store_dwordx4 v[250:251], v[104:107], off
	s_nop 1
	v_mov_b32_e32 v252, v88
	v_mov_b32_e32 v253, v89
	v_mov_b32_e32 v254, v90
	v_mov_b32_e32 v255, v91
	v_mov_b32_dpp v88, v84 row_shr:8 row_mask:0xf bank_mask:0xc
	v_mov_b32_dpp v89, v85 row_shr:8 row_mask:0xf bank_mask:0xc
	v_mov_b32_dpp v90, v86 row_shr:8 row_mask:0xf bank_mask:0xc
	v_mov_b32_dpp v91, v87 row_shr:8 row_mask:0xf bank_mask:0xc
	v_mov_b32_dpp v84, v252 row_shl:8 row_mask:0xf bank_mask:0x3
	v_mov_b32_dpp v85, v253 row_shl:8 row_mask:0xf bank_mask:0x3
	v_mov_b32_dpp v86, v254 row_shl:8 row_mask:0xf bank_mask:0x3
	v_mov_b32_dpp v87, v255 row_shl:8 row_mask:0xf bank_mask:0x3
	v_lshl_add_u64 v[250:251], v[234:235], 0, v[248:249]
	global_store_dwordx4 v[234:235], v[88:91], off offset:512
	global_store_dwordx4 v[250:251], v[84:87], off offset:512
	s_nop 1
	v_mov_b32_e32 v252, v108
	v_mov_b32_e32 v253, v109
	v_mov_b32_e32 v254, v110
	v_mov_b32_e32 v255, v111
	v_mov_b32_dpp v108, v100 row_shr:8 row_mask:0xf bank_mask:0xc
	v_mov_b32_dpp v109, v101 row_shr:8 row_mask:0xf bank_mask:0xc
	v_mov_b32_dpp v110, v102 row_shr:8 row_mask:0xf bank_mask:0xc
	v_mov_b32_dpp v111, v103 row_shr:8 row_mask:0xf bank_mask:0xc
	v_mov_b32_dpp v100, v252 row_shl:8 row_mask:0xf bank_mask:0x3
	v_mov_b32_dpp v101, v253 row_shl:8 row_mask:0xf bank_mask:0x3
	v_mov_b32_dpp v102, v254 row_shl:8 row_mask:0xf bank_mask:0x3
	v_mov_b32_dpp v103, v255 row_shl:8 row_mask:0xf bank_mask:0x3
	v_lshl_add_u64 v[250:251], v[236:237], 0, v[248:249]
	global_store_dwordx4 v[236:237], v[108:111], off
	global_store_dwordx4 v[250:251], v[100:103], off
	s_nop 1
	v_mov_b32_e32 v252, v80
	v_mov_b32_e32 v253, v81
	v_mov_b32_e32 v254, v82
	v_mov_b32_e32 v255, v83
	v_mov_b32_dpp v80, v72 row_shr:8 row_mask:0xf bank_mask:0xc
	v_mov_b32_dpp v81, v73 row_shr:8 row_mask:0xf bank_mask:0xc
	v_mov_b32_dpp v82, v74 row_shr:8 row_mask:0xf bank_mask:0xc
	v_mov_b32_dpp v83, v75 row_shr:8 row_mask:0xf bank_mask:0xc
	v_mov_b32_dpp v72, v252 row_shl:8 row_mask:0xf bank_mask:0x3
	v_mov_b32_dpp v73, v253 row_shl:8 row_mask:0xf bank_mask:0x3
	v_mov_b32_dpp v74, v254 row_shl:8 row_mask:0xf bank_mask:0x3
	v_mov_b32_dpp v75, v255 row_shl:8 row_mask:0xf bank_mask:0x3
	v_lshl_add_u64 v[250:251], v[236:237], 0, v[248:249]
	global_store_dwordx4 v[236:237], v[80:83], off offset:512
	global_store_dwordx4 v[250:251], v[72:75], off offset:512
	v_pk_fma_f32 v[66:67], v[66:67], v[130:131], v[230:231]
	v_lshl_add_u64 v[80:81], v[238:239], 0, v[246:247]
	v_pk_fma_f32 v[64:65], v[64:65], v[128:129], v[228:229]
	v_pk_fma_f32 v[94:95], v[94:95], v[142:143], v[218:219]
	v_pk_fma_f32 v[92:93], v[92:93], v[140:141], v[216:217]
	v_add_co_u32_e32 v242, vcc, s57, v160
	v_pk_fma_f32 v[74:75], v[78:79], v[138:139], v[222:223]
	v_pk_fma_f32 v[72:73], v[76:77], v[136:137], v[220:221]
	v_pk_fma_f32 v[70:71], v[70:71], v[134:135], v[226:227]
	v_pk_fma_f32 v[68:69], v[68:69], v[132:133], v[224:225]
	v_addc_co_u32_e32 v243, vcc, 0, v161, vcc
	s_nop 1
	v_mov_b32_e32 v252, v92
	v_mov_b32_e32 v253, v93
	v_mov_b32_e32 v254, v94
	v_mov_b32_e32 v255, v95
	v_mov_b32_dpp v92, v72 row_shr:8 row_mask:0xf bank_mask:0xc
	v_mov_b32_dpp v93, v73 row_shr:8 row_mask:0xf bank_mask:0xc
	v_mov_b32_dpp v94, v74 row_shr:8 row_mask:0xf bank_mask:0xc
	v_mov_b32_dpp v95, v75 row_shr:8 row_mask:0xf bank_mask:0xc
	v_mov_b32_dpp v72, v252 row_shl:8 row_mask:0xf bank_mask:0x3
	v_mov_b32_dpp v73, v253 row_shl:8 row_mask:0xf bank_mask:0x3
	v_mov_b32_dpp v74, v254 row_shl:8 row_mask:0xf bank_mask:0x3
	v_mov_b32_dpp v75, v255 row_shl:8 row_mask:0xf bank_mask:0x3
	v_lshl_add_u64 v[250:251], v[80:81], 0, v[248:249]
	global_store_dwordx4 v[80:81], v[92:95], off
	global_store_dwordx4 v[250:251], v[72:75], off
	s_nop 1
	v_mov_b32_e32 v252, v68
	v_mov_b32_e32 v253, v69
	v_mov_b32_e32 v254, v70
	v_mov_b32_e32 v255, v71
	v_mov_b32_dpp v68, v64 row_shr:8 row_mask:0xf bank_mask:0xc
	v_mov_b32_dpp v69, v65 row_shr:8 row_mask:0xf bank_mask:0xc
	v_mov_b32_dpp v70, v66 row_shr:8 row_mask:0xf bank_mask:0xc
	v_mov_b32_dpp v71, v67 row_shr:8 row_mask:0xf bank_mask:0xc
	v_mov_b32_dpp v64, v252 row_shl:8 row_mask:0xf bank_mask:0x3
	v_mov_b32_dpp v65, v253 row_shl:8 row_mask:0xf bank_mask:0x3
	v_mov_b32_dpp v66, v254 row_shl:8 row_mask:0xf bank_mask:0x3
	v_mov_b32_dpp v67, v255 row_shl:8 row_mask:0xf bank_mask:0x3
	v_lshl_add_u64 v[250:251], v[80:81], 0, v[248:249]
	global_store_dwordx4 v[80:81], v[68:71], off offset:512
	global_store_dwordx4 v[250:251], v[64:67], off offset:512
	v_add_co_u32_e32 v80, vcc, s58, v160
	v_lshl_add_u64 v[76:77], v[160:161], 0, s[14:15]
	s_nop 0
	v_addc_co_u32_e32 v81, vcc, 0, v161, vcc
	v_lshl_add_u64 v[92:93], v[160:161], 0, s[16:17]
	v_add_co_u32_e32 v96, vcc, s59, v160
	global_load_dwordx4 v[64:67], v[242:243], off
	s_nop 0
	global_load_dwordx4 v[68:71], v[76:77], off offset:64
	global_load_dwordx4 v[72:75], v[76:77], off offset:512
	s_nop 0
	global_load_dwordx4 v[76:79], v[76:77], off offset:576
	v_addc_co_u32_e32 v97, vcc, 0, v161, vcc
	global_load_dwordx4 v[80:83], v[80:81], off
	s_nop 0
	global_load_dwordx4 v[84:87], v[92:93], off offset:64
	global_load_dwordx4 v[88:91], v[92:93], off offset:512
	s_nop 0
	global_load_dwordx4 v[92:95], v[92:93], off offset:576
	v_lshl_add_u64 v[108:109], v[160:161], 0, s[18:19]
	global_load_dwordx4 v[96:99], v[96:97], off
	v_add_co_u32_e32 v112, vcc, s60, v160
	global_load_dwordx4 v[100:103], v[108:109], off offset:64
	global_load_dwordx4 v[104:107], v[108:109], off offset:512
	s_nop 0
	global_load_dwordx4 v[108:111], v[108:109], off offset:576
	v_addc_co_u32_e32 v113, vcc, 0, v161, vcc
	global_load_dwordx4 v[112:115], v[112:113], off
	s_nop 0
	global_load_dwordx4 v[116:119], v[124:125], off offset:64
	global_load_dwordx4 v[120:123], v[124:125], off offset:512
	s_nop 0
	global_load_dwordx4 v[124:127], v[124:125], off offset:576
	v_lshl_add_u64 v[160:161], v[158:159], 0, s[14:15]
	s_nop 0
	s_waitcnt vmcnt(15)
;     __device__ __forceinline__ void operator()(const f32x4 (&acc)[2][2][4][2], const Unit& u, int wr, int wc, int fr, int fq) const {
;     ...
;             for (int m = 0; m < 4; ++m) { const size_t off = (row0 + ai * HALF + m * 16) * 1024 + col0;
; #pragma unroll
;                 for (int bj = 0; bj < 2; ++bj)
; #pragma unroll
;                     for (int n = 0; n < 2; ++n) *(f32x4*)(out + off + bj * HALF + n * 16) = xv[m][bj][n] + gv[bj][n] * acc[ai][bj][m][n]; }
	v_pk_fma_f32 v[62:63], v[62:63], v[142:143], v[66:67]
	v_pk_fma_f32 v[60:61], v[60:61], v[140:141], v[64:65]
	s_waitcnt vmcnt(14)
	v_pk_fma_f32 v[58:59], v[58:59], v[138:139], v[70:71]
	v_pk_fma_f32 v[56:57], v[56:57], v[136:137], v[68:69]
	s_waitcnt vmcnt(13)
	v_pk_fma_f32 v[46:47], v[46:47], v[134:135], v[74:75]
	s_waitcnt vmcnt(8)
	v_pk_fma_f32 v[30:31], v[30:31], v[130:131], v[94:95]
	v_pk_fma_f32 v[44:45], v[44:45], v[132:133], v[72:73]
	v_pk_fma_f32 v[42:43], v[42:43], v[130:131], v[78:79]
	v_pk_fma_f32 v[40:41], v[40:41], v[128:129], v[76:77]
	v_pk_fma_f32 v[54:55], v[54:55], v[142:143], v[82:83]
	v_pk_fma_f32 v[52:53], v[52:53], v[140:141], v[80:81]
	v_pk_fma_f32 v[50:51], v[50:51], v[138:139], v[86:87]
	v_pk_fma_f32 v[48:49], v[48:49], v[136:137], v[84:85]
	v_pk_fma_f32 v[38:39], v[38:39], v[134:135], v[90:91]
	v_pk_fma_f32 v[36:37], v[36:37], v[132:133], v[88:89]
	v_pk_fma_f32 v[28:29], v[28:29], v[128:129], v[92:93]
	s_nop 1
	v_mov_b32_e32 v252, v60
	v_mov_b32_e32 v253, v61
	v_mov_b32_e32 v254, v62
	v_mov_b32_e32 v255, v63
	v_mov_b32_dpp v60, v56 row_shr:8 row_mask:0xf bank_mask:0xc
	v_mov_b32_dpp v61, v57 row_shr:8 row_mask:0xf bank_mask:0xc
	v_mov_b32_dpp v62, v58 row_shr:8 row_mask:0xf bank_mask:0xc
	v_mov_b32_dpp v63, v59 row_shr:8 row_mask:0xf bank_mask:0xc
	v_mov_b32_dpp v56, v252 row_shl:8 row_mask:0xf bank_mask:0x3
	v_mov_b32_dpp v57, v253 row_shl:8 row_mask:0xf bank_mask:0x3
	v_mov_b32_dpp v58, v254 row_shl:8 row_mask:0xf bank_mask:0x3
	v_mov_b32_dpp v59, v255 row_shl:8 row_mask:0xf bank_mask:0x3
	v_lshl_add_u64 v[250:251], v[160:161], 0, v[248:249]
	global_store_dwordx4 v[160:161], v[60:63], off
	global_store_dwordx4 v[250:251], v[56:59], off
	s_nop 1
	v_mov_b32_e32 v252, v44
	v_mov_b32_e32 v253, v45
	v_mov_b32_e32 v254, v46
	v_mov_b32_e32 v255, v47
	v_mov_b32_dpp v44, v40 row_shr:8 row_mask:0xf bank_mask:0xc
	v_mov_b32_dpp v45, v41 row_shr:8 row_mask:0xf bank_mask:0xc
	v_mov_b32_dpp v46, v42 row_shr:8 row_mask:0xf bank_mask:0xc
	v_mov_b32_dpp v47, v43 row_shr:8 row_mask:0xf bank_mask:0xc
	v_mov_b32_dpp v40, v252 row_shl:8 row_mask:0xf bank_mask:0x3
	v_mov_b32_dpp v41, v253 row_shl:8 row_mask:0xf bank_mask:0x3
	v_mov_b32_dpp v42, v254 row_shl:8 row_mask:0xf bank_mask:0x3
	v_mov_b32_dpp v43, v255 row_shl:8 row_mask:0xf bank_mask:0x3
	v_lshl_add_u64 v[250:251], v[160:161], 0, v[248:249]
	global_store_dwordx4 v[160:161], v[44:47], off offset:512
	global_store_dwordx4 v[250:251], v[40:43], off offset:512
	s_nop 1
	v_mov_b32_e32 v252, v52
	v_mov_b32_e32 v253, v53
	v_mov_b32_e32 v254, v54
	v_mov_b32_e32 v255, v55
	v_mov_b32_dpp v52, v48 row_shr:8 row_mask:0xf bank_mask:0xc
	v_mov_b32_dpp v53, v49 row_shr:8 row_mask:0xf bank_mask:0xc
	v_mov_b32_dpp v54, v50 row_shr:8 row_mask:0xf bank_mask:0xc
	v_mov_b32_dpp v55, v51 row_shr:8 row_mask:0xf bank_mask:0xc
	v_mov_b32_dpp v48, v252 row_shl:8 row_mask:0xf bank_mask:0x3
	v_mov_b32_dpp v49, v253 row_shl:8 row_mask:0xf bank_mask:0x3
	v_mov_b32_dpp v50, v254 row_shl:8 row_mask:0xf bank_mask:0x3
	v_mov_b32_dpp v51, v255 row_shl:8 row_mask:0xf bank_mask:0x3
	v_lshl_add_u64 v[250:251], v[170:171], 0, v[248:249]
	global_store_dwordx4 v[170:171], v[52:55], off
	global_store_dwordx4 v[250:251], v[48:51], off
	s_nop 1
	v_mov_b32_e32 v252, v36
	v_mov_b32_e32 v253, v37
	v_mov_b32_e32 v254, v38
	v_mov_b32_e32 v255, v39
	v_mov_b32_dpp v36, v28 row_shr:8 row_mask:0xf bank_mask:0xc
	v_mov_b32_dpp v37, v29 row_shr:8 row_mask:0xf bank_mask:0xc
	v_mov_b32_dpp v38, v30 row_shr:8 row_mask:0xf bank_mask:0xc
	v_mov_b32_dpp v39, v31 row_shr:8 row_mask:0xf bank_mask:0xc
	v_mov_b32_dpp v28, v252 row_shl:8 row_mask:0xf bank_mask:0x3
	v_mov_b32_dpp v29, v253 row_shl:8 row_mask:0xf bank_mask:0x3
	v_mov_b32_dpp v30, v254 row_shl:8 row_mask:0xf bank_mask:0x3
	v_mov_b32_dpp v31, v255 row_shl:8 row_mask:0xf bank_mask:0x3
	v_lshl_add_u64 v[250:251], v[170:171], 0, v[248:249]
	global_store_dwordx4 v[170:171], v[36:39], off offset:512
	global_store_dwordx4 v[250:251], v[28:31], off offset:512
	s_waitcnt vmcnt(13)
; #define PG8_BAR __builtin_amdgcn_s_barrier()
;     __device__ __forceinline__ void operator()(const f32x4 (&acc)[2][2][4][2], const Unit& u, int wr, int wc, int fr, int fq) const {
;     ...
;             for (int m = 0; m < 4; ++m) { const size_t off = (row0 + ai * HALF + m * 16) * 1024 + col0;
; #pragma unroll
;                 for (int bj = 0; bj < 2; ++bj)
; #pragma unroll
;                     for (int n = 0; n < 2; ++n) *(f32x4*)(out + off + bj * HALF + n * 16) = xv[m][bj][n] + gv[bj][n] * acc[ai][bj][m][n]; }
; template <class Epi, class Sched, bool ALIGN_EPI = false, bool SP2 = false>
; __device__ __forceinline__ void gemm_phase(PG8_LAS unsigned char* lds, const Gemm g, const Sched& S, const Epi& E) {
;     ...
;         if (!has_next) break;
; #pragma unroll
;         for (int a = 0; a < 2; ++a)
; #pragma unroll
;             for (int b = 0; b < 2; ++b)
; #pragma unroll
;                 for (int m = 0; m < 4; ++m)
; #pragma unroll
;                     for (int n = 0; n < 2; ++n) acc[a][b][m][n] = (f32x4){0.f, 0.f, 0.f, 0.f};
;         cur = nxt; cA = nA; cB = nB; ++ui;
;         if constexpr (ALIGN_EPI) { if (wr == 1) PG8_BAR; }
	v_pk_fma_f32 v[18:19], v[18:19], v[134:135], v[106:107]
	v_pk_fma_f32 v[16:17], v[16:17], v[132:133], v[104:105]
	v_pk_fma_f32 v[30:31], v[34:35], v[142:143], v[98:99]
	v_pk_fma_f32 v[28:29], v[32:33], v[140:141], v[96:97]
	v_lshl_add_u64 v[32:33], v[158:159], 0, s[18:19]
	s_waitcnt vmcnt(12)
	v_pk_fma_f32 v[14:15], v[14:15], v[130:131], v[110:111]
	v_pk_fma_f32 v[12:13], v[12:13], v[128:129], v[108:109]
	v_pk_fma_f32 v[26:27], v[26:27], v[138:139], v[102:103]
	v_pk_fma_f32 v[24:25], v[24:25], v[136:137], v[100:101]
	s_nop 1
	v_mov_b32_e32 v252, v16
	v_mov_b32_e32 v253, v17
	v_mov_b32_e32 v254, v18
	v_mov_b32_e32 v255, v19
	v_mov_b32_dpp v16, v12 row_shr:8 row_mask:0xf bank_mask:0xc
	v_mov_b32_dpp v17, v13 row_shr:8 row_mask:0xf bank_mask:0xc
	v_mov_b32_dpp v18, v14 row_shr:8 row_mask:0xf bank_mask:0xc
	v_mov_b32_dpp v19, v15 row_shr:8 row_mask:0xf bank_mask:0xc
	v_mov_b32_dpp v12, v252 row_shl:8 row_mask:0xf bank_mask:0x3
	v_mov_b32_dpp v13, v253 row_shl:8 row_mask:0xf bank_mask:0x3
	v_mov_b32_dpp v14, v254 row_shl:8 row_mask:0xf bank_mask:0x3
	v_mov_b32_dpp v15, v255 row_shl:8 row_mask:0xf bank_mask:0x3
	v_lshl_add_u64 v[250:251], v[32:33], 0, v[248:249]
	global_store_dwordx4 v[32:33], v[16:19], off offset:512
	global_store_dwordx4 v[250:251], v[12:15], off offset:512
	v_lshl_add_u64 v[244:245], v[158:159], 0, s[20:21]
	s_waitcnt vmcnt(13)
	v_pk_fma_f32 v[14:15], v[22:23], v[142:143], v[114:115]
	v_pk_fma_f32 v[12:13], v[20:21], v[140:141], v[112:113]
	s_waitcnt vmcnt(12)
	v_pk_fma_f32 v[10:11], v[10:11], v[138:139], v[118:119]
	v_pk_fma_f32 v[8:9], v[8:9], v[136:137], v[116:117]
	s_waitcnt vmcnt(11)
	v_pk_fma_f32 v[6:7], v[6:7], v[134:135], v[122:123]
	v_pk_fma_f32 v[4:5], v[4:5], v[132:133], v[120:121]
	s_waitcnt vmcnt(10)
	v_pk_fma_f32 v[2:3], v[2:3], v[130:131], v[126:127]
	v_pk_fma_f32 v[0:1], v[0:1], v[128:129], v[124:125]
	s_nop 1
	v_mov_b32_e32 v252, v28
	v_mov_b32_e32 v253, v29
	v_mov_b32_e32 v254, v30
	v_mov_b32_e32 v255, v31
	v_mov_b32_dpp v28, v24 row_shr:8 row_mask:0xf bank_mask:0xc
	v_mov_b32_dpp v29, v25 row_shr:8 row_mask:0xf bank_mask:0xc
	v_mov_b32_dpp v30, v26 row_shr:8 row_mask:0xf bank_mask:0xc
	v_mov_b32_dpp v31, v27 row_shr:8 row_mask:0xf bank_mask:0xc
	v_mov_b32_dpp v24, v252 row_shl:8 row_mask:0xf bank_mask:0x3
	v_mov_b32_dpp v25, v253 row_shl:8 row_mask:0xf bank_mask:0x3
	v_mov_b32_dpp v26, v254 row_shl:8 row_mask:0xf bank_mask:0x3
	v_mov_b32_dpp v27, v255 row_shl:8 row_mask:0xf bank_mask:0x3
	v_lshl_add_u64 v[250:251], v[32:33], 0, v[248:249]
	global_store_dwordx4 v[32:33], v[28:31], off
	global_store_dwordx4 v[250:251], v[24:27], off
	s_nop 1
	v_mov_b32_e32 v252, v12
	v_mov_b32_e32 v253, v13
	v_mov_b32_e32 v254, v14
	v_mov_b32_e32 v255, v15
	v_mov_b32_dpp v12, v8 row_shr:8 row_mask:0xf bank_mask:0xc
	v_mov_b32_dpp v13, v9 row_shr:8 row_mask:0xf bank_mask:0xc
	v_mov_b32_dpp v14, v10 row_shr:8 row_mask:0xf bank_mask:0xc
	v_mov_b32_dpp v15, v11 row_shr:8 row_mask:0xf bank_mask:0xc
	v_mov_b32_dpp v8, v252 row_shl:8 row_mask:0xf bank_mask:0x3
	v_mov_b32_dpp v9, v253 row_shl:8 row_mask:0xf bank_mask:0x3
	v_mov_b32_dpp v10, v254 row_shl:8 row_mask:0xf bank_mask:0x3
	v_mov_b32_dpp v11, v255 row_shl:8 row_mask:0xf bank_mask:0x3
	v_lshl_add_u64 v[250:251], v[244:245], 0, v[248:249]
	global_store_dwordx4 v[244:245], v[12:15], off
	global_store_dwordx4 v[250:251], v[8:11], off
	s_nop 1
	v_mov_b32_e32 v252, v4
	v_mov_b32_e32 v253, v5
	v_mov_b32_e32 v254, v6
	v_mov_b32_e32 v255, v7
	v_mov_b32_dpp v4, v0 row_shr:8 row_mask:0xf bank_mask:0xc
	v_mov_b32_dpp v5, v1 row_shr:8 row_mask:0xf bank_mask:0xc
	v_mov_b32_dpp v6, v2 row_shr:8 row_mask:0xf bank_mask:0xc
	v_mov_b32_dpp v7, v3 row_shr:8 row_mask:0xf bank_mask:0xc
	v_mov_b32_dpp v0, v252 row_shl:8 row_mask:0xf bank_mask:0x3
	v_mov_b32_dpp v1, v253 row_shl:8 row_mask:0xf bank_mask:0x3
	v_mov_b32_dpp v2, v254 row_shl:8 row_mask:0xf bank_mask:0x3
	v_mov_b32_dpp v3, v255 row_shl:8 row_mask:0xf bank_mask:0x3
	v_lshl_add_u64 v[250:251], v[244:245], 0, v[248:249]
	global_store_dwordx4 v[244:245], v[4:7], off offset:512
	global_store_dwordx4 v[250:251], v[0:3], off offset:512
	s_andn2_b64 vcc, exec, s[0:1]
	s_mov_b64 s[0:1], -1
	s_cbranch_vccnz .LBB0_577
	s_andn2_b64 vcc, exec, s[8:9]
	s_cbranch_vccnz .LBB0_576
	s_barrier
	s_branch .LBB0_576
